# all eight GEMM K loops: hipcc's per-phase s_setprio flips removed; one static s_setprio 1 for waves 4-7 at kernel entry (kept for the whole kernel); on v079
# speedup vs baseline: 1.0107x; 1.0012x over previous
_Z4mega6Paramsii:
	s_mov_b32 s16, s2
	s_load_dwordx16 s[36:51], s[0:1], 0x0
	s_load_dwordx8 s[20:27], s[0:1], 0x80
	s_load_dword s2, s[0:1], 0xb0
	s_load_dwordx2 s[90:91], s[0:1], 0xa8
	s_add_u32 s4, s0, 0xa8
	v_and_b32_e32 v194, 0x3ff, v0
	s_addc_u32 s5, s1, 0
	v_cmp_eq_u32_e64 s[14:15], 0, v194
	v_readfirstlane_b32 s99, v194
	s_nop 3
	s_cmp_lt_u32 s99, 0x100
	s_cbranch_scc1 .Lprio_done
	s_setprio 1
.Lprio_done:
	s_waitcnt lgkmcnt(0)
	v_writelane_b32 v242, s2, 0
	s_cmp_lt_u32 s16, 0x80
	s_cbranch_scc0 .Lf11_zskip
	s_lshl_b32 s2, s16, 7
	s_add_u32 s6, s26, 0x3c08000
	s_addc_u32 s7, s27, 0
	s_add_u32 s6, s6, s2
	s_addc_u32 s7, s7, 0
	v_mov_b32_e32 v1, 0
	s_and_saveexec_b64 s[2:3], s[14:15]
	global_store_dword v1, v1, s[6:7]
	s_or_b64 exec, exec, s[2:3]

.LBB0_342:
	ds_read_b128 v[146:149], v143
	ds_read_b128 v[150:153], v143 offset:1024
	ds_read_b128 v[154:157], v143 offset:2048
	ds_read_b128 v[158:161], v143 offset:3072
	s_add_u32 s46, s44, 0xfffc0080
	s_addc_u32 s47, s45, -1
	s_cmp_eq_u32 s67, 12
	s_cselect_b32 s49, s9, s47
	s_cselect_b32 s48, s63, s46
	s_cselect_b32 s47, s7, s66
	s_cselect_b32 s46, s64, s65
	v_lshl_add_u64 v[190:191], s[44:45], 0, v[136:137]
	s_add_i32 m0, s43, 0xc000
	ds_read_b128 v[162:165], v144
	ds_read_b128 v[166:169], v144 offset:1024
	ds_read_b128 v[170:173], v144 offset:2048
	ds_read_b128 v[174:177], v144 offset:3072
	ds_read_b128 v[178:181], v144 offset:4096
	ds_read_b128 v[182:185], v144 offset:5120
	ds_read_b128 v[186:189], v144 offset:6144
	ds_read_b128 v[196:199], v144 offset:7168
	global_load_lds_dwordx4 v[190:191], off
	v_lshl_add_u64 v[190:191], s[44:45], 0, v[138:139]
	s_add_i32 m0, s43, 0xe000
	s_nop 0
	global_load_lds_dwordx4 v[190:191], off
	s_waitcnt lgkmcnt(8)
	s_barrier
	s_waitcnt lgkmcnt(0)
	s_waitcnt lgkmcnt(0)
	v_mfma_f32_16x16x32_bf16 v[124:127], v[146:149], v[162:165], v[124:127]
	v_mfma_f32_16x16x32_bf16 v[120:123], v[154:157], v[162:165], v[120:123]
	v_mfma_f32_16x16x32_bf16 v[108:111], v[146:149], v[170:173], v[108:111]
	v_mfma_f32_16x16x32_bf16 v[104:107], v[154:157], v[170:173], v[104:107]
	v_mfma_f32_16x16x32_bf16 v[92:95], v[146:149], v[178:181], v[92:95]
	v_mfma_f32_16x16x32_bf16 v[88:91], v[154:157], v[178:181], v[88:91]
	v_mfma_f32_16x16x32_bf16 v[76:79], v[146:149], v[186:189], v[76:79]
	v_mfma_f32_16x16x32_bf16 v[72:75], v[154:157], v[186:189], v[72:75]
	v_mfma_f32_16x16x32_bf16 v[124:127], v[150:153], v[166:169], v[124:127]
	v_mfma_f32_16x16x32_bf16 v[120:123], v[158:161], v[166:169], v[120:123]
	v_mfma_f32_16x16x32_bf16 v[108:111], v[150:153], v[174:177], v[108:111]
	v_mfma_f32_16x16x32_bf16 v[104:107], v[158:161], v[174:177], v[104:107]
	v_mfma_f32_16x16x32_bf16 v[92:95], v[150:153], v[182:185], v[92:95]
	v_mfma_f32_16x16x32_bf16 v[88:91], v[158:161], v[182:185], v[88:91]
	v_mfma_f32_16x16x32_bf16 v[76:79], v[150:153], v[196:199], v[76:79]
	v_mfma_f32_16x16x32_bf16 v[72:75], v[158:161], v[196:199], v[72:75]
	s_barrier
	s_add_i32 s84, s60, s50
	v_lshl_add_u64 v[190:191], s[46:47], 0, v[132:133]
	s_mov_b32 m0, s84
	ds_read_b128 v[200:203], v145
	ds_read_b128 v[204:207], v145 offset:1024
	ds_read_b128 v[208:211], v145 offset:2048
	ds_read_b128 v[212:215], v145 offset:3072
	global_load_lds_dwordx4 v[190:191], off
	v_lshl_add_u64 v[216:217], s[46:47], 0, v[128:129]
	s_add_i32 m0, s84, 0x2000
	s_nop 0
	global_load_lds_dwordx4 v[216:217], off
	s_barrier
	s_waitcnt lgkmcnt(0)
	s_waitcnt lgkmcnt(0)
	v_mfma_f32_16x16x32_bf16 v[116:119], v[200:203], v[162:165], v[116:119]
	v_mfma_f32_16x16x32_bf16 v[112:115], v[208:211], v[162:165], v[112:115]
	v_mfma_f32_16x16x32_bf16 v[100:103], v[200:203], v[170:173], v[100:103]
	v_mfma_f32_16x16x32_bf16 v[96:99], v[208:211], v[170:173], v[96:99]
	v_mfma_f32_16x16x32_bf16 v[84:87], v[200:203], v[178:181], v[84:87]
	v_mfma_f32_16x16x32_bf16 v[80:83], v[208:211], v[178:181], v[80:83]
	v_mfma_f32_16x16x32_bf16 v[68:71], v[200:203], v[186:189], v[68:71]
	v_mfma_f32_16x16x32_bf16 v[64:67], v[208:211], v[186:189], v[64:67]
	v_mfma_f32_16x16x32_bf16 v[116:119], v[204:207], v[166:169], v[116:119]
	v_mfma_f32_16x16x32_bf16 v[112:115], v[212:215], v[166:169], v[112:115]
	v_mfma_f32_16x16x32_bf16 v[100:103], v[204:207], v[174:177], v[100:103]
	v_mfma_f32_16x16x32_bf16 v[96:99], v[212:215], v[174:177], v[96:99]
	v_mfma_f32_16x16x32_bf16 v[84:87], v[204:207], v[182:185], v[84:87]
	v_mfma_f32_16x16x32_bf16 v[80:83], v[212:215], v[182:185], v[80:83]
	v_mfma_f32_16x16x32_bf16 v[68:71], v[204:207], v[196:199], v[68:71]
	v_mfma_f32_16x16x32_bf16 v[64:67], v[212:215], v[196:199], v[64:67]
	s_mov_b32 m0, s43
	v_lshl_add_u64 v[218:219], s[48:49], 0, v[134:135]
	s_barrier
	ds_read_b128 v[162:165], v144 offset:16384
	ds_read_b128 v[166:169], v144 offset:17408
	ds_read_b128 v[170:173], v144 offset:18432
	ds_read_b128 v[174:177], v144 offset:19456
	ds_read_b128 v[178:181], v144 offset:20480
	ds_read_b128 v[182:185], v144 offset:21504
	ds_read_b128 v[186:189], v144 offset:22528
	ds_read_b128 v[196:199], v144 offset:23552
	global_load_lds_dwordx4 v[218:219], off
	v_lshl_add_u64 v[220:221], s[48:49], 0, v[130:131]
	s_mov_b32 m0, s52
	s_nop 0
	global_load_lds_dwordx4 v[220:221], off
	s_barrier
	s_waitcnt lgkmcnt(0)
	s_waitcnt lgkmcnt(0)
	v_mfma_f32_16x16x32_bf16 v[60:63], v[146:149], v[162:165], v[60:63]
	v_mfma_f32_16x16x32_bf16 v[56:59], v[154:157], v[162:165], v[56:59]
	v_mfma_f32_16x16x32_bf16 v[44:47], v[146:149], v[170:173], v[44:47]
	v_mfma_f32_16x16x32_bf16 v[40:43], v[154:157], v[170:173], v[40:43]
	v_mfma_f32_16x16x32_bf16 v[28:31], v[146:149], v[178:181], v[28:31]
	v_mfma_f32_16x16x32_bf16 v[24:27], v[154:157], v[178:181], v[24:27]
	v_mfma_f32_16x16x32_bf16 v[12:15], v[146:149], v[186:189], v[12:15]
	v_mfma_f32_16x16x32_bf16 v[8:11], v[154:157], v[186:189], v[8:11]
	v_mfma_f32_16x16x32_bf16 v[60:63], v[150:153], v[166:169], v[60:63]
	v_mfma_f32_16x16x32_bf16 v[56:59], v[158:161], v[166:169], v[56:59]
	v_mfma_f32_16x16x32_bf16 v[44:47], v[150:153], v[174:177], v[44:47]
	v_mfma_f32_16x16x32_bf16 v[40:43], v[158:161], v[174:177], v[40:43]
	v_mfma_f32_16x16x32_bf16 v[28:31], v[150:153], v[182:185], v[28:31]
	v_mfma_f32_16x16x32_bf16 v[24:27], v[158:161], v[182:185], v[24:27]
	v_mfma_f32_16x16x32_bf16 v[12:15], v[150:153], v[196:199], v[12:15]
	v_mfma_f32_16x16x32_bf16 v[8:11], v[158:161], v[196:199], v[8:11]
	s_barrier
	s_add_u32 s84, s46, 0x10000
	s_addc_u32 s85, s47, 0
	s_add_i32 s89, s61, s50
	v_lshl_add_u64 v[146:147], s[84:85], 0, v[132:133]
	s_mov_b32 m0, s89
	s_nop 0
	global_load_lds_dwordx4 v[146:147], off
	v_lshl_add_u64 v[146:147], s[84:85], 0, v[128:129]
	s_add_i32 m0, s89, 0x2000
	s_nop 0
	global_load_lds_dwordx4 v[146:147], off
	s_waitcnt vmcnt(6)
	s_barrier
	v_mfma_f32_16x16x32_bf16 v[52:55], v[200:203], v[162:165], v[52:55]
	v_mfma_f32_16x16x32_bf16 v[48:51], v[208:211], v[162:165], v[48:51]
	v_mfma_f32_16x16x32_bf16 v[36:39], v[200:203], v[170:173], v[36:39]
	v_mfma_f32_16x16x32_bf16 v[32:35], v[208:211], v[170:173], v[32:35]
	v_mfma_f32_16x16x32_bf16 v[20:23], v[200:203], v[178:181], v[20:23]
	v_mfma_f32_16x16x32_bf16 v[16:19], v[208:211], v[178:181], v[16:19]
	v_mfma_f32_16x16x32_bf16 v[4:7], v[200:203], v[186:189], v[4:7]
	v_mfma_f32_16x16x32_bf16 v[0:3], v[208:211], v[186:189], v[0:3]
	v_mfma_f32_16x16x32_bf16 v[52:55], v[204:207], v[166:169], v[52:55]
	v_mfma_f32_16x16x32_bf16 v[48:51], v[212:215], v[166:169], v[48:51]
	v_mfma_f32_16x16x32_bf16 v[36:39], v[204:207], v[174:177], v[36:39]
	v_mfma_f32_16x16x32_bf16 v[32:35], v[212:215], v[174:177], v[32:35]
	v_mfma_f32_16x16x32_bf16 v[20:23], v[204:207], v[182:185], v[20:23]
	v_mfma_f32_16x16x32_bf16 v[16:19], v[212:215], v[182:185], v[16:19]
	v_mfma_f32_16x16x32_bf16 v[4:7], v[204:207], v[196:199], v[4:7]
	v_mfma_f32_16x16x32_bf16 v[0:3], v[212:215], v[196:199], v[0:3]
	s_add_i32 s84, 0, 0x18000
	v_add_u32_e32 v158, s84, v141
	s_barrier
	ds_read_b128 v[146:149], v158
	ds_read_b128 v[150:153], v158 offset:1024
	ds_read_b128 v[154:157], v158 offset:2048
	ds_read_b128 v[158:161], v158 offset:3072
	s_add_u32 s48, s48, 0x40000
	s_addc_u32 s49, s49, 0
	s_mov_b32 m0, s53
	v_lshl_add_u64 v[200:201], s[48:49], 0, v[134:135]
	ds_read_b128 v[162:165], v144 offset:32768
	ds_read_b128 v[166:169], v144 offset:33792
	ds_read_b128 v[170:173], v144 offset:34816
	ds_read_b128 v[174:177], v144 offset:35840
	ds_read_b128 v[178:181], v144 offset:36864
	ds_read_b128 v[182:185], v144 offset:37888
	ds_read_b128 v[186:189], v144 offset:38912
	ds_read_b128 v[196:199], v144 offset:39936
	global_load_lds_dwordx4 v[200:201], off
	v_lshl_add_u64 v[200:201], s[48:49], 0, v[130:131]
	s_mov_b32 m0, s54
	s_nop 0
	global_load_lds_dwordx4 v[200:201], off
	s_waitcnt lgkmcnt(8)
	s_barrier
	s_waitcnt lgkmcnt(0)
	s_waitcnt lgkmcnt(0)
	v_mfma_f32_16x16x32_bf16 v[124:127], v[146:149], v[162:165], v[124:127]
	v_mfma_f32_16x16x32_bf16 v[120:123], v[154:157], v[162:165], v[120:123]
	v_mfma_f32_16x16x32_bf16 v[108:111], v[146:149], v[170:173], v[108:111]
	v_mfma_f32_16x16x32_bf16 v[104:107], v[154:157], v[170:173], v[104:107]
	v_mfma_f32_16x16x32_bf16 v[92:95], v[146:149], v[178:181], v[92:95]
	v_mfma_f32_16x16x32_bf16 v[88:91], v[154:157], v[178:181], v[88:91]
	v_mfma_f32_16x16x32_bf16 v[76:79], v[146:149], v[186:189], v[76:79]
	v_mfma_f32_16x16x32_bf16 v[72:75], v[154:157], v[186:189], v[72:75]
	v_mfma_f32_16x16x32_bf16 v[124:127], v[150:153], v[166:169], v[124:127]
	v_mfma_f32_16x16x32_bf16 v[120:123], v[158:161], v[166:169], v[120:123]
	v_mfma_f32_16x16x32_bf16 v[108:111], v[150:153], v[174:177], v[108:111]
	v_mfma_f32_16x16x32_bf16 v[104:107], v[158:161], v[174:177], v[104:107]
	v_mfma_f32_16x16x32_bf16 v[92:95], v[150:153], v[182:185], v[92:95]
	v_mfma_f32_16x16x32_bf16 v[88:91], v[158:161], v[182:185], v[88:91]
	v_mfma_f32_16x16x32_bf16 v[76:79], v[150:153], v[196:199], v[76:79]
	v_mfma_f32_16x16x32_bf16 v[72:75], v[158:161], v[196:199], v[72:75]
	s_barrier
	s_add_i32 s48, 0, 0x1c000
	s_add_i32 s49, s84, s50
	v_add_u32_e32 v195, s48, v141
	v_lshl_add_u64 v[190:191], v[190:191], 0, s[0:1]
	s_mov_b32 m0, s49
	ds_read_b128 v[200:203], v195
	ds_read_b128 v[204:207], v195 offset:1024
	ds_read_b128 v[208:211], v195 offset:2048
	ds_read_b128 v[212:215], v195 offset:3072
	global_load_lds_dwordx4 v[190:191], off
	v_lshl_add_u64 v[190:191], v[216:217], 0, s[0:1]
	s_add_i32 m0, s49, 0x2000
	s_nop 0
	global_load_lds_dwordx4 v[190:191], off
	s_barrier
	s_waitcnt lgkmcnt(0)
	s_waitcnt lgkmcnt(0)
	v_mfma_f32_16x16x32_bf16 v[116:119], v[200:203], v[162:165], v[116:119]
	v_mfma_f32_16x16x32_bf16 v[112:115], v[208:211], v[162:165], v[112:115]
	v_mfma_f32_16x16x32_bf16 v[100:103], v[200:203], v[170:173], v[100:103]
	v_mfma_f32_16x16x32_bf16 v[96:99], v[208:211], v[170:173], v[96:99]
	v_mfma_f32_16x16x32_bf16 v[84:87], v[200:203], v[178:181], v[84:87]
	v_mfma_f32_16x16x32_bf16 v[80:83], v[208:211], v[178:181], v[80:83]
	v_mfma_f32_16x16x32_bf16 v[68:71], v[200:203], v[186:189], v[68:71]
	v_mfma_f32_16x16x32_bf16 v[64:67], v[208:211], v[186:189], v[64:67]
	v_mfma_f32_16x16x32_bf16 v[116:119], v[204:207], v[166:169], v[116:119]
	v_mfma_f32_16x16x32_bf16 v[112:115], v[212:215], v[166:169], v[112:115]
	v_mfma_f32_16x16x32_bf16 v[100:103], v[204:207], v[174:177], v[100:103]
	v_mfma_f32_16x16x32_bf16 v[96:99], v[212:215], v[174:177], v[96:99]
	v_mfma_f32_16x16x32_bf16 v[84:87], v[204:207], v[182:185], v[84:87]
	v_mfma_f32_16x16x32_bf16 v[80:83], v[212:215], v[182:185], v[80:83]
	v_mfma_f32_16x16x32_bf16 v[68:71], v[204:207], v[196:199], v[68:71]
	v_mfma_f32_16x16x32_bf16 v[64:67], v[212:215], v[196:199], v[64:67]
	s_mov_b32 m0, s57
	v_lshl_add_u64 v[190:191], v[218:219], 0, s[0:1]
	s_barrier
	ds_read_b128 v[162:165], v144 offset:49152
	ds_read_b128 v[166:169], v144 offset:50176
	ds_read_b128 v[170:173], v144 offset:51200
	ds_read_b128 v[174:177], v144 offset:52224
	ds_read_b128 v[178:181], v144 offset:53248
	ds_read_b128 v[182:185], v144 offset:54272
	ds_read_b128 v[186:189], v144 offset:55296
	ds_read_b128 v[196:199], v144 offset:56320
	global_load_lds_dwordx4 v[190:191], off
	v_lshl_add_u64 v[190:191], v[220:221], 0, s[0:1]
	s_mov_b32 m0, s58
	s_nop 0
	global_load_lds_dwordx4 v[190:191], off
	s_barrier
	s_waitcnt lgkmcnt(0)
	s_waitcnt lgkmcnt(0)
	v_mfma_f32_16x16x32_bf16 v[60:63], v[146:149], v[162:165], v[60:63]
	v_mfma_f32_16x16x32_bf16 v[56:59], v[154:157], v[162:165], v[56:59]
	v_mfma_f32_16x16x32_bf16 v[44:47], v[146:149], v[170:173], v[44:47]
	v_mfma_f32_16x16x32_bf16 v[40:43], v[154:157], v[170:173], v[40:43]
	v_mfma_f32_16x16x32_bf16 v[28:31], v[146:149], v[178:181], v[28:31]
	v_mfma_f32_16x16x32_bf16 v[24:27], v[154:157], v[178:181], v[24:27]
	v_mfma_f32_16x16x32_bf16 v[12:15], v[146:149], v[186:189], v[12:15]
	v_mfma_f32_16x16x32_bf16 v[8:11], v[154:157], v[186:189], v[8:11]
	v_mfma_f32_16x16x32_bf16 v[60:63], v[150:153], v[166:169], v[60:63]
	v_mfma_f32_16x16x32_bf16 v[56:59], v[158:161], v[166:169], v[56:59]
	v_mfma_f32_16x16x32_bf16 v[44:47], v[150:153], v[174:177], v[44:47]
	v_mfma_f32_16x16x32_bf16 v[40:43], v[158:161], v[174:177], v[40:43]
	v_mfma_f32_16x16x32_bf16 v[28:31], v[150:153], v[182:185], v[28:31]
	v_mfma_f32_16x16x32_bf16 v[24:27], v[158:161], v[182:185], v[24:27]
	v_mfma_f32_16x16x32_bf16 v[12:15], v[150:153], v[196:199], v[12:15]
	v_mfma_f32_16x16x32_bf16 v[8:11], v[158:161], v[196:199], v[8:11]
	s_barrier
	s_add_u32 s46, s46, 0x10080
	s_addc_u32 s47, s47, 0
	s_add_i32 s48, s48, s50
	v_lshl_add_u64 v[146:147], s[46:47], 0, v[132:133]
	s_mov_b32 m0, s48
	s_nop 0
	global_load_lds_dwordx4 v[146:147], off
	v_lshl_add_u64 v[146:147], s[46:47], 0, v[128:129]
	s_add_i32 m0, s48, 0x2000
	s_nop 0
	global_load_lds_dwordx4 v[146:147], off
	s_waitcnt vmcnt(6)
	s_barrier
	v_mfma_f32_16x16x32_bf16 v[52:55], v[200:203], v[162:165], v[52:55]
	v_mfma_f32_16x16x32_bf16 v[48:51], v[208:211], v[162:165], v[48:51]
	v_mfma_f32_16x16x32_bf16 v[36:39], v[200:203], v[170:173], v[36:39]
	v_mfma_f32_16x16x32_bf16 v[32:35], v[208:211], v[170:173], v[32:35]
	v_mfma_f32_16x16x32_bf16 v[20:23], v[200:203], v[178:181], v[20:23]
	v_mfma_f32_16x16x32_bf16 v[16:19], v[208:211], v[178:181], v[16:19]
	v_mfma_f32_16x16x32_bf16 v[4:7], v[200:203], v[186:189], v[4:7]
	v_mfma_f32_16x16x32_bf16 v[0:3], v[208:211], v[186:189], v[0:3]
	v_mfma_f32_16x16x32_bf16 v[52:55], v[204:207], v[166:169], v[52:55]
	v_mfma_f32_16x16x32_bf16 v[48:51], v[212:215], v[166:169], v[48:51]
	v_mfma_f32_16x16x32_bf16 v[36:39], v[204:207], v[174:177], v[36:39]
	v_mfma_f32_16x16x32_bf16 v[32:35], v[212:215], v[174:177], v[32:35]
	v_mfma_f32_16x16x32_bf16 v[20:23], v[204:207], v[182:185], v[20:23]
	v_mfma_f32_16x16x32_bf16 v[16:19], v[212:215], v[182:185], v[16:19]
	v_mfma_f32_16x16x32_bf16 v[4:7], v[204:207], v[196:199], v[4:7]
	v_mfma_f32_16x16x32_bf16 v[0:3], v[212:215], v[196:199], v[0:3]
	s_add_i32 s67, s67, 2
	s_add_u32 s44, s44, 0x100
	s_addc_u32 s45, s45, 0
	s_add_u32 s65, s65, 0x100
	s_addc_u32 s66, s66, 0
	s_cmp_gt_u32 s67, 13
	s_barrier
	s_cbranch_scc0 .LBB0_342
	v_cvt_pk_bf16_f32 v124, v124, v125
	v_cvt_pk_bf16_f32 v120, v120, v121
	v_cvt_pk_bf16_f32 v121, v122, v123
	v_cvt_pk_bf16_f32 v122, v116, v117
	v_cvt_pk_bf16_f32 v112, v112, v113
	v_cvt_pk_bf16_f32 v125, v126, v127
	v_cvt_pk_bf16_f32 v118, v118, v119
	v_cvt_pk_bf16_f32 v113, v114, v115
	v_cndmask_b32_e64 v114, v124, v122, s[2:3]
	v_mov_b32_e32 v123, 0
	v_cndmask_b32_e64 v115, v120, v112, s[2:3]
	v_mov_b32_e32 v126, 0
	v_lshl_add_u32 v148, s42, 8, v140
	v_mov_b32_dpp v123, v114 row_ror:8 row_mask:0xf bank_mask:0xf
	v_cndmask_b32_e64 v114, v125, v118, s[2:3]
	v_mov_b32_e32 v119, 0
	v_mov_b32_dpp v126, v115 row_ror:8 row_mask:0xf bank_mask:0xf
	v_mov_b32_e32 v127, 0
	v_mov_b32_dpp v119, v114 row_ror:8 row_mask:0xf bank_mask:0xf
	v_cndmask_b32_e64 v114, v121, v113, s[2:3]
	v_cndmask_b32_e64 v116, v126, v120, s[2:3]
	v_cndmask_b32_e64 v120, v112, v126, s[2:3]
	v_add_u32_e32 v112, -8, v148
	v_mov_b32_dpp v127, v114 row_ror:8 row_mask:0xf bank_mask:0xf
	v_cndmask_b32_e64 v112, v112, v148, s[2:3]
	v_lshl_or_b32 v146, s62, 8, v142
	v_cndmask_b32_e64 v117, v127, v121, s[2:3]
	v_cndmask_b32_e64 v121, v113, v127, s[2:3]
	v_ashrrev_i32_e32 v113, 31, v112
	v_ashrrev_i32_e32 v147, 31, v146
	v_lshlrev_b64 v[112:113], 11, v[112:113]
	v_cndmask_b32_e64 v115, v119, v125, s[2:3]
	v_cndmask_b32_e64 v114, v123, v124, s[2:3]
	v_cndmask_b32_e64 v119, v118, v119, s[2:3]
	v_cndmask_b32_e64 v118, v122, v123, s[2:3]
	v_lshl_add_u64 v[122:123], s[40:41], 0, v[112:113]
	v_lshlrev_b64 v[112:113], 1, v[146:147]
	v_lshl_add_u64 v[122:123], v[122:123], 0, v[112:113]
	global_store_dwordx4 v[122:123], v[114:117], off
	v_cvt_pk_bf16_f32 v108, v108, v109
	v_cvt_pk_bf16_f32 v100, v100, v101
	v_add_u32_e32 v116, 8, v148
	v_cndmask_b32_e64 v114, v148, v116, s[2:3]
	v_ashrrev_i32_e32 v115, 31, v114
	v_lshlrev_b64 v[114:115], 11, v[114:115]
	v_lshl_add_u64 v[114:115], s[40:41], 0, v[114:115]
	v_cvt_pk_bf16_f32 v109, v110, v111
	v_cvt_pk_bf16_f32 v104, v104, v105
	v_cvt_pk_bf16_f32 v105, v106, v107
	v_cvt_pk_bf16_f32 v101, v102, v103
	v_cvt_pk_bf16_f32 v102, v96, v97
	v_cndmask_b32_e64 v96, v108, v100, s[2:3]
	v_mov_b32_e32 v106, 0
	v_lshl_add_u64 v[114:115], v[114:115], 0, v[112:113]
	v_cvt_pk_bf16_f32 v103, v98, v99
	v_mov_b32_dpp v106, v96 row_ror:8 row_mask:0xf bank_mask:0xf
	v_cndmask_b32_e64 v96, v109, v101, s[2:3]
	v_mov_b32_e32 v107, 0
	v_cndmask_b32_e64 v97, v104, v102, s[2:3]
	v_mov_b32_e32 v110, 0
	global_store_dwordx4 v[114:115], v[118:121], off
	v_or_b32_e32 v114, 16, v148
	v_mov_b32_dpp v107, v96 row_ror:8 row_mask:0xf bank_mask:0xf
	v_cndmask_b32_e64 v96, v105, v103, s[2:3]
	v_mov_b32_dpp v110, v97 row_ror:8 row_mask:0xf bank_mask:0xf
	v_mov_b32_e32 v111, 0
	v_cndmask_b32_e64 v98, v110, v104, s[2:3]
	v_cndmask_b32_e64 v104, v116, v114, s[2:3]
	v_mov_b32_dpp v111, v96 row_ror:8 row_mask:0xf bank_mask:0xf
	v_cndmask_b32_e64 v99, v111, v105, s[2:3]
	v_ashrrev_i32_e32 v105, 31, v104
	v_lshlrev_b64 v[104:105], 11, v[104:105]
	v_lshl_add_u64 v[104:105], s[40:41], 0, v[104:105]
	v_cndmask_b32_e64 v97, v107, v109, s[2:3]
	v_cndmask_b32_e64 v96, v106, v108, s[2:3]
	v_lshl_add_u64 v[104:105], v[104:105], 0, v[112:113]
	global_store_dwordx4 v[104:105], v[96:99], off
	v_cvt_pk_bf16_f32 v92, v92, v93
	v_cvt_pk_bf16_f32 v84, v84, v85
	v_add_u32_e32 v98, 24, v148
	v_cndmask_b32_e64 v96, v114, v98, s[2:3]
	v_ashrrev_i32_e32 v97, 31, v96
	v_lshlrev_b64 v[96:97], 11, v[96:97]
	v_lshl_add_u64 v[96:97], s[40:41], 0, v[96:97]
	v_cvt_pk_bf16_f32 v93, v94, v95
	v_cvt_pk_bf16_f32 v88, v88, v89
	v_cvt_pk_bf16_f32 v89, v90, v91
	v_cvt_pk_bf16_f32 v85, v86, v87
	v_cvt_pk_bf16_f32 v86, v80, v81
	v_cndmask_b32_e64 v80, v92, v84, s[2:3]
	v_mov_b32_e32 v90, 0
	v_cndmask_b32_e64 v103, v103, v111, s[2:3]
	v_cndmask_b32_e64 v102, v102, v110, s[2:3]
	v_cndmask_b32_e64 v101, v101, v107, s[2:3]
	v_cndmask_b32_e64 v100, v100, v106, s[2:3]
	v_lshl_add_u64 v[96:97], v[96:97], 0, v[112:113]
	v_cvt_pk_bf16_f32 v87, v82, v83
	v_mov_b32_dpp v90, v80 row_ror:8 row_mask:0xf bank_mask:0xf
	v_cndmask_b32_e64 v80, v93, v85, s[2:3]
	v_mov_b32_e32 v91, 0
	v_cndmask_b32_e64 v81, v88, v86, s[2:3]
	v_mov_b32_e32 v94, 0
	global_store_dwordx4 v[96:97], v[100:103], off
	v_or_b32_e32 v96, 32, v148
	v_mov_b32_dpp v91, v80 row_ror:8 row_mask:0xf bank_mask:0xf
	v_cndmask_b32_e64 v80, v89, v87, s[2:3]
	v_mov_b32_dpp v94, v81 row_ror:8 row_mask:0xf bank_mask:0xf
	v_mov_b32_e32 v95, 0
	v_cndmask_b32_e64 v82, v94, v88, s[2:3]
	v_cndmask_b32_e64 v88, v98, v96, s[2:3]
	v_mov_b32_dpp v95, v80 row_ror:8 row_mask:0xf bank_mask:0xf
	v_cndmask_b32_e64 v83, v95, v89, s[2:3]
	v_ashrrev_i32_e32 v89, 31, v88
	v_lshlrev_b64 v[88:89], 11, v[88:89]
	v_lshl_add_u64 v[88:89], s[40:41], 0, v[88:89]
	v_cndmask_b32_e64 v81, v91, v93, s[2:3]
	v_cndmask_b32_e64 v80, v90, v92, s[2:3]
	v_lshl_add_u64 v[88:89], v[88:89], 0, v[112:113]
	global_store_dwordx4 v[88:89], v[80:83], off
	v_cvt_pk_bf16_f32 v76, v76, v77
	v_cvt_pk_bf16_f32 v68, v68, v69
	v_add_u32_e32 v82, 40, v148
	v_cndmask_b32_e64 v80, v96, v82, s[2:3]
	v_ashrrev_i32_e32 v81, 31, v80
	v_lshlrev_b64 v[80:81], 11, v[80:81]
	v_lshl_add_u64 v[80:81], s[40:41], 0, v[80:81]
	v_cvt_pk_bf16_f32 v77, v78, v79
	v_cvt_pk_bf16_f32 v72, v72, v73
	v_cvt_pk_bf16_f32 v73, v74, v75
	v_cvt_pk_bf16_f32 v69, v70, v71
	v_cvt_pk_bf16_f32 v70, v64, v65
	v_cndmask_b32_e64 v64, v76, v68, s[2:3]
	v_mov_b32_e32 v74, 0
	v_cndmask_b32_e64 v87, v87, v95, s[2:3]
	v_cndmask_b32_e64 v86, v86, v94, s[2:3]
	v_cndmask_b32_e64 v85, v85, v91, s[2:3]
	v_cndmask_b32_e64 v84, v84, v90, s[2:3]
	v_lshl_add_u64 v[80:81], v[80:81], 0, v[112:113]
	v_cvt_pk_bf16_f32 v71, v66, v67
	v_mov_b32_dpp v74, v64 row_ror:8 row_mask:0xf bank_mask:0xf
	v_cndmask_b32_e64 v64, v77, v69, s[2:3]
	v_mov_b32_e32 v75, 0
	v_cndmask_b32_e64 v65, v72, v70, s[2:3]
	v_mov_b32_e32 v78, 0
	global_store_dwordx4 v[80:81], v[84:87], off
	v_or_b32_e32 v80, 48, v148
	v_mov_b32_dpp v75, v64 row_ror:8 row_mask:0xf bank_mask:0xf
	v_cndmask_b32_e64 v64, v73, v71, s[2:3]
	v_mov_b32_dpp v78, v65 row_ror:8 row_mask:0xf bank_mask:0xf
	v_mov_b32_e32 v79, 0
	v_cndmask_b32_e64 v66, v78, v72, s[2:3]
	v_cndmask_b32_e64 v72, v82, v80, s[2:3]
	v_mov_b32_dpp v79, v64 row_ror:8 row_mask:0xf bank_mask:0xf
	v_cndmask_b32_e64 v67, v79, v73, s[2:3]
	v_ashrrev_i32_e32 v73, 31, v72
	v_lshlrev_b64 v[72:73], 11, v[72:73]
	v_lshl_add_u64 v[72:73], s[40:41], 0, v[72:73]
	v_cndmask_b32_e64 v65, v75, v77, s[2:3]
	v_cndmask_b32_e64 v64, v74, v76, s[2:3]
	v_lshl_add_u64 v[72:73], v[72:73], 0, v[112:113]
	global_store_dwordx4 v[72:73], v[64:67], off
	v_cvt_pk_bf16_f32 v60, v60, v61
	v_cvt_pk_bf16_f32 v56, v56, v57
	v_add_u32_e32 v64, 56, v148
	v_cndmask_b32_e64 v64, v80, v64, s[2:3]
	v_ashrrev_i32_e32 v65, 31, v64
	v_lshlrev_b64 v[64:65], 11, v[64:65]
	v_cvt_pk_bf16_f32 v52, v52, v53
	v_cvt_pk_bf16_f32 v53, v54, v55
	v_cvt_pk_bf16_f32 v54, v48, v49
	v_lshl_add_u64 v[64:65], s[40:41], 0, v[64:65]
	v_cvt_pk_bf16_f32 v61, v62, v63
	v_cvt_pk_bf16_f32 v57, v58, v59
	v_cndmask_b32_e64 v48, v60, v52, s[2:3]
	v_mov_b32_e32 v58, 0
	v_cndmask_b32_e64 v49, v56, v54, s[2:3]
	v_mov_b32_e32 v62, 0
	v_cndmask_b32_e64 v71, v71, v79, s[2:3]
	v_cndmask_b32_e64 v70, v70, v78, s[2:3]
	v_cndmask_b32_e64 v69, v69, v75, s[2:3]
	v_cndmask_b32_e64 v68, v68, v74, s[2:3]
	v_lshl_add_u64 v[64:65], v[64:65], 0, v[112:113]
	v_cvt_pk_bf16_f32 v55, v50, v51
	v_mov_b32_dpp v58, v48 row_ror:8 row_mask:0xf bank_mask:0xf
	v_cndmask_b32_e64 v48, v61, v53, s[2:3]
	v_mov_b32_e32 v59, 0
	v_mov_b32_dpp v62, v49 row_ror:8 row_mask:0xf bank_mask:0xf
	global_store_dwordx4 v[64:65], v[68:71], off
	v_add_u32_e32 v64, 0x80, v148
	v_mov_b32_dpp v59, v48 row_ror:8 row_mask:0xf bank_mask:0xf
	v_cndmask_b32_e64 v48, v57, v55, s[2:3]
	v_mov_b32_e32 v63, 0
	v_cndmask_b32_e64 v50, v62, v56, s[2:3]
	v_add_u32_e32 v56, 0x78, v148
	v_mov_b32_dpp v63, v48 row_ror:8 row_mask:0xf bank_mask:0xf
	v_cndmask_b32_e64 v56, v56, v64, s[2:3]
	v_cndmask_b32_e64 v51, v63, v57, s[2:3]
	v_ashrrev_i32_e32 v57, 31, v56
	v_lshlrev_b64 v[56:57], 11, v[56:57]
	v_lshl_add_u64 v[56:57], s[40:41], 0, v[56:57]
	v_cndmask_b32_e64 v49, v59, v61, s[2:3]
	v_cndmask_b32_e64 v48, v58, v60, s[2:3]
	v_lshl_add_u64 v[56:57], v[56:57], 0, v[112:113]
	global_store_dwordx4 v[56:57], v[48:51], off
	v_cvt_pk_bf16_f32 v44, v44, v45
	v_cvt_pk_bf16_f32 v36, v36, v37
	v_add_u32_e32 v50, 0x88, v148
	v_cndmask_b32_e64 v48, v64, v50, s[2:3]
	v_ashrrev_i32_e32 v49, 31, v48
	v_lshlrev_b64 v[48:49], 11, v[48:49]
	v_lshl_add_u64 v[48:49], s[40:41], 0, v[48:49]
	v_cvt_pk_bf16_f32 v45, v46, v47
	v_cvt_pk_bf16_f32 v40, v40, v41
	v_cvt_pk_bf16_f32 v41, v42, v43
	v_cvt_pk_bf16_f32 v37, v38, v39
	v_cvt_pk_bf16_f32 v38, v32, v33
	v_cndmask_b32_e64 v32, v44, v36, s[2:3]
	v_mov_b32_e32 v42, 0
	v_cndmask_b32_e64 v55, v55, v63, s[2:3]
	v_cndmask_b32_e64 v54, v54, v62, s[2:3]
	v_cndmask_b32_e64 v53, v53, v59, s[2:3]
	v_cndmask_b32_e64 v52, v52, v58, s[2:3]
	v_lshl_add_u64 v[48:49], v[48:49], 0, v[112:113]
	v_cvt_pk_bf16_f32 v39, v34, v35
	v_mov_b32_dpp v42, v32 row_ror:8 row_mask:0xf bank_mask:0xf
	v_cndmask_b32_e64 v32, v45, v37, s[2:3]
	v_mov_b32_e32 v43, 0
	v_cndmask_b32_e64 v33, v40, v38, s[2:3]
	v_mov_b32_e32 v46, 0
	global_store_dwordx4 v[48:49], v[52:55], off
	v_add_u32_e32 v48, 0x90, v148
	v_mov_b32_dpp v43, v32 row_ror:8 row_mask:0xf bank_mask:0xf
	v_cndmask_b32_e64 v32, v41, v39, s[2:3]
	v_mov_b32_dpp v46, v33 row_ror:8 row_mask:0xf bank_mask:0xf
	v_mov_b32_e32 v47, 0
	v_cndmask_b32_e64 v34, v46, v40, s[2:3]
	v_cndmask_b32_e64 v40, v50, v48, s[2:3]
	v_mov_b32_dpp v47, v32 row_ror:8 row_mask:0xf bank_mask:0xf
	v_cndmask_b32_e64 v35, v47, v41, s[2:3]
	v_ashrrev_i32_e32 v41, 31, v40
	v_lshlrev_b64 v[40:41], 11, v[40:41]
	v_lshl_add_u64 v[40:41], s[40:41], 0, v[40:41]
	v_cndmask_b32_e64 v33, v43, v45, s[2:3]
	v_cndmask_b32_e64 v32, v42, v44, s[2:3]
	v_lshl_add_u64 v[40:41], v[40:41], 0, v[112:113]
	global_store_dwordx4 v[40:41], v[32:35], off
	v_cvt_pk_bf16_f32 v28, v28, v29
	v_cvt_pk_bf16_f32 v20, v20, v21
	v_add_u32_e32 v34, 0x98, v148
	v_cndmask_b32_e64 v32, v48, v34, s[2:3]
	v_ashrrev_i32_e32 v33, 31, v32
	v_lshlrev_b64 v[32:33], 11, v[32:33]
	v_lshl_add_u64 v[32:33], s[40:41], 0, v[32:33]
	v_cvt_pk_bf16_f32 v29, v30, v31
	v_cvt_pk_bf16_f32 v24, v24, v25
	v_cvt_pk_bf16_f32 v25, v26, v27
	v_cvt_pk_bf16_f32 v21, v22, v23
	v_cvt_pk_bf16_f32 v22, v16, v17
	v_cndmask_b32_e64 v16, v28, v20, s[2:3]
	v_mov_b32_e32 v26, 0
	v_cndmask_b32_e64 v39, v39, v47, s[2:3]
	v_cndmask_b32_e64 v38, v38, v46, s[2:3]
	v_cndmask_b32_e64 v37, v37, v43, s[2:3]
	v_cndmask_b32_e64 v36, v36, v42, s[2:3]
	v_lshl_add_u64 v[32:33], v[32:33], 0, v[112:113]
	v_cvt_pk_bf16_f32 v23, v18, v19
	v_mov_b32_dpp v26, v16 row_ror:8 row_mask:0xf bank_mask:0xf
	v_cndmask_b32_e64 v16, v29, v21, s[2:3]
	v_mov_b32_e32 v27, 0
	v_cndmask_b32_e64 v17, v24, v22, s[2:3]
	v_mov_b32_e32 v30, 0
	global_store_dwordx4 v[32:33], v[36:39], off
	v_add_u32_e32 v32, 0xa0, v148
	v_mov_b32_dpp v27, v16 row_ror:8 row_mask:0xf bank_mask:0xf
	v_cndmask_b32_e64 v16, v25, v23, s[2:3]
	v_mov_b32_dpp v30, v17 row_ror:8 row_mask:0xf bank_mask:0xf
	v_mov_b32_e32 v31, 0
	v_cndmask_b32_e64 v18, v30, v24, s[2:3]
	v_cndmask_b32_e64 v24, v34, v32, s[2:3]
	v_mov_b32_dpp v31, v16 row_ror:8 row_mask:0xf bank_mask:0xf
	v_cndmask_b32_e64 v19, v31, v25, s[2:3]
	v_ashrrev_i32_e32 v25, 31, v24
	v_lshlrev_b64 v[24:25], 11, v[24:25]
	v_lshl_add_u64 v[24:25], s[40:41], 0, v[24:25]
	v_cndmask_b32_e64 v17, v27, v29, s[2:3]
	v_cndmask_b32_e64 v16, v26, v28, s[2:3]
	v_lshl_add_u64 v[24:25], v[24:25], 0, v[112:113]
	global_store_dwordx4 v[24:25], v[16:19], off
	v_cndmask_b32_e64 v23, v23, v31, s[2:3]
	v_cndmask_b32_e64 v22, v22, v30, s[2:3]
	v_add_u32_e32 v18, 0xa8, v148
	v_cndmask_b32_e64 v16, v32, v18, s[2:3]
	v_ashrrev_i32_e32 v17, 31, v16
	v_lshlrev_b64 v[16:17], 11, v[16:17]
	v_lshl_add_u64 v[16:17], s[40:41], 0, v[16:17]
	v_cndmask_b32_e64 v21, v21, v27, s[2:3]
	v_cndmask_b32_e64 v20, v20, v26, s[2:3]
	v_lshl_add_u64 v[16:17], v[16:17], 0, v[112:113]
	global_store_dwordx4 v[16:17], v[20:23], off
	v_add_u32_e32 v16, 0xb0, v148
	v_cvt_pk_bf16_f32 v12, v12, v13
	v_cvt_pk_bf16_f32 v8, v8, v9
	v_cvt_pk_bf16_f32 v9, v10, v11
	v_cvt_pk_bf16_f32 v10, v4, v5
	v_cvt_pk_bf16_f32 v13, v14, v15
	v_cvt_pk_bf16_f32 v6, v6, v7
	v_cvt_pk_bf16_f32 v7, v0, v1
	v_cndmask_b32_e64 v0, v12, v10, s[2:3]
	v_mov_b32_e32 v14, 0
	v_cndmask_b32_e64 v4, v18, v16, s[2:3]
	v_cvt_pk_bf16_f32 v11, v2, v3
	v_mov_b32_dpp v14, v0 row_ror:8 row_mask:0xf bank_mask:0xf
	v_cndmask_b32_e64 v0, v13, v6, s[2:3]
	v_mov_b32_e32 v15, 0
	v_ashrrev_i32_e32 v5, 31, v4
	v_cndmask_b32_e64 v1, v8, v7, s[2:3]
	v_mov_b32_dpp v15, v0 row_ror:8 row_mask:0xf bank_mask:0xf
	v_cndmask_b32_e64 v0, v9, v11, s[2:3]
	v_mov_b32_e32 v17, 0
	v_mov_b32_e32 v19, 0
	v_lshlrev_b64 v[4:5], 11, v[4:5]
	v_mov_b32_dpp v17, v1 row_ror:8 row_mask:0xf bank_mask:0xf
	v_mov_b32_dpp v19, v0 row_ror:8 row_mask:0xf bank_mask:0xf
	v_lshl_add_u64 v[4:5], s[40:41], 0, v[4:5]
	v_cndmask_b32_e64 v3, v19, v9, s[2:3]
	v_cndmask_b32_e64 v2, v17, v8, s[2:3]
	v_cndmask_b32_e64 v1, v15, v13, s[2:3]
	v_cndmask_b32_e64 v0, v14, v12, s[2:3]
	v_lshl_add_u64 v[4:5], v[4:5], 0, v[112:113]
	global_store_dwordx4 v[4:5], v[0:3], off
	s_and_b64 vcc, exec, s[4:5]
	s_mov_b32 s62, s6
	v_add_u32_e32 v0, 0xb8, v148
	v_cndmask_b32_e64 v0, v16, v0, s[2:3]
	v_ashrrev_i32_e32 v1, 31, v0
	v_lshlrev_b64 v[0:1], 11, v[0:1]
	v_lshl_add_u64 v[0:1], s[40:41], 0, v[0:1]
	v_lshl_add_u64 v[4:5], v[0:1], 0, v[112:113]
	v_cndmask_b32_e64 v3, v11, v19, s[2:3]
	v_cndmask_b32_e64 v2, v7, v17, s[2:3]
	v_cndmask_b32_e64 v1, v6, v15, s[2:3]
	v_cndmask_b32_e64 v0, v10, v14, s[2:3]
	s_mov_b32 s42, s8
	s_mov_b64 s[46:47], s[12:13]
	s_mov_b64 s[44:45], s[10:11]
	global_store_dwordx4 v[4:5], v[0:3], off
	s_cbranch_vccz .LBB0_335
	s_waitcnt vmcnt(0)
	s_cmpk_gt_u32 s17, 0xff
	s_cbranch_scc1 .LBB0_346
	s_barrier

.LBB0_667:
	s_add_u32 s56, s52, s54
	s_addc_u32 s57, s53, s55
	s_add_u32 s56, s56, 0x100
	s_addc_u32 s57, s57, 0
	s_add_u32 vcc_lo, s96, s54
	s_addc_u32 vcc_hi, s97, s55
	s_cmpk_eq_i32 s54, 0x700
	s_cselect_b32 s59, s47, s57
	s_cselect_b32 s58, s94, s56
	s_cselect_b32 s57, s45, vcc_hi
	s_cselect_b32 s56, s95, vcc_lo
	s_add_i32 vcc_lo, 0, 0x10000
	v_add_u32_e32 v1, vcc_lo, v196
	ds_read_b128 v[132:135], v1
	ds_read_b128 v[136:139], v1 offset:1024
	ds_read_b128 v[140:143], v1 offset:2048
	ds_read_b128 v[144:147], v1 offset:3072
	v_lshl_add_u64 v[2:3], v[188:189], 0, s[54:55]
	s_add_i32 m0, s63, 0xc000
	ds_read_b128 v[148:151], v199
	ds_read_b128 v[152:155], v199 offset:1024
	ds_read_b128 v[156:159], v199 offset:2048
	ds_read_b128 v[160:163], v199 offset:3072
	ds_read_b128 v[164:167], v199 offset:4096
	ds_read_b128 v[200:203], v199 offset:5120
	ds_read_b128 v[204:207], v199 offset:6144
	ds_read_b128 v[208:211], v199 offset:7168
	global_load_lds_dwordx4 v[2:3], off
	v_lshl_add_u64 v[2:3], v[190:191], 0, s[54:55]
	s_add_i32 m0, s63, 0xe000
	s_nop 0
	global_load_lds_dwordx4 v[2:3], off
	s_waitcnt lgkmcnt(8)
	s_barrier
	s_waitcnt lgkmcnt(0)
	s_waitcnt lgkmcnt(0)
	v_mfma_f32_16x16x32_bf16 v[128:131], v[132:135], v[148:151], v[128:131]
	v_mfma_f32_16x16x32_bf16 v[124:127], v[140:143], v[148:151], v[124:127]
	v_mfma_f32_16x16x32_bf16 v[112:115], v[132:135], v[156:159], v[112:115]
	v_mfma_f32_16x16x32_bf16 v[108:111], v[140:143], v[156:159], v[108:111]
	v_mfma_f32_16x16x32_bf16 v[96:99], v[132:135], v[164:167], v[96:99]
	v_mfma_f32_16x16x32_bf16 v[92:95], v[140:143], v[164:167], v[92:95]
	v_mfma_f32_16x16x32_bf16 v[80:83], v[132:135], v[204:207], v[80:83]
	v_mfma_f32_16x16x32_bf16 v[76:79], v[140:143], v[204:207], v[76:79]
	v_mfma_f32_16x16x32_bf16 v[128:131], v[136:139], v[152:155], v[128:131]
	v_mfma_f32_16x16x32_bf16 v[124:127], v[144:147], v[152:155], v[124:127]
	v_mfma_f32_16x16x32_bf16 v[112:115], v[136:139], v[160:163], v[112:115]
	v_mfma_f32_16x16x32_bf16 v[108:111], v[144:147], v[160:163], v[108:111]
	v_mfma_f32_16x16x32_bf16 v[96:99], v[136:139], v[200:203], v[96:99]
	v_mfma_f32_16x16x32_bf16 v[92:95], v[144:147], v[200:203], v[92:95]
	v_mfma_f32_16x16x32_bf16 v[80:83], v[136:139], v[208:211], v[80:83]
	v_mfma_f32_16x16x32_bf16 v[76:79], v[144:147], v[208:211], v[76:79]
	s_barrier
	s_add_i32 vcc_lo, vcc_lo, s61
	v_add_u32_e32 v1, s93, v196
	v_lshl_add_u64 v[228:229], s[56:57], 0, v[172:173]
	s_mov_b32 m0, vcc_lo
	ds_read_b128 v[212:215], v1
	ds_read_b128 v[216:219], v1 offset:1024
	ds_read_b128 v[220:223], v1 offset:2048
	ds_read_b128 v[224:227], v1 offset:3072
	global_load_lds_dwordx4 v[228:229], off
	v_lshl_add_u64 v[230:231], s[56:57], 0, v[168:169]
	s_add_i32 m0, vcc_lo, 0x2000
	s_nop 0
	global_load_lds_dwordx4 v[230:231], off
	s_barrier
	s_waitcnt lgkmcnt(0)
	s_waitcnt lgkmcnt(0)
	v_mfma_f32_16x16x32_bf16 v[120:123], v[212:215], v[148:151], v[120:123]
	v_mfma_f32_16x16x32_bf16 v[116:119], v[220:223], v[148:151], v[116:119]
	v_mfma_f32_16x16x32_bf16 v[104:107], v[212:215], v[156:159], v[104:107]
	v_mfma_f32_16x16x32_bf16 v[100:103], v[220:223], v[156:159], v[100:103]
	v_mfma_f32_16x16x32_bf16 v[88:91], v[212:215], v[164:167], v[88:91]
	v_mfma_f32_16x16x32_bf16 v[84:87], v[220:223], v[164:167], v[84:87]
	v_mfma_f32_16x16x32_bf16 v[72:75], v[212:215], v[204:207], v[72:75]
	v_mfma_f32_16x16x32_bf16 v[68:71], v[220:223], v[204:207], v[68:71]
	v_mfma_f32_16x16x32_bf16 v[120:123], v[216:219], v[152:155], v[120:123]
	v_mfma_f32_16x16x32_bf16 v[116:119], v[224:227], v[152:155], v[116:119]
	v_mfma_f32_16x16x32_bf16 v[104:107], v[216:219], v[160:163], v[104:107]
	v_mfma_f32_16x16x32_bf16 v[100:103], v[224:227], v[160:163], v[100:103]
	v_mfma_f32_16x16x32_bf16 v[88:91], v[216:219], v[200:203], v[88:91]
	v_mfma_f32_16x16x32_bf16 v[84:87], v[224:227], v[200:203], v[84:87]
	v_mfma_f32_16x16x32_bf16 v[72:75], v[216:219], v[208:211], v[72:75]
	v_mfma_f32_16x16x32_bf16 v[68:71], v[224:227], v[208:211], v[68:71]
	s_mov_b32 m0, s63
	v_lshl_add_u64 v[232:233], s[58:59], 0, v[174:175]
	s_barrier
	ds_read_b128 v[148:151], v199 offset:16384
	ds_read_b128 v[152:155], v199 offset:17408
	ds_read_b128 v[156:159], v199 offset:18432
	ds_read_b128 v[160:163], v199 offset:19456
	ds_read_b128 v[164:167], v199 offset:20480
	ds_read_b128 v[200:203], v199 offset:21504
	ds_read_b128 v[204:207], v199 offset:22528
	ds_read_b128 v[208:211], v199 offset:23552
	global_load_lds_dwordx4 v[232:233], off
	v_lshl_add_u64 v[234:235], s[58:59], 0, v[170:171]
	s_mov_b32 m0, s64
	s_nop 0
	global_load_lds_dwordx4 v[234:235], off
	s_barrier
	s_waitcnt lgkmcnt(0)
	s_waitcnt lgkmcnt(0)
	v_mfma_f32_16x16x32_bf16 v[64:67], v[132:135], v[148:151], v[64:67]
	v_mfma_f32_16x16x32_bf16 v[60:63], v[140:143], v[148:151], v[60:63]
	v_mfma_f32_16x16x32_bf16 v[48:51], v[132:135], v[156:159], v[48:51]
	v_mfma_f32_16x16x32_bf16 v[44:47], v[140:143], v[156:159], v[44:47]
	v_mfma_f32_16x16x32_bf16 v[32:35], v[132:135], v[164:167], v[32:35]
	v_mfma_f32_16x16x32_bf16 v[28:31], v[140:143], v[164:167], v[28:31]
	v_mfma_f32_16x16x32_bf16 v[16:19], v[132:135], v[204:207], v[16:19]
	v_mfma_f32_16x16x32_bf16 v[12:15], v[140:143], v[204:207], v[12:15]
	v_mfma_f32_16x16x32_bf16 v[64:67], v[136:139], v[152:155], v[64:67]
	v_mfma_f32_16x16x32_bf16 v[60:63], v[144:147], v[152:155], v[60:63]
	v_mfma_f32_16x16x32_bf16 v[48:51], v[136:139], v[160:163], v[48:51]
	v_mfma_f32_16x16x32_bf16 v[44:47], v[144:147], v[160:163], v[44:47]
	v_mfma_f32_16x16x32_bf16 v[32:35], v[136:139], v[200:203], v[32:35]
	v_mfma_f32_16x16x32_bf16 v[28:31], v[144:147], v[200:203], v[28:31]
	v_mfma_f32_16x16x32_bf16 v[16:19], v[136:139], v[208:211], v[16:19]
	v_mfma_f32_16x16x32_bf16 v[12:15], v[144:147], v[208:211], v[12:15]
	s_barrier
	s_add_u32 vcc_lo, s56, 0x10000
	s_addc_u32 vcc_hi, s57, 0
	s_add_i32 s28, s93, s61
	v_lshl_add_u64 v[2:3], vcc, 0, v[172:173]
	s_mov_b32 m0, s28
	s_nop 0
	global_load_lds_dwordx4 v[2:3], off
	v_lshl_add_u64 v[2:3], vcc, 0, v[168:169]
	s_add_i32 m0, s28, 0x2000
	s_nop 0
	global_load_lds_dwordx4 v[2:3], off
	s_waitcnt vmcnt(6)
	s_barrier
	v_mfma_f32_16x16x32_bf16 v[56:59], v[212:215], v[148:151], v[56:59]
	v_mfma_f32_16x16x32_bf16 v[52:55], v[220:223], v[148:151], v[52:55]
	v_mfma_f32_16x16x32_bf16 v[40:43], v[212:215], v[156:159], v[40:43]
	v_mfma_f32_16x16x32_bf16 v[36:39], v[220:223], v[156:159], v[36:39]
	v_mfma_f32_16x16x32_bf16 v[24:27], v[212:215], v[164:167], v[24:27]
	v_mfma_f32_16x16x32_bf16 v[20:23], v[220:223], v[164:167], v[20:23]
	v_mfma_f32_16x16x32_bf16 v[8:11], v[212:215], v[204:207], v[8:11]
	v_mfma_f32_16x16x32_bf16 v[2:5], v[220:223], v[204:207], v[4:7]
	v_mfma_f32_16x16x32_bf16 v[56:59], v[216:219], v[152:155], v[56:59]
	v_mfma_f32_16x16x32_bf16 v[52:55], v[224:227], v[152:155], v[52:55]
	v_mfma_f32_16x16x32_bf16 v[40:43], v[216:219], v[160:163], v[40:43]
	v_mfma_f32_16x16x32_bf16 v[36:39], v[224:227], v[160:163], v[36:39]
	v_mfma_f32_16x16x32_bf16 v[24:27], v[216:219], v[200:203], v[24:27]
	v_mfma_f32_16x16x32_bf16 v[20:23], v[224:227], v[200:203], v[20:23]
	v_mfma_f32_16x16x32_bf16 v[8:11], v[216:219], v[208:211], v[8:11]
	v_mfma_f32_16x16x32_bf16 v[2:5], v[224:227], v[208:211], v[2:5]
	s_add_i32 s28, 0, 0x18000
	v_add_u32_e32 v1, s28, v196
	s_barrier
	ds_read_b128 v[132:135], v1
	ds_read_b128 v[136:139], v1 offset:1024
	ds_read_b128 v[140:143], v1 offset:2048
	ds_read_b128 v[144:147], v1 offset:3072
	s_add_u32 s58, s58, 0x40000
	s_addc_u32 s59, s59, 0
	s_mov_b32 m0, s65
	v_lshl_add_u64 v[6:7], s[58:59], 0, v[174:175]
	ds_read_b128 v[148:151], v199 offset:32768
	ds_read_b128 v[152:155], v199 offset:33792
	ds_read_b128 v[156:159], v199 offset:34816
	ds_read_b128 v[160:163], v199 offset:35840
	ds_read_b128 v[164:167], v199 offset:36864
	ds_read_b128 v[200:203], v199 offset:37888
	ds_read_b128 v[204:207], v199 offset:38912
	ds_read_b128 v[208:211], v199 offset:39936
	global_load_lds_dwordx4 v[6:7], off
	v_lshl_add_u64 v[6:7], s[58:59], 0, v[170:171]
	s_mov_b32 m0, s66
	s_nop 0
	global_load_lds_dwordx4 v[6:7], off
	s_waitcnt lgkmcnt(8)
	s_barrier
	s_waitcnt lgkmcnt(0)
	s_waitcnt lgkmcnt(0)
	v_mfma_f32_16x16x32_bf16 v[128:131], v[132:135], v[148:151], v[128:131]
	v_mfma_f32_16x16x32_bf16 v[124:127], v[140:143], v[148:151], v[124:127]
	v_mfma_f32_16x16x32_bf16 v[112:115], v[132:135], v[156:159], v[112:115]
	v_mfma_f32_16x16x32_bf16 v[108:111], v[140:143], v[156:159], v[108:111]
	v_mfma_f32_16x16x32_bf16 v[96:99], v[132:135], v[164:167], v[96:99]
	v_mfma_f32_16x16x32_bf16 v[92:95], v[140:143], v[164:167], v[92:95]
	v_mfma_f32_16x16x32_bf16 v[80:83], v[132:135], v[204:207], v[80:83]
	v_mfma_f32_16x16x32_bf16 v[76:79], v[140:143], v[204:207], v[76:79]
	v_mfma_f32_16x16x32_bf16 v[128:131], v[136:139], v[152:155], v[128:131]
	v_mfma_f32_16x16x32_bf16 v[124:127], v[144:147], v[152:155], v[124:127]
	v_mfma_f32_16x16x32_bf16 v[112:115], v[136:139], v[160:163], v[112:115]
	v_mfma_f32_16x16x32_bf16 v[108:111], v[144:147], v[160:163], v[108:111]
	v_mfma_f32_16x16x32_bf16 v[96:99], v[136:139], v[200:203], v[96:99]
	v_mfma_f32_16x16x32_bf16 v[92:95], v[144:147], v[200:203], v[92:95]
	v_mfma_f32_16x16x32_bf16 v[80:83], v[136:139], v[208:211], v[80:83]
	v_mfma_f32_16x16x32_bf16 v[76:79], v[144:147], v[208:211], v[76:79]
	s_barrier
	s_add_i32 s29, 0, 0x1c000
	s_add_i32 s28, s28, s61
	v_add_u32_e32 v1, s29, v196
	v_lshl_add_u64 v[6:7], v[228:229], 0, s[0:1]
	s_mov_b32 m0, s28
	ds_read_b128 v[212:215], v1
	ds_read_b128 v[216:219], v1 offset:1024
	ds_read_b128 v[220:223], v1 offset:2048
	ds_read_b128 v[224:227], v1 offset:3072
	global_load_lds_dwordx4 v[6:7], off
	v_lshl_add_u64 v[6:7], v[230:231], 0, s[0:1]
	s_add_i32 m0, s28, 0x2000
	s_nop 0
	global_load_lds_dwordx4 v[6:7], off
	s_barrier
	s_waitcnt lgkmcnt(0)
	s_waitcnt lgkmcnt(0)
	v_mfma_f32_16x16x32_bf16 v[120:123], v[212:215], v[148:151], v[120:123]
	v_mfma_f32_16x16x32_bf16 v[116:119], v[220:223], v[148:151], v[116:119]
	v_mfma_f32_16x16x32_bf16 v[104:107], v[212:215], v[156:159], v[104:107]
	v_mfma_f32_16x16x32_bf16 v[100:103], v[220:223], v[156:159], v[100:103]
	v_mfma_f32_16x16x32_bf16 v[88:91], v[212:215], v[164:167], v[88:91]
	v_mfma_f32_16x16x32_bf16 v[84:87], v[220:223], v[164:167], v[84:87]
	v_mfma_f32_16x16x32_bf16 v[72:75], v[212:215], v[204:207], v[72:75]
	v_mfma_f32_16x16x32_bf16 v[68:71], v[220:223], v[204:207], v[68:71]
	v_mfma_f32_16x16x32_bf16 v[120:123], v[216:219], v[152:155], v[120:123]
	v_mfma_f32_16x16x32_bf16 v[116:119], v[224:227], v[152:155], v[116:119]
	v_mfma_f32_16x16x32_bf16 v[104:107], v[216:219], v[160:163], v[104:107]
	v_mfma_f32_16x16x32_bf16 v[100:103], v[224:227], v[160:163], v[100:103]
	v_mfma_f32_16x16x32_bf16 v[88:91], v[216:219], v[200:203], v[88:91]
	v_mfma_f32_16x16x32_bf16 v[84:87], v[224:227], v[200:203], v[84:87]
	v_mfma_f32_16x16x32_bf16 v[72:75], v[216:219], v[208:211], v[72:75]
	v_mfma_f32_16x16x32_bf16 v[68:71], v[224:227], v[208:211], v[68:71]
	s_mov_b32 m0, s81
	v_lshl_add_u64 v[6:7], v[232:233], 0, s[0:1]
	s_barrier
	ds_read_b128 v[148:151], v199 offset:49152
	ds_read_b128 v[152:155], v199 offset:50176
	ds_read_b128 v[156:159], v199 offset:51200
	ds_read_b128 v[160:163], v199 offset:52224
	ds_read_b128 v[164:167], v199 offset:53248
	ds_read_b128 v[200:203], v199 offset:54272
	ds_read_b128 v[204:207], v199 offset:55296
	ds_read_b128 v[208:211], v199 offset:56320
	global_load_lds_dwordx4 v[6:7], off
	v_lshl_add_u64 v[6:7], v[234:235], 0, s[0:1]
	s_mov_b32 m0, s82
	s_nop 0
	global_load_lds_dwordx4 v[6:7], off
	s_barrier
	s_waitcnt lgkmcnt(0)
	s_waitcnt lgkmcnt(0)
	v_mfma_f32_16x16x32_bf16 v[64:67], v[132:135], v[148:151], v[64:67]
	v_mfma_f32_16x16x32_bf16 v[60:63], v[140:143], v[148:151], v[60:63]
	v_mfma_f32_16x16x32_bf16 v[48:51], v[132:135], v[156:159], v[48:51]
	v_mfma_f32_16x16x32_bf16 v[44:47], v[140:143], v[156:159], v[44:47]
	v_mfma_f32_16x16x32_bf16 v[32:35], v[132:135], v[164:167], v[32:35]
	v_mfma_f32_16x16x32_bf16 v[28:31], v[140:143], v[164:167], v[28:31]
	v_mfma_f32_16x16x32_bf16 v[16:19], v[132:135], v[204:207], v[16:19]
	v_mfma_f32_16x16x32_bf16 v[12:15], v[140:143], v[204:207], v[12:15]
	v_mfma_f32_16x16x32_bf16 v[64:67], v[136:139], v[152:155], v[64:67]
	v_mfma_f32_16x16x32_bf16 v[60:63], v[144:147], v[152:155], v[60:63]
	v_mfma_f32_16x16x32_bf16 v[48:51], v[136:139], v[160:163], v[48:51]
	v_mfma_f32_16x16x32_bf16 v[44:47], v[144:147], v[160:163], v[44:47]
	v_mfma_f32_16x16x32_bf16 v[32:35], v[136:139], v[200:203], v[32:35]
	v_mfma_f32_16x16x32_bf16 v[28:31], v[144:147], v[200:203], v[28:31]
	v_mfma_f32_16x16x32_bf16 v[16:19], v[136:139], v[208:211], v[16:19]
	v_mfma_f32_16x16x32_bf16 v[12:15], v[144:147], v[208:211], v[12:15]
	s_barrier
	s_add_u32 s56, s56, 0x10080
	s_addc_u32 s57, s57, 0
	s_add_i32 s28, s29, s61
	v_lshl_add_u64 v[6:7], s[56:57], 0, v[172:173]
	s_mov_b32 m0, s28
	s_nop 0
	global_load_lds_dwordx4 v[6:7], off
	v_lshl_add_u64 v[6:7], s[56:57], 0, v[168:169]
	s_add_i32 m0, s28, 0x2000
	s_nop 0
	global_load_lds_dwordx4 v[6:7], off
	s_waitcnt vmcnt(6)
	s_barrier
	v_mfma_f32_16x16x32_bf16 v[56:59], v[212:215], v[148:151], v[56:59]
	v_mfma_f32_16x16x32_bf16 v[52:55], v[220:223], v[148:151], v[52:55]
	v_mfma_f32_16x16x32_bf16 v[40:43], v[212:215], v[156:159], v[40:43]
	v_mfma_f32_16x16x32_bf16 v[36:39], v[220:223], v[156:159], v[36:39]
	v_mfma_f32_16x16x32_bf16 v[24:27], v[212:215], v[164:167], v[24:27]
	v_mfma_f32_16x16x32_bf16 v[20:23], v[220:223], v[164:167], v[20:23]
	v_mfma_f32_16x16x32_bf16 v[6:9], v[212:215], v[204:207], v[8:11]
	v_mfma_f32_16x16x32_bf16 v[2:5], v[220:223], v[204:207], v[2:5]
	v_mfma_f32_16x16x32_bf16 v[56:59], v[216:219], v[152:155], v[56:59]
	v_mfma_f32_16x16x32_bf16 v[52:55], v[224:227], v[152:155], v[52:55]
	v_mfma_f32_16x16x32_bf16 v[40:43], v[216:219], v[160:163], v[40:43]
	v_mfma_f32_16x16x32_bf16 v[36:39], v[224:227], v[160:163], v[36:39]
	v_mfma_f32_16x16x32_bf16 v[24:27], v[216:219], v[200:203], v[24:27]
	v_mfma_f32_16x16x32_bf16 v[20:23], v[224:227], v[200:203], v[20:23]
	v_mfma_f32_16x16x32_bf16 v[8:11], v[216:219], v[208:211], v[6:9]
	v_mfma_f32_16x16x32_bf16 v[4:7], v[224:227], v[208:211], v[2:5]
	s_add_i32 s17, s17, 2
	s_add_u32 s54, s54, 0x100
	s_addc_u32 s55, s55, 0
	s_cmp_gt_u32 s17, 13
	s_barrier
	s_cbranch_scc1 .LBB0_659

.LBB0_740:
	ds_read_b128 v[64:67], v221
	ds_read_b128 v[68:71], v221 offset:1024
	ds_read_b128 v[84:87], v221 offset:2048
	ds_read_b128 v[92:95], v221 offset:3072
	s_add_u32 s28, s10, 0xfffc0080
	s_addc_u32 s29, s11, -1
	s_cmp_eq_u32 s92, 12
	s_cselect_b32 s65, s9, s29
	s_cselect_b32 s64, s13, s28
	s_cselect_b32 s63, s17, s57
	s_cselect_b32 s62, s44, s55
	v_lshl_add_u64 v[176:177], s[10:11], 0, v[204:205]
	s_add_i32 m0, s78, 0xc000
	ds_read_b128 v[144:147], v222
	ds_read_b128 v[148:151], v222 offset:1024
	ds_read_b128 v[152:155], v222 offset:2048
	ds_read_b128 v[156:159], v222 offset:3072
	ds_read_b128 v[160:163], v222 offset:4096
	ds_read_b128 v[164:167], v222 offset:5120
	ds_read_b128 v[168:171], v222 offset:6144
	ds_read_b128 v[172:175], v222 offset:7168
	global_load_lds_dwordx4 v[176:177], off
	v_lshl_add_u64 v[176:177], s[10:11], 0, v[206:207]
	s_add_i32 m0, s78, 0xe000
	s_nop 0
	global_load_lds_dwordx4 v[176:177], off
	s_waitcnt lgkmcnt(8)
	s_barrier
	s_waitcnt lgkmcnt(0)
	s_waitcnt lgkmcnt(0)
	v_mfma_f32_16x16x32_bf16 v[140:143], v[64:67], v[144:147], v[140:143]
	v_mfma_f32_16x16x32_bf16 v[136:139], v[84:87], v[144:147], v[136:139]
	v_mfma_f32_16x16x32_bf16 v[124:127], v[64:67], v[152:155], v[124:127]
	v_mfma_f32_16x16x32_bf16 v[120:123], v[84:87], v[152:155], v[120:123]
	v_mfma_f32_16x16x32_bf16 v[108:111], v[64:67], v[160:163], v[108:111]
	v_mfma_f32_16x16x32_bf16 v[104:107], v[84:87], v[160:163], v[104:107]
	v_mfma_f32_16x16x32_bf16 v[88:91], v[64:67], v[168:171], v[88:91]
	v_mfma_f32_16x16x32_bf16 v[80:83], v[84:87], v[168:171], v[80:83]
	v_mfma_f32_16x16x32_bf16 v[140:143], v[68:71], v[148:151], v[140:143]
	v_mfma_f32_16x16x32_bf16 v[136:139], v[92:95], v[148:151], v[136:139]
	v_mfma_f32_16x16x32_bf16 v[124:127], v[68:71], v[156:159], v[124:127]
	v_mfma_f32_16x16x32_bf16 v[120:123], v[92:95], v[156:159], v[120:123]
	v_mfma_f32_16x16x32_bf16 v[108:111], v[68:71], v[164:167], v[108:111]
	v_mfma_f32_16x16x32_bf16 v[104:107], v[92:95], v[164:167], v[104:107]
	v_mfma_f32_16x16x32_bf16 v[88:91], v[68:71], v[172:175], v[88:91]
	v_mfma_f32_16x16x32_bf16 v[80:83], v[92:95], v[172:175], v[80:83]
	s_barrier
	s_add_i32 s28, s89, s67
	v_lshl_add_u64 v[212:213], s[62:63], 0, v[198:199]
	s_mov_b32 m0, s28
	ds_read_b128 v[176:179], v223
	ds_read_b128 v[180:183], v223 offset:1024
	ds_read_b128 v[184:187], v223 offset:2048
	ds_read_b128 v[188:191], v223 offset:3072
	global_load_lds_dwordx4 v[212:213], off
	v_lshl_add_u64 v[214:215], s[62:63], 0, v[202:203]
	s_add_i32 m0, s28, 0x2000
	s_nop 0
	global_load_lds_dwordx4 v[214:215], off
	s_barrier
	s_waitcnt lgkmcnt(0)
	s_waitcnt lgkmcnt(0)
	v_mfma_f32_16x16x32_bf16 v[132:135], v[176:179], v[144:147], v[132:135]
	v_mfma_f32_16x16x32_bf16 v[128:131], v[184:187], v[144:147], v[128:131]
	v_mfma_f32_16x16x32_bf16 v[116:119], v[176:179], v[152:155], v[116:119]
	v_mfma_f32_16x16x32_bf16 v[112:115], v[184:187], v[152:155], v[112:115]
	v_mfma_f32_16x16x32_bf16 v[100:103], v[176:179], v[160:163], v[100:103]
	v_mfma_f32_16x16x32_bf16 v[96:99], v[184:187], v[160:163], v[96:99]
	v_mfma_f32_16x16x32_bf16 v[76:79], v[176:179], v[168:171], v[76:79]
	v_mfma_f32_16x16x32_bf16 v[72:75], v[184:187], v[168:171], v[72:75]
	v_mfma_f32_16x16x32_bf16 v[132:135], v[180:183], v[148:151], v[132:135]
	v_mfma_f32_16x16x32_bf16 v[128:131], v[188:191], v[148:151], v[128:131]
	v_mfma_f32_16x16x32_bf16 v[116:119], v[180:183], v[156:159], v[116:119]
	v_mfma_f32_16x16x32_bf16 v[112:115], v[188:191], v[156:159], v[112:115]
	v_mfma_f32_16x16x32_bf16 v[100:103], v[180:183], v[164:167], v[100:103]
	v_mfma_f32_16x16x32_bf16 v[96:99], v[188:191], v[164:167], v[96:99]
	v_mfma_f32_16x16x32_bf16 v[76:79], v[180:183], v[172:175], v[76:79]
	v_mfma_f32_16x16x32_bf16 v[72:75], v[188:191], v[172:175], v[72:75]
	s_mov_b32 m0, s78
	v_lshl_add_u64 v[216:217], s[64:65], 0, v[196:197]
	s_barrier
	ds_read_b128 v[144:147], v222 offset:16384
	ds_read_b128 v[148:151], v222 offset:17408
	ds_read_b128 v[152:155], v222 offset:18432
	ds_read_b128 v[156:159], v222 offset:19456
	ds_read_b128 v[160:163], v222 offset:20480
	ds_read_b128 v[164:167], v222 offset:21504
	ds_read_b128 v[168:171], v222 offset:22528
	ds_read_b128 v[172:175], v222 offset:23552
	global_load_lds_dwordx4 v[216:217], off
	v_lshl_add_u64 v[226:227], s[64:65], 0, v[200:201]
	s_mov_b32 m0, s79
	s_nop 0
	global_load_lds_dwordx4 v[226:227], off
	s_barrier
	s_waitcnt lgkmcnt(0)
	s_waitcnt lgkmcnt(0)
	v_mfma_f32_16x16x32_bf16 v[60:63], v[64:67], v[144:147], v[60:63]
	v_mfma_f32_16x16x32_bf16 v[56:59], v[84:87], v[144:147], v[56:59]
	v_mfma_f32_16x16x32_bf16 v[44:47], v[64:67], v[152:155], v[44:47]
	v_mfma_f32_16x16x32_bf16 v[40:43], v[84:87], v[152:155], v[40:43]
	v_mfma_f32_16x16x32_bf16 v[28:31], v[64:67], v[160:163], v[28:31]
	v_mfma_f32_16x16x32_bf16 v[24:27], v[84:87], v[160:163], v[24:27]
	v_mfma_f32_16x16x32_bf16 v[12:15], v[64:67], v[168:171], v[12:15]
	v_mfma_f32_16x16x32_bf16 v[8:11], v[84:87], v[168:171], v[8:11]
	v_mfma_f32_16x16x32_bf16 v[60:63], v[68:71], v[148:151], v[60:63]
	v_mfma_f32_16x16x32_bf16 v[56:59], v[92:95], v[148:151], v[56:59]
	v_mfma_f32_16x16x32_bf16 v[44:47], v[68:71], v[156:159], v[44:47]
	v_mfma_f32_16x16x32_bf16 v[40:43], v[92:95], v[156:159], v[40:43]
	v_mfma_f32_16x16x32_bf16 v[28:31], v[68:71], v[164:167], v[28:31]
	v_mfma_f32_16x16x32_bf16 v[24:27], v[92:95], v[164:167], v[24:27]
	v_mfma_f32_16x16x32_bf16 v[12:15], v[68:71], v[172:175], v[12:15]
	v_mfma_f32_16x16x32_bf16 v[8:11], v[92:95], v[172:175], v[8:11]
	s_barrier
	s_add_u32 s94, s62, 0x10000
	s_addc_u32 s95, s63, 0
	s_add_i32 s28, s90, s67
	v_lshl_add_u64 v[64:65], s[94:95], 0, v[198:199]
	s_mov_b32 m0, s28
	s_nop 0
	global_load_lds_dwordx4 v[64:65], off
	v_lshl_add_u64 v[64:65], s[94:95], 0, v[202:203]
	s_add_i32 m0, s28, 0x2000
	s_nop 0
	global_load_lds_dwordx4 v[64:65], off
	s_waitcnt vmcnt(6)
	s_barrier
	v_mfma_f32_16x16x32_bf16 v[52:55], v[176:179], v[144:147], v[52:55]
	v_mfma_f32_16x16x32_bf16 v[48:51], v[184:187], v[144:147], v[48:51]
	v_mfma_f32_16x16x32_bf16 v[36:39], v[176:179], v[152:155], v[36:39]
	v_mfma_f32_16x16x32_bf16 v[32:35], v[184:187], v[152:155], v[32:35]
	v_mfma_f32_16x16x32_bf16 v[20:23], v[176:179], v[160:163], v[20:23]
	v_mfma_f32_16x16x32_bf16 v[16:19], v[184:187], v[160:163], v[16:19]
	v_mfma_f32_16x16x32_bf16 v[4:7], v[176:179], v[168:171], v[4:7]
	v_mfma_f32_16x16x32_bf16 v[0:3], v[184:187], v[168:171], v[0:3]
	v_mfma_f32_16x16x32_bf16 v[52:55], v[180:183], v[148:151], v[52:55]
	v_mfma_f32_16x16x32_bf16 v[48:51], v[188:191], v[148:151], v[48:51]
	v_mfma_f32_16x16x32_bf16 v[36:39], v[180:183], v[156:159], v[36:39]
	v_mfma_f32_16x16x32_bf16 v[32:35], v[188:191], v[156:159], v[32:35]
	v_mfma_f32_16x16x32_bf16 v[20:23], v[180:183], v[164:167], v[20:23]
	v_mfma_f32_16x16x32_bf16 v[16:19], v[188:191], v[164:167], v[16:19]
	v_mfma_f32_16x16x32_bf16 v[4:7], v[180:183], v[172:175], v[4:7]
	v_mfma_f32_16x16x32_bf16 v[0:3], v[188:191], v[172:175], v[0:3]
	s_add_i32 s28, 0, 0x18000
	v_add_u32_e32 v92, s28, v218
	s_barrier
	ds_read_b128 v[64:67], v92
	ds_read_b128 v[68:71], v92 offset:1024
	ds_read_b128 v[84:87], v92 offset:2048
	ds_read_b128 v[92:95], v92 offset:3072
	s_add_u32 s64, s64, 0x40000
	s_addc_u32 s65, s65, 0
	s_mov_b32 m0, s80
	v_lshl_add_u64 v[176:177], s[64:65], 0, v[196:197]
	ds_read_b128 v[144:147], v222 offset:32768
	ds_read_b128 v[148:151], v222 offset:33792
	ds_read_b128 v[152:155], v222 offset:34816
	ds_read_b128 v[156:159], v222 offset:35840
	ds_read_b128 v[160:163], v222 offset:36864
	ds_read_b128 v[164:167], v222 offset:37888
	ds_read_b128 v[168:171], v222 offset:38912
	ds_read_b128 v[172:175], v222 offset:39936
	global_load_lds_dwordx4 v[176:177], off
	v_lshl_add_u64 v[176:177], s[64:65], 0, v[200:201]
	s_mov_b32 m0, s81
	s_nop 0
	global_load_lds_dwordx4 v[176:177], off
	s_waitcnt lgkmcnt(8)
	s_barrier
	s_waitcnt lgkmcnt(0)
	s_waitcnt lgkmcnt(0)
	v_mfma_f32_16x16x32_bf16 v[140:143], v[64:67], v[144:147], v[140:143]
	v_mfma_f32_16x16x32_bf16 v[136:139], v[84:87], v[144:147], v[136:139]
	v_mfma_f32_16x16x32_bf16 v[124:127], v[64:67], v[152:155], v[124:127]
	v_mfma_f32_16x16x32_bf16 v[120:123], v[84:87], v[152:155], v[120:123]
	v_mfma_f32_16x16x32_bf16 v[108:111], v[64:67], v[160:163], v[108:111]
	v_mfma_f32_16x16x32_bf16 v[104:107], v[84:87], v[160:163], v[104:107]
	v_mfma_f32_16x16x32_bf16 v[88:91], v[64:67], v[168:171], v[88:91]
	v_mfma_f32_16x16x32_bf16 v[80:83], v[84:87], v[168:171], v[80:83]
	v_mfma_f32_16x16x32_bf16 v[140:143], v[68:71], v[148:151], v[140:143]
	v_mfma_f32_16x16x32_bf16 v[136:139], v[92:95], v[148:151], v[136:139]
	v_mfma_f32_16x16x32_bf16 v[124:127], v[68:71], v[156:159], v[124:127]
	v_mfma_f32_16x16x32_bf16 v[120:123], v[92:95], v[156:159], v[120:123]
	v_mfma_f32_16x16x32_bf16 v[108:111], v[68:71], v[164:167], v[108:111]
	v_mfma_f32_16x16x32_bf16 v[104:107], v[92:95], v[164:167], v[104:107]
	v_mfma_f32_16x16x32_bf16 v[88:91], v[68:71], v[172:175], v[88:91]
	v_mfma_f32_16x16x32_bf16 v[80:83], v[92:95], v[172:175], v[80:83]
	s_barrier
	s_add_i32 s29, 0, 0x1c000
	s_add_i32 s28, s28, s67
	v_add_u32_e32 v188, s29, v218
	v_lshl_add_u64 v[212:213], v[212:213], 0, s[52:53]
	s_mov_b32 m0, s28
	ds_read_b128 v[176:179], v188
	ds_read_b128 v[180:183], v188 offset:1024
	ds_read_b128 v[184:187], v188 offset:2048
	ds_read_b128 v[188:191], v188 offset:3072
	global_load_lds_dwordx4 v[212:213], off
	v_lshl_add_u64 v[212:213], v[214:215], 0, s[52:53]
	s_add_i32 m0, s28, 0x2000
	s_nop 0
	global_load_lds_dwordx4 v[212:213], off
	s_barrier
	s_waitcnt lgkmcnt(0)
	s_waitcnt lgkmcnt(0)
	v_mfma_f32_16x16x32_bf16 v[132:135], v[176:179], v[144:147], v[132:135]
	v_mfma_f32_16x16x32_bf16 v[128:131], v[184:187], v[144:147], v[128:131]
	v_mfma_f32_16x16x32_bf16 v[116:119], v[176:179], v[152:155], v[116:119]
	v_mfma_f32_16x16x32_bf16 v[112:115], v[184:187], v[152:155], v[112:115]
	v_mfma_f32_16x16x32_bf16 v[100:103], v[176:179], v[160:163], v[100:103]
	v_mfma_f32_16x16x32_bf16 v[96:99], v[184:187], v[160:163], v[96:99]
	v_mfma_f32_16x16x32_bf16 v[76:79], v[176:179], v[168:171], v[76:79]
	v_mfma_f32_16x16x32_bf16 v[72:75], v[184:187], v[168:171], v[72:75]
	v_mfma_f32_16x16x32_bf16 v[132:135], v[180:183], v[148:151], v[132:135]
	v_mfma_f32_16x16x32_bf16 v[128:131], v[188:191], v[148:151], v[128:131]
	v_mfma_f32_16x16x32_bf16 v[116:119], v[180:183], v[156:159], v[116:119]
	v_mfma_f32_16x16x32_bf16 v[112:115], v[188:191], v[156:159], v[112:115]
	v_mfma_f32_16x16x32_bf16 v[100:103], v[180:183], v[164:167], v[100:103]
	v_mfma_f32_16x16x32_bf16 v[96:99], v[188:191], v[164:167], v[96:99]
	v_mfma_f32_16x16x32_bf16 v[76:79], v[180:183], v[172:175], v[76:79]
	v_mfma_f32_16x16x32_bf16 v[72:75], v[188:191], v[172:175], v[72:75]
	s_mov_b32 m0, s85
	v_lshl_add_u64 v[212:213], v[216:217], 0, s[52:53]
	s_barrier
	ds_read_b128 v[144:147], v222 offset:49152
	ds_read_b128 v[148:151], v222 offset:50176
	ds_read_b128 v[152:155], v222 offset:51200
	ds_read_b128 v[156:159], v222 offset:52224
	ds_read_b128 v[160:163], v222 offset:53248
	ds_read_b128 v[164:167], v222 offset:54272
	ds_read_b128 v[168:171], v222 offset:55296
	ds_read_b128 v[172:175], v222 offset:56320
	global_load_lds_dwordx4 v[212:213], off
	v_lshl_add_u64 v[212:213], v[226:227], 0, s[52:53]
	s_mov_b32 m0, s87
	s_nop 0
	global_load_lds_dwordx4 v[212:213], off
	s_barrier
	s_waitcnt lgkmcnt(0)
	s_waitcnt lgkmcnt(0)
	v_mfma_f32_16x16x32_bf16 v[60:63], v[64:67], v[144:147], v[60:63]
	v_mfma_f32_16x16x32_bf16 v[56:59], v[84:87], v[144:147], v[56:59]
	v_mfma_f32_16x16x32_bf16 v[44:47], v[64:67], v[152:155], v[44:47]
	v_mfma_f32_16x16x32_bf16 v[40:43], v[84:87], v[152:155], v[40:43]
	v_mfma_f32_16x16x32_bf16 v[28:31], v[64:67], v[160:163], v[28:31]
	v_mfma_f32_16x16x32_bf16 v[24:27], v[84:87], v[160:163], v[24:27]
	v_mfma_f32_16x16x32_bf16 v[12:15], v[64:67], v[168:171], v[12:15]
	v_mfma_f32_16x16x32_bf16 v[8:11], v[84:87], v[168:171], v[8:11]
	v_mfma_f32_16x16x32_bf16 v[60:63], v[68:71], v[148:151], v[60:63]
	v_mfma_f32_16x16x32_bf16 v[56:59], v[92:95], v[148:151], v[56:59]
	v_mfma_f32_16x16x32_bf16 v[44:47], v[68:71], v[156:159], v[44:47]
	v_mfma_f32_16x16x32_bf16 v[40:43], v[92:95], v[156:159], v[40:43]
	v_mfma_f32_16x16x32_bf16 v[28:31], v[68:71], v[164:167], v[28:31]
	v_mfma_f32_16x16x32_bf16 v[24:27], v[92:95], v[164:167], v[24:27]
	v_mfma_f32_16x16x32_bf16 v[12:15], v[68:71], v[172:175], v[12:15]
	v_mfma_f32_16x16x32_bf16 v[8:11], v[92:95], v[172:175], v[8:11]
	s_barrier
	s_add_u32 s62, s62, 0x10080
	s_addc_u32 s63, s63, 0
	s_add_i32 s28, s29, s67
	v_lshl_add_u64 v[64:65], s[62:63], 0, v[198:199]
	s_mov_b32 m0, s28
	s_nop 0
	global_load_lds_dwordx4 v[64:65], off
	v_lshl_add_u64 v[64:65], s[62:63], 0, v[202:203]
	s_add_i32 m0, s28, 0x2000
	s_nop 0
	global_load_lds_dwordx4 v[64:65], off
	s_waitcnt vmcnt(6)
	s_barrier
	v_mfma_f32_16x16x32_bf16 v[52:55], v[176:179], v[144:147], v[52:55]
	v_mfma_f32_16x16x32_bf16 v[48:51], v[184:187], v[144:147], v[48:51]
	v_mfma_f32_16x16x32_bf16 v[36:39], v[176:179], v[152:155], v[36:39]
	v_mfma_f32_16x16x32_bf16 v[32:35], v[184:187], v[152:155], v[32:35]
	v_mfma_f32_16x16x32_bf16 v[20:23], v[176:179], v[160:163], v[20:23]
	v_mfma_f32_16x16x32_bf16 v[16:19], v[184:187], v[160:163], v[16:19]
	v_mfma_f32_16x16x32_bf16 v[4:7], v[176:179], v[168:171], v[4:7]
	v_mfma_f32_16x16x32_bf16 v[0:3], v[184:187], v[168:171], v[0:3]
	v_mfma_f32_16x16x32_bf16 v[52:55], v[180:183], v[148:151], v[52:55]
	v_mfma_f32_16x16x32_bf16 v[48:51], v[188:191], v[148:151], v[48:51]
	v_mfma_f32_16x16x32_bf16 v[36:39], v[180:183], v[156:159], v[36:39]
	v_mfma_f32_16x16x32_bf16 v[32:35], v[188:191], v[156:159], v[32:35]
	v_mfma_f32_16x16x32_bf16 v[20:23], v[180:183], v[164:167], v[20:23]
	v_mfma_f32_16x16x32_bf16 v[16:19], v[188:191], v[164:167], v[16:19]
	v_mfma_f32_16x16x32_bf16 v[4:7], v[180:183], v[172:175], v[4:7]
	v_mfma_f32_16x16x32_bf16 v[0:3], v[188:191], v[172:175], v[0:3]
	s_add_i32 s92, s92, 2
	s_add_u32 s10, s10, 0x100
	s_addc_u32 s11, s11, 0
	s_add_u32 s55, s55, 0x100
	s_addc_u32 s57, s57, 0
	s_cmp_gt_u32 s92, 13
	s_barrier
	s_cbranch_scc0 .LBB0_740
	v_lshl_add_u32 v212, s8, 8, v195
	v_lshl_or_b32 v214, s12, 8, v219
	v_ashrrev_i32_e32 v213, 31, v212
	v_ashrrev_i32_e32 v215, 31, v214
	s_mov_b64 s[8:9], -1
	s_and_b64 vcc, exec, s[48:49]
	s_cbranch_vccz .LBB0_743
	v_lshlrev_b64 v[64:65], 12, v[212:213]
	v_lshl_add_u64 v[64:65], s[36:37], 0, v[64:65]
	v_lshl_add_u64 v[64:65], v[214:215], 2, v[64:65]
	global_load_dwordx4 v[160:163], v[64:65], off offset:16
	global_load_dwordx4 v[164:167], v[64:65], off
	global_load_dwordx4 v[168:171], v[64:65], off offset:144
	global_load_dwordx4 v[172:175], v[64:65], off offset:128
	s_mov_b64 s[8:9], 0

.LBB0_904:
	ds_read_b128 v[146:149], v169
	ds_read_b128 v[150:153], v169 offset:1024
	ds_read_b128 v[154:157], v169 offset:2048
	ds_read_b128 v[174:177], v169 offset:3072
	s_add_u32 s28, s0, 0xfffc0080
	s_addc_u32 s29, s1, -1
	s_cmp_eq_u32 s78, 12
	s_cselect_b32 s53, s7, s29
	s_cselect_b32 s52, s45, s28
	s_cselect_b32 s51, s37, s77
	s_cselect_b32 s50, s67, s76
	v_lshl_add_u64 v[158:159], s[0:1], 0, v[138:139]
	s_add_i32 m0, s54, 0xc000
	ds_read_b128 v[178:181], v171
	ds_read_b128 v[182:185], v171 offset:1024
	ds_read_b128 v[186:189], v171 offset:2048
	ds_read_b128 v[196:199], v171 offset:3072
	ds_read_b128 v[200:203], v171 offset:4096
	ds_read_b128 v[204:207], v171 offset:5120
	ds_read_b128 v[208:211], v171 offset:6144
	ds_read_b128 v[212:215], v171 offset:7168
	global_load_lds_dwordx4 v[158:159], off
	v_lshl_add_u64 v[158:159], s[0:1], 0, v[140:141]
	s_add_i32 m0, s54, 0xe000
	s_nop 0
	global_load_lds_dwordx4 v[158:159], off
	s_waitcnt lgkmcnt(8)
	s_barrier
	s_waitcnt lgkmcnt(0)
	s_waitcnt lgkmcnt(0)
	v_mfma_f32_16x16x32_bf16 v[124:127], v[146:149], v[178:181], v[124:127]
	v_mfma_f32_16x16x32_bf16 v[120:123], v[154:157], v[178:181], v[120:123]
	v_mfma_f32_16x16x32_bf16 v[108:111], v[146:149], v[186:189], v[108:111]
	v_mfma_f32_16x16x32_bf16 v[104:107], v[154:157], v[186:189], v[104:107]
	v_mfma_f32_16x16x32_bf16 v[92:95], v[146:149], v[200:203], v[92:95]
	v_mfma_f32_16x16x32_bf16 v[88:91], v[154:157], v[200:203], v[88:91]
	v_mfma_f32_16x16x32_bf16 v[76:79], v[146:149], v[208:211], v[76:79]
	v_mfma_f32_16x16x32_bf16 v[72:75], v[154:157], v[208:211], v[72:75]
	v_mfma_f32_16x16x32_bf16 v[124:127], v[150:153], v[182:185], v[124:127]
	v_mfma_f32_16x16x32_bf16 v[120:123], v[174:177], v[182:185], v[120:123]
	v_mfma_f32_16x16x32_bf16 v[108:111], v[150:153], v[196:199], v[108:111]
	v_mfma_f32_16x16x32_bf16 v[104:107], v[174:177], v[196:199], v[104:107]
	v_mfma_f32_16x16x32_bf16 v[92:95], v[150:153], v[204:207], v[92:95]
	v_mfma_f32_16x16x32_bf16 v[88:91], v[174:177], v[204:207], v[88:91]
	v_mfma_f32_16x16x32_bf16 v[76:79], v[150:153], v[212:215], v[76:79]
	v_mfma_f32_16x16x32_bf16 v[72:75], v[174:177], v[212:215], v[72:75]
	s_barrier
	s_add_i32 s28, s63, s13
	v_lshl_add_u64 v[158:159], s[50:51], 0, v[132:133]
	s_mov_b32 m0, s28
	ds_read_b128 v[216:219], v172
	ds_read_b128 v[220:223], v172 offset:1024
	ds_read_b128 v[224:227], v172 offset:2048
	ds_read_b128 v[228:231], v172 offset:3072
	global_load_lds_dwordx4 v[158:159], off
	v_lshl_add_u64 v[164:165], s[50:51], 0, v[128:129]
	s_add_i32 m0, s28, 0x2000
	s_nop 0
	global_load_lds_dwordx4 v[164:165], off
	s_barrier
	s_waitcnt lgkmcnt(0)
	s_waitcnt lgkmcnt(0)
	v_mfma_f32_16x16x32_bf16 v[116:119], v[216:219], v[178:181], v[116:119]
	v_mfma_f32_16x16x32_bf16 v[112:115], v[224:227], v[178:181], v[112:115]
	v_mfma_f32_16x16x32_bf16 v[100:103], v[216:219], v[186:189], v[100:103]
	v_mfma_f32_16x16x32_bf16 v[96:99], v[224:227], v[186:189], v[96:99]
	v_mfma_f32_16x16x32_bf16 v[84:87], v[216:219], v[200:203], v[84:87]
	v_mfma_f32_16x16x32_bf16 v[80:83], v[224:227], v[200:203], v[80:83]
	v_mfma_f32_16x16x32_bf16 v[68:71], v[216:219], v[208:211], v[68:71]
	v_mfma_f32_16x16x32_bf16 v[64:67], v[224:227], v[208:211], v[64:67]
	v_mfma_f32_16x16x32_bf16 v[116:119], v[220:223], v[182:185], v[116:119]
	v_mfma_f32_16x16x32_bf16 v[112:115], v[228:231], v[182:185], v[112:115]
	v_mfma_f32_16x16x32_bf16 v[100:103], v[220:223], v[196:199], v[100:103]
	v_mfma_f32_16x16x32_bf16 v[96:99], v[228:231], v[196:199], v[96:99]
	v_mfma_f32_16x16x32_bf16 v[84:87], v[220:223], v[204:207], v[84:87]
	v_mfma_f32_16x16x32_bf16 v[80:83], v[228:231], v[204:207], v[80:83]
	v_mfma_f32_16x16x32_bf16 v[68:71], v[220:223], v[212:215], v[68:71]
	v_mfma_f32_16x16x32_bf16 v[64:67], v[228:231], v[212:215], v[64:67]
	s_mov_b32 m0, s54
	v_lshl_add_u64 v[190:191], s[52:53], 0, v[134:135]
	s_barrier
	ds_read_b128 v[178:181], v171 offset:16384
	ds_read_b128 v[182:185], v171 offset:17408
	ds_read_b128 v[186:189], v171 offset:18432
	ds_read_b128 v[196:199], v171 offset:19456
	ds_read_b128 v[200:203], v171 offset:20480
	ds_read_b128 v[204:207], v171 offset:21504
	ds_read_b128 v[208:211], v171 offset:22528
	ds_read_b128 v[212:215], v171 offset:23552
	global_load_lds_dwordx4 v[190:191], off
	v_lshl_add_u64 v[232:233], s[52:53], 0, v[130:131]
	s_mov_b32 m0, s55
	s_nop 0
	global_load_lds_dwordx4 v[232:233], off
	s_barrier
	s_waitcnt lgkmcnt(0)
	s_waitcnt lgkmcnt(0)
	v_mfma_f32_16x16x32_bf16 v[60:63], v[146:149], v[178:181], v[60:63]
	v_mfma_f32_16x16x32_bf16 v[56:59], v[154:157], v[178:181], v[56:59]
	v_mfma_f32_16x16x32_bf16 v[44:47], v[146:149], v[186:189], v[44:47]
	v_mfma_f32_16x16x32_bf16 v[40:43], v[154:157], v[186:189], v[40:43]
	v_mfma_f32_16x16x32_bf16 v[28:31], v[146:149], v[200:203], v[28:31]
	v_mfma_f32_16x16x32_bf16 v[24:27], v[154:157], v[200:203], v[24:27]
	v_mfma_f32_16x16x32_bf16 v[12:15], v[146:149], v[208:211], v[12:15]
	v_mfma_f32_16x16x32_bf16 v[8:11], v[154:157], v[208:211], v[8:11]
	v_mfma_f32_16x16x32_bf16 v[60:63], v[150:153], v[182:185], v[60:63]
	v_mfma_f32_16x16x32_bf16 v[56:59], v[174:177], v[182:185], v[56:59]
	v_mfma_f32_16x16x32_bf16 v[44:47], v[150:153], v[196:199], v[44:47]
	v_mfma_f32_16x16x32_bf16 v[40:43], v[174:177], v[196:199], v[40:43]
	v_mfma_f32_16x16x32_bf16 v[28:31], v[150:153], v[204:207], v[28:31]
	v_mfma_f32_16x16x32_bf16 v[24:27], v[174:177], v[204:207], v[24:27]
	v_mfma_f32_16x16x32_bf16 v[12:15], v[150:153], v[212:215], v[12:15]
	v_mfma_f32_16x16x32_bf16 v[8:11], v[174:177], v[212:215], v[8:11]
	s_barrier
	s_add_u32 s80, s50, 0x10000
	s_addc_u32 s81, s51, 0
	s_add_i32 s28, s64, s13
	v_lshl_add_u64 v[146:147], s[80:81], 0, v[132:133]
	s_mov_b32 m0, s28
	s_nop 0
	global_load_lds_dwordx4 v[146:147], off
	v_lshl_add_u64 v[146:147], s[80:81], 0, v[128:129]
	s_add_i32 m0, s28, 0x2000
	s_nop 0
	global_load_lds_dwordx4 v[146:147], off
	s_waitcnt vmcnt(6)
	s_barrier
	v_mfma_f32_16x16x32_bf16 v[52:55], v[216:219], v[178:181], v[52:55]
	v_mfma_f32_16x16x32_bf16 v[48:51], v[224:227], v[178:181], v[48:51]
	v_mfma_f32_16x16x32_bf16 v[36:39], v[216:219], v[186:189], v[36:39]
	v_mfma_f32_16x16x32_bf16 v[32:35], v[224:227], v[186:189], v[32:35]
	v_mfma_f32_16x16x32_bf16 v[20:23], v[216:219], v[200:203], v[20:23]
	v_mfma_f32_16x16x32_bf16 v[16:19], v[224:227], v[200:203], v[16:19]
	v_mfma_f32_16x16x32_bf16 v[4:7], v[216:219], v[208:211], v[4:7]
	v_mfma_f32_16x16x32_bf16 v[0:3], v[224:227], v[208:211], v[0:3]
	v_mfma_f32_16x16x32_bf16 v[52:55], v[220:223], v[182:185], v[52:55]
	v_mfma_f32_16x16x32_bf16 v[48:51], v[228:231], v[182:185], v[48:51]
	v_mfma_f32_16x16x32_bf16 v[36:39], v[220:223], v[196:199], v[36:39]
	v_mfma_f32_16x16x32_bf16 v[32:35], v[228:231], v[196:199], v[32:35]
	v_mfma_f32_16x16x32_bf16 v[20:23], v[220:223], v[204:207], v[20:23]
	v_mfma_f32_16x16x32_bf16 v[16:19], v[228:231], v[204:207], v[16:19]
	v_mfma_f32_16x16x32_bf16 v[4:7], v[220:223], v[212:215], v[4:7]
	v_mfma_f32_16x16x32_bf16 v[0:3], v[228:231], v[212:215], v[0:3]
	s_add_i32 s28, 0, 0x18000
	v_add_u32_e32 v160, s28, v163
	s_barrier
	ds_read_b128 v[146:149], v160
	ds_read_b128 v[150:153], v160 offset:1024
	ds_read_b128 v[154:157], v160 offset:2048
	ds_read_b128 v[174:177], v160 offset:3072
	s_add_u32 s52, s52, 0x40000
	s_addc_u32 s53, s53, 0
	s_mov_b32 m0, s56
	v_lshl_add_u64 v[216:217], s[52:53], 0, v[134:135]
	ds_read_b128 v[178:181], v171 offset:32768
	ds_read_b128 v[182:185], v171 offset:33792
	ds_read_b128 v[186:189], v171 offset:34816
	ds_read_b128 v[196:199], v171 offset:35840
	ds_read_b128 v[200:203], v171 offset:36864
	ds_read_b128 v[204:207], v171 offset:37888
	ds_read_b128 v[208:211], v171 offset:38912
	ds_read_b128 v[212:215], v171 offset:39936
	global_load_lds_dwordx4 v[216:217], off
	v_lshl_add_u64 v[216:217], s[52:53], 0, v[130:131]
	s_mov_b32 m0, s57
	s_nop 0
	global_load_lds_dwordx4 v[216:217], off
	s_waitcnt lgkmcnt(8)
	s_barrier
	s_waitcnt lgkmcnt(0)
	s_waitcnt lgkmcnt(0)
	v_mfma_f32_16x16x32_bf16 v[124:127], v[146:149], v[178:181], v[124:127]
	v_mfma_f32_16x16x32_bf16 v[120:123], v[154:157], v[178:181], v[120:123]
	v_mfma_f32_16x16x32_bf16 v[108:111], v[146:149], v[186:189], v[108:111]
	v_mfma_f32_16x16x32_bf16 v[104:107], v[154:157], v[186:189], v[104:107]
	v_mfma_f32_16x16x32_bf16 v[92:95], v[146:149], v[200:203], v[92:95]
	v_mfma_f32_16x16x32_bf16 v[88:91], v[154:157], v[200:203], v[88:91]
	v_mfma_f32_16x16x32_bf16 v[76:79], v[146:149], v[208:211], v[76:79]
	v_mfma_f32_16x16x32_bf16 v[72:75], v[154:157], v[208:211], v[72:75]
	v_mfma_f32_16x16x32_bf16 v[124:127], v[150:153], v[182:185], v[124:127]
	v_mfma_f32_16x16x32_bf16 v[120:123], v[174:177], v[182:185], v[120:123]
	v_mfma_f32_16x16x32_bf16 v[108:111], v[150:153], v[196:199], v[108:111]
	v_mfma_f32_16x16x32_bf16 v[104:107], v[174:177], v[196:199], v[104:107]
	v_mfma_f32_16x16x32_bf16 v[92:95], v[150:153], v[204:207], v[92:95]
	v_mfma_f32_16x16x32_bf16 v[88:91], v[174:177], v[204:207], v[88:91]
	v_mfma_f32_16x16x32_bf16 v[76:79], v[150:153], v[212:215], v[76:79]
	v_mfma_f32_16x16x32_bf16 v[72:75], v[174:177], v[212:215], v[72:75]
	s_barrier
	s_add_i32 s29, 0, 0x1c000
	s_add_i32 s28, s28, s13
	v_add_u32_e32 v160, s29, v163
	v_lshl_add_u64 v[158:159], v[158:159], 0, s[8:9]
	s_mov_b32 m0, s28
	ds_read_b128 v[216:219], v160
	ds_read_b128 v[220:223], v160 offset:1024
	ds_read_b128 v[224:227], v160 offset:2048
	ds_read_b128 v[228:231], v160 offset:3072
	global_load_lds_dwordx4 v[158:159], off
	v_lshl_add_u64 v[158:159], v[164:165], 0, s[8:9]
	s_add_i32 m0, s28, 0x2000
	s_nop 0
	global_load_lds_dwordx4 v[158:159], off
	s_barrier
	s_waitcnt lgkmcnt(0)
	s_waitcnt lgkmcnt(0)
	v_mfma_f32_16x16x32_bf16 v[116:119], v[216:219], v[178:181], v[116:119]
	v_mfma_f32_16x16x32_bf16 v[112:115], v[224:227], v[178:181], v[112:115]
	v_mfma_f32_16x16x32_bf16 v[100:103], v[216:219], v[186:189], v[100:103]
	v_mfma_f32_16x16x32_bf16 v[96:99], v[224:227], v[186:189], v[96:99]
	v_mfma_f32_16x16x32_bf16 v[84:87], v[216:219], v[200:203], v[84:87]
	v_mfma_f32_16x16x32_bf16 v[80:83], v[224:227], v[200:203], v[80:83]
	v_mfma_f32_16x16x32_bf16 v[68:71], v[216:219], v[208:211], v[68:71]
	v_mfma_f32_16x16x32_bf16 v[64:67], v[224:227], v[208:211], v[64:67]
	v_mfma_f32_16x16x32_bf16 v[116:119], v[220:223], v[182:185], v[116:119]
	v_mfma_f32_16x16x32_bf16 v[112:115], v[228:231], v[182:185], v[112:115]
	v_mfma_f32_16x16x32_bf16 v[100:103], v[220:223], v[196:199], v[100:103]
	v_mfma_f32_16x16x32_bf16 v[96:99], v[228:231], v[196:199], v[96:99]
	v_mfma_f32_16x16x32_bf16 v[84:87], v[220:223], v[204:207], v[84:87]
	v_mfma_f32_16x16x32_bf16 v[80:83], v[228:231], v[204:207], v[80:83]
	v_mfma_f32_16x16x32_bf16 v[68:71], v[220:223], v[212:215], v[68:71]
	v_mfma_f32_16x16x32_bf16 v[64:67], v[228:231], v[212:215], v[64:67]
	s_mov_b32 m0, s60
	v_lshl_add_u64 v[158:159], v[190:191], 0, s[8:9]
	s_barrier
	ds_read_b128 v[178:181], v171 offset:49152
	ds_read_b128 v[182:185], v171 offset:50176
	ds_read_b128 v[186:189], v171 offset:51200
	ds_read_b128 v[196:199], v171 offset:52224
	ds_read_b128 v[200:203], v171 offset:53248
	ds_read_b128 v[204:207], v171 offset:54272
	ds_read_b128 v[208:211], v171 offset:55296
	ds_read_b128 v[212:215], v171 offset:56320
	global_load_lds_dwordx4 v[158:159], off
	v_lshl_add_u64 v[158:159], v[232:233], 0, s[8:9]
	s_mov_b32 m0, s61
	s_nop 0
	global_load_lds_dwordx4 v[158:159], off
	s_barrier
	s_waitcnt lgkmcnt(0)
	s_waitcnt lgkmcnt(0)
	v_mfma_f32_16x16x32_bf16 v[60:63], v[146:149], v[178:181], v[60:63]
	v_mfma_f32_16x16x32_bf16 v[56:59], v[154:157], v[178:181], v[56:59]
	v_mfma_f32_16x16x32_bf16 v[44:47], v[146:149], v[186:189], v[44:47]
	v_mfma_f32_16x16x32_bf16 v[40:43], v[154:157], v[186:189], v[40:43]
	v_mfma_f32_16x16x32_bf16 v[28:31], v[146:149], v[200:203], v[28:31]
	v_mfma_f32_16x16x32_bf16 v[24:27], v[154:157], v[200:203], v[24:27]
	v_mfma_f32_16x16x32_bf16 v[12:15], v[146:149], v[208:211], v[12:15]
	v_mfma_f32_16x16x32_bf16 v[8:11], v[154:157], v[208:211], v[8:11]
	v_mfma_f32_16x16x32_bf16 v[60:63], v[150:153], v[182:185], v[60:63]
	v_mfma_f32_16x16x32_bf16 v[56:59], v[174:177], v[182:185], v[56:59]
	v_mfma_f32_16x16x32_bf16 v[44:47], v[150:153], v[196:199], v[44:47]
	v_mfma_f32_16x16x32_bf16 v[40:43], v[174:177], v[196:199], v[40:43]
	v_mfma_f32_16x16x32_bf16 v[28:31], v[150:153], v[204:207], v[28:31]
	v_mfma_f32_16x16x32_bf16 v[24:27], v[174:177], v[204:207], v[24:27]
	v_mfma_f32_16x16x32_bf16 v[12:15], v[150:153], v[212:215], v[12:15]
	v_mfma_f32_16x16x32_bf16 v[8:11], v[174:177], v[212:215], v[8:11]
	s_barrier
	s_add_u32 s50, s50, 0x10080
	s_addc_u32 s51, s51, 0
	s_add_i32 s28, s29, s13
	v_lshl_add_u64 v[146:147], s[50:51], 0, v[132:133]
	s_mov_b32 m0, s28
	s_nop 0
	global_load_lds_dwordx4 v[146:147], off
	v_lshl_add_u64 v[146:147], s[50:51], 0, v[128:129]
	s_add_i32 m0, s28, 0x2000
	s_nop 0
	global_load_lds_dwordx4 v[146:147], off
	s_waitcnt vmcnt(6)
	s_barrier
	v_mfma_f32_16x16x32_bf16 v[52:55], v[216:219], v[178:181], v[52:55]
	v_mfma_f32_16x16x32_bf16 v[48:51], v[224:227], v[178:181], v[48:51]
	v_mfma_f32_16x16x32_bf16 v[36:39], v[216:219], v[186:189], v[36:39]
	v_mfma_f32_16x16x32_bf16 v[32:35], v[224:227], v[186:189], v[32:35]
	v_mfma_f32_16x16x32_bf16 v[20:23], v[216:219], v[200:203], v[20:23]
	v_mfma_f32_16x16x32_bf16 v[16:19], v[224:227], v[200:203], v[16:19]
	v_mfma_f32_16x16x32_bf16 v[4:7], v[216:219], v[208:211], v[4:7]
	v_mfma_f32_16x16x32_bf16 v[0:3], v[224:227], v[208:211], v[0:3]
	v_mfma_f32_16x16x32_bf16 v[52:55], v[220:223], v[182:185], v[52:55]
	v_mfma_f32_16x16x32_bf16 v[48:51], v[228:231], v[182:185], v[48:51]
	v_mfma_f32_16x16x32_bf16 v[36:39], v[220:223], v[196:199], v[36:39]
	v_mfma_f32_16x16x32_bf16 v[32:35], v[228:231], v[196:199], v[32:35]
	v_mfma_f32_16x16x32_bf16 v[20:23], v[220:223], v[204:207], v[20:23]
	v_mfma_f32_16x16x32_bf16 v[16:19], v[228:231], v[204:207], v[16:19]
	v_mfma_f32_16x16x32_bf16 v[4:7], v[220:223], v[212:215], v[4:7]
	v_mfma_f32_16x16x32_bf16 v[0:3], v[228:231], v[212:215], v[0:3]
	s_add_i32 s78, s78, 2
	s_add_u32 s0, s0, 0x100
	s_addc_u32 s1, s1, 0
	s_add_u32 s76, s76, 0x100
	s_addc_u32 s77, s77, 0
	s_cmp_gt_u32 s78, 13
	s_barrier
	s_cbranch_scc0 .LBB0_904
	v_lshl_add_u32 v146, s6, 8, v161
	v_or_b32_e32 v164, 16, v146
	v_ashrrev_i32_e32 v165, 31, v164
	v_lshlrev_b64 v[148:149], 6, v[164:165]
	v_or_b32_e32 v158, 32, v146
	v_lshl_add_u64 v[148:149], v[136:137], 0, v[148:149]
	v_ashrrev_i32_e32 v159, 31, v158
	v_or_b32_e32 v156, 48, v146
	global_load_dwordx4 v[174:177], v[148:149], off
	v_lshlrev_b64 v[148:149], 6, v[158:159]
	v_ashrrev_i32_e32 v157, 31, v156
	v_add_u32_e32 v154, 0x80, v146
	v_lshl_add_u64 v[148:149], v[136:137], 0, v[148:149]
	v_lshlrev_b64 v[150:151], 6, v[156:157]
	v_ashrrev_i32_e32 v155, 31, v154
	v_lshl_add_u64 v[150:151], v[136:137], 0, v[150:151]
	global_load_dwordx4 v[178:181], v[148:149], off
	global_load_dwordx4 v[182:185], v[150:151], off
	v_lshlrev_b64 v[148:149], 6, v[154:155]
	v_lshl_add_u64 v[148:149], v[136:137], 0, v[148:149]
	global_load_dwordx4 v[186:189], v[148:149], off
	v_ashrrev_i32_e32 v147, 31, v146
	v_lshlrev_b64 v[148:149], 6, v[146:147]
	v_add_u32_e32 v152, 0x90, v146
	v_lshl_add_u64 v[148:149], v[136:137], 0, v[148:149]
	v_ashrrev_i32_e32 v153, 31, v152
	global_load_dwordx4 v[196:199], v[148:149], off
	v_lshlrev_b64 v[148:149], 6, v[152:153]
	v_lshl_add_u64 v[148:149], v[136:137], 0, v[148:149]
	global_load_dwordx4 v[200:203], v[148:149], off
	v_add_u32_e32 v148, 0xa0, v146
	v_ashrrev_i32_e32 v149, 31, v148
	v_lshlrev_b64 v[150:151], 6, v[148:149]
	v_lshl_add_u64 v[150:151], v[136:137], 0, v[150:151]
	global_load_dwordx4 v[204:207], v[150:151], off
	v_add_u32_e32 v150, 0xb0, v146
	v_ashrrev_i32_e32 v151, 31, v150
	v_lshlrev_b64 v[208:209], 6, v[150:151]
	v_lshl_add_u64 v[208:209], v[136:137], 0, v[208:209]
	global_load_dwordx4 v[208:211], v[208:209], off
	v_and_b32_e32 v149, 64, v173
	v_xor_b32_e32 v147, 16, v173
	v_add_u32_e32 v149, 64, v149
	v_cmp_lt_i32_e32 vcc, v147, v149
	v_xor_b32_e32 v153, 32, v173
	v_mov_b64_e32 v[190:191], s[12:13]
	v_cndmask_b32_e32 v147, v173, v147, vcc
	v_lshlrev_b32_e32 v147, 2, v147
	v_cmp_lt_i32_e32 vcc, v153, v149
	s_waitcnt vmcnt(0)
	v_mov_b32_e32 v212, v175
	v_mov_b32_e32 v213, v176
	v_mov_b32_e32 v175, v177
	v_pk_add_f32 v[174:175], v[212:213], v[174:175]
	v_cndmask_b32_e32 v149, v173, v153, vcc
	v_lshlrev_b32_e32 v149, 2, v149
	v_mov_b32_e32 v176, v179
	v_mov_b32_e32 v177, v180
	v_mov_b32_e32 v179, v181
	v_mov_b32_e32 v180, v183
	v_mov_b32_e32 v181, v184
	v_mov_b32_e32 v183, v185
	v_mov_b32_e32 v184, v187
	v_mov_b32_e32 v185, v188
	v_mov_b32_e32 v187, v189
	v_pk_add_f32 v[176:177], v[176:177], v[178:179]
	v_pk_add_f32 v[178:179], v[180:181], v[182:183]
	v_pk_add_f32 v[180:181], v[184:185], v[186:187]
	v_mov_b32_e32 v182, v176
	v_mov_b32_e32 v183, v174
	v_mov_b32_e32 v174, v177
	v_mov_b32_e32 v176, v180
	v_mov_b32_e32 v177, v178
	v_mov_b32_e32 v178, v181
	v_pk_add_f32 v[174:175], v[182:183], v[174:175]
	v_pk_add_f32 v[176:177], v[176:177], v[178:179]
	ds_bpermute_b32 v179, v147, v175
	ds_bpermute_b32 v178, v147, v174
	ds_bpermute_b32 v181, v147, v177
	ds_bpermute_b32 v180, v147, v176
	v_mov_b32_e32 v184, v201
	v_mov_b32_e32 v185, v202
	s_waitcnt lgkmcnt(0)
	v_pk_add_f32 v[174:175], v[174:175], v[178:179]
	ds_bpermute_b32 v179, v149, v175
	v_pk_add_f32 v[176:177], v[176:177], v[180:181]
	ds_bpermute_b32 v178, v149, v174
	ds_bpermute_b32 v181, v149, v177
	ds_bpermute_b32 v180, v149, v176
	v_mov_b32_e32 v201, v203
	v_mov_b32_e32 v182, v197
	s_waitcnt lgkmcnt(2)
	v_pk_add_f32 v[174:175], v[174:175], v[178:179]
	v_pk_add_f32 v[178:179], v[184:185], v[200:201]
	s_waitcnt lgkmcnt(0)
	v_pk_add_f32 v[176:177], v[176:177], v[180:181]
	v_pk_fma_f32 v[174:175], v[174:175], s[10:11], v[190:191] op_sel_hi:[1,0,0]
	v_mov_b32_e32 v180, v205
	v_mov_b32_e32 v181, v206
	v_mov_b32_e32 v205, v207
	v_mul_f32_e32 v151, 0x4b800000, v175
	v_cmp_gt_f32_e32 vcc, s65, v175
	v_pk_add_f32 v[180:181], v[180:181], v[204:205]
	v_mov_b32_e32 v185, v178
	v_cndmask_b32_e32 v151, v175, v151, vcc
	v_mov_b32_e32 v184, v180
	v_mov_b32_e32 v178, v181
	v_rsq_f32_e32 v151, v151
	v_pk_add_f32 v[178:179], v[184:185], v[178:179]
	ds_bpermute_b32 v181, v147, v179
	ds_bpermute_b32 v180, v147, v178
	v_pk_fma_f32 v[176:177], v[176:177], s[10:11], v[190:191] op_sel_hi:[1,0,0]
	v_mul_f32_e32 v153, 0x4b800000, v174
	v_cmp_gt_f32_e64 s[0:1], s65, v174
	v_mul_f32_e32 v157, 0x45800000, v151
	v_mul_f32_e32 v155, 0x4b800000, v177
	v_cndmask_b32_e64 v153, v174, v153, s[0:1]
	v_cmp_gt_f32_e64 s[6:7], s65, v177
	v_cndmask_b32_e32 v174, v151, v157, vcc
	v_mul_f32_e32 v151, 0x4b800000, v176
	v_cmp_gt_f32_e32 vcc, s65, v176
	v_cndmask_b32_e64 v155, v177, v155, s[6:7]
	v_rsq_f32_e32 v153, v153
	v_cndmask_b32_e32 v151, v176, v151, vcc
	s_waitcnt lgkmcnt(0)
	v_pk_add_f32 v[176:177], v[178:179], v[180:181]
	ds_bpermute_b32 v179, v149, v177
	ds_bpermute_b32 v178, v149, v176
	v_rsq_f32_e32 v155, v155
	v_mul_f32_e32 v159, 0x45800000, v153
	v_cndmask_b32_e64 v180, v153, v159, s[0:1]
	v_rsq_f32_e32 v151, v151
	s_waitcnt lgkmcnt(0)
	v_pk_add_f32 v[176:177], v[176:177], v[178:179]
	v_mul_f32_e32 v153, 0x45800000, v155
	v_pk_fma_f32 v[176:177], v[176:177], s[10:11], v[190:191] op_sel_hi:[1,0,0]
	v_cndmask_b32_e64 v170, v155, v153, s[6:7]
	v_mul_f32_e32 v155, 0x4b800000, v177
	v_cmp_gt_f32_e64 s[0:1], s65, v177
	v_mul_f32_e32 v157, 0x4b800000, v176
	v_cmp_gt_f32_e64 s[6:7], s65, v176
	v_cndmask_b32_e64 v155, v177, v155, s[0:1]
	v_rsq_f32_e32 v155, v155
	v_cndmask_b32_e64 v157, v176, v157, s[6:7]
	v_rsq_f32_e32 v157, v157
	v_mul_f32_e32 v153, 0x45800000, v151
	v_cndmask_b32_e32 v168, v151, v153, vcc
	v_mul_f32_e32 v151, 0x45800000, v155
	v_mov_b32_e32 v183, v198
	v_mov_b32_e32 v197, v199
	v_cndmask_b32_e64 v166, v155, v151, s[0:1]
	v_mul_f32_e32 v151, 0x45800000, v157
	v_mov_b32_e32 v176, v209
	v_mov_b32_e32 v177, v210
	v_mov_b32_e32 v209, v211
	v_pk_add_f32 v[182:183], v[182:183], v[196:197]
	v_cndmask_b32_e64 v162, v157, v151, s[6:7]
	v_pk_add_f32 v[176:177], v[176:177], v[208:209]
	v_mov_b32_e32 v178, v182
	v_mov_b32_e32 v179, v176
	v_mov_b32_e32 v176, v183
	v_pk_add_f32 v[176:177], v[178:179], v[176:177]
	ds_bpermute_b32 v178, v147, v176
	ds_bpermute_b32 v179, v147, v177
	v_lshl_or_b32 v182, s66, 8, v167
	v_pk_mul_f32 v[100:101], v[100:101], v[174:175] op_sel_hi:[1,0]
	v_pk_mul_f32 v[108:109], v[108:109], v[174:175] op_sel_hi:[1,0]
	v_ashrrev_i32_e32 v183, 31, v182
	s_waitcnt lgkmcnt(0)
	v_pk_add_f32 v[176:177], v[176:177], v[178:179]
	ds_bpermute_b32 v178, v149, v176
	ds_bpermute_b32 v179, v149, v177
	v_pk_mul_f32 v[96:97], v[96:97], v[174:175] op_sel_hi:[1,0]
	v_pk_mul_f32 v[102:103], v[102:103], v[174:175] op_sel_hi:[1,0]
	v_pk_mul_f32 v[110:111], v[110:111], v[174:175] op_sel_hi:[1,0]
	v_cvt_pk_bf16_f32 v108, v108, v109
	s_waitcnt lgkmcnt(0)
	v_pk_add_f32 v[176:177], v[176:177], v[178:179]
	v_pk_mul_f32 v[106:107], v[106:107], v[174:175] op_sel_hi:[1,0]
	v_pk_fma_f32 v[176:177], v[176:177], s[10:11], v[190:191] op_sel_hi:[1,0,0]
	v_pk_mul_f32 v[104:105], v[104:105], v[174:175] op_sel_hi:[1,0]
	v_mul_f32_e32 v147, 0x4b800000, v177
	v_cmp_gt_f32_e32 vcc, s65, v177
	v_mul_f32_e32 v149, 0x4b800000, v176
	v_cmp_gt_f32_e64 s[0:1], s65, v176
	v_cndmask_b32_e32 v147, v177, v147, vcc
	v_rsq_f32_e32 v147, v147
	v_cndmask_b32_e64 v149, v176, v149, s[0:1]
	v_rsq_f32_e32 v149, v149
	v_cvt_pk_bf16_f32 v100, v100, v101
	v_mul_f32_e32 v151, 0x45800000, v147
	v_cndmask_b32_e32 v160, v147, v151, vcc
	v_mul_f32_e32 v147, 0x45800000, v149
	v_cndmask_b32_e64 v176, v149, v147, s[0:1]
	v_pk_mul_f32 v[112:113], v[112:113], v[176:177] op_sel_hi:[1,0]
	v_pk_mul_f32 v[116:117], v[116:117], v[176:177] op_sel_hi:[1,0]
	v_pk_mul_f32 v[124:125], v[124:125], v[176:177] op_sel_hi:[1,0]
	v_pk_mul_f32 v[122:123], v[122:123], v[176:177] op_sel_hi:[1,0]
	v_pk_mul_f32 v[120:121], v[120:121], v[176:177] op_sel_hi:[1,0]
	v_pk_mul_f32 v[114:115], v[114:115], v[176:177] op_sel_hi:[1,0]
	v_pk_mul_f32 v[118:119], v[118:119], v[176:177] op_sel_hi:[1,0]
	v_pk_mul_f32 v[126:127], v[126:127], v[176:177] op_sel_hi:[1,0]
	v_cvt_pk_bf16_f32 v124, v124, v125
	v_cvt_pk_bf16_f32 v120, v120, v121
	v_cvt_pk_bf16_f32 v121, v122, v123
	v_cvt_pk_bf16_f32 v122, v116, v117
	v_cvt_pk_bf16_f32 v112, v112, v113
	v_cvt_pk_bf16_f32 v125, v126, v127
	v_cvt_pk_bf16_f32 v118, v118, v119
	v_cvt_pk_bf16_f32 v113, v114, v115
	v_cndmask_b32_e64 v114, v124, v122, s[2:3]
	v_mov_b32_e32 v123, 0
	v_cndmask_b32_e64 v115, v120, v112, s[2:3]
	v_mov_b32_e32 v126, 0
	v_mov_b32_dpp v123, v114 row_ror:8 row_mask:0xf bank_mask:0xf
	v_cndmask_b32_e64 v114, v125, v118, s[2:3]
	v_mov_b32_e32 v119, 0
	v_mov_b32_dpp v126, v115 row_ror:8 row_mask:0xf bank_mask:0xf
	v_mov_b32_e32 v127, 0
	v_mov_b32_dpp v119, v114 row_ror:8 row_mask:0xf bank_mask:0xf
	v_cndmask_b32_e64 v114, v121, v113, s[2:3]
	v_cndmask_b32_e64 v116, v126, v120, s[2:3]
	v_cndmask_b32_e64 v120, v112, v126, s[2:3]
	v_add_u32_e32 v112, -8, v146
	v_mov_b32_dpp v127, v114 row_ror:8 row_mask:0xf bank_mask:0xf
	v_cndmask_b32_e64 v112, v112, v146, s[2:3]
	v_cndmask_b32_e64 v117, v127, v121, s[2:3]
	v_cndmask_b32_e64 v121, v113, v127, s[2:3]
	v_ashrrev_i32_e32 v113, 31, v112
	v_lshlrev_b64 v[112:113], 10, v[112:113]
	v_cndmask_b32_e64 v115, v119, v125, s[2:3]
	v_cndmask_b32_e64 v114, v123, v124, s[2:3]
	v_cndmask_b32_e64 v119, v118, v119, s[2:3]
	v_cndmask_b32_e64 v118, v122, v123, s[2:3]
	v_lshl_add_u64 v[122:123], s[38:39], 0, v[112:113]
	v_lshlrev_b64 v[112:113], 1, v[182:183]
	v_pk_mul_f32 v[98:99], v[98:99], v[174:175] op_sel_hi:[1,0]
	v_cvt_pk_bf16_f32 v109, v110, v111
	v_cvt_pk_bf16_f32 v104, v104, v105
	v_cvt_pk_bf16_f32 v105, v106, v107
	v_cvt_pk_bf16_f32 v101, v102, v103
	v_cvt_pk_bf16_f32 v102, v96, v97
	v_cndmask_b32_e64 v96, v108, v100, s[2:3]
	v_mov_b32_e32 v106, 0
	v_lshl_add_u64 v[122:123], v[122:123], 0, v[112:113]
	v_cvt_pk_bf16_f32 v103, v98, v99
	v_mov_b32_dpp v106, v96 row_ror:8 row_mask:0xf bank_mask:0xf
	v_cndmask_b32_e64 v96, v109, v101, s[2:3]
	v_mov_b32_e32 v107, 0
	v_cndmask_b32_e64 v97, v104, v102, s[2:3]
	v_mov_b32_e32 v110, 0
	global_store_dwordx4 v[122:123], v[114:117], off
	v_mov_b32_dpp v107, v96 row_ror:8 row_mask:0xf bank_mask:0xf
	v_cndmask_b32_e64 v96, v105, v103, s[2:3]
	v_add_u32_e32 v116, 8, v146
	v_mov_b32_dpp v110, v97 row_ror:8 row_mask:0xf bank_mask:0xf
	v_mov_b32_e32 v111, 0
	v_cndmask_b32_e64 v114, v146, v116, s[2:3]
	v_cndmask_b32_e64 v98, v110, v104, s[2:3]
	v_mov_b32_dpp v111, v96 row_ror:8 row_mask:0xf bank_mask:0xf
	v_cndmask_b32_e64 v104, v116, v164, s[2:3]
	v_ashrrev_i32_e32 v115, 31, v114
	v_cndmask_b32_e64 v99, v111, v105, s[2:3]
	v_ashrrev_i32_e32 v105, 31, v104
	v_pk_mul_f32 v[84:85], v[84:85], v[180:181] op_sel_hi:[1,0]
	v_pk_mul_f32 v[92:93], v[92:93], v[180:181] op_sel_hi:[1,0]
	v_lshlrev_b64 v[114:115], 10, v[114:115]
	v_lshlrev_b64 v[104:105], 10, v[104:105]
	v_pk_mul_f32 v[80:81], v[80:81], v[180:181] op_sel_hi:[1,0]
	v_pk_mul_f32 v[86:87], v[86:87], v[180:181] op_sel_hi:[1,0]
	v_pk_mul_f32 v[94:95], v[94:95], v[180:181] op_sel_hi:[1,0]
	v_cvt_pk_bf16_f32 v92, v92, v93
	v_pk_mul_f32 v[90:91], v[90:91], v[180:181] op_sel_hi:[1,0]
	v_pk_mul_f32 v[88:89], v[88:89], v[180:181] op_sel_hi:[1,0]
	v_cvt_pk_bf16_f32 v84, v84, v85
	v_lshl_add_u64 v[114:115], s[38:39], 0, v[114:115]
	v_lshl_add_u64 v[104:105], s[38:39], 0, v[104:105]
	v_pk_mul_f32 v[82:83], v[82:83], v[180:181] op_sel_hi:[1,0]
	v_cvt_pk_bf16_f32 v93, v94, v95
	v_cvt_pk_bf16_f32 v88, v88, v89
	v_cvt_pk_bf16_f32 v89, v90, v91
	v_cvt_pk_bf16_f32 v85, v86, v87
	v_cvt_pk_bf16_f32 v86, v80, v81
	v_cndmask_b32_e64 v80, v92, v84, s[2:3]
	v_mov_b32_e32 v90, 0
	v_lshl_add_u64 v[114:115], v[114:115], 0, v[112:113]
	v_cndmask_b32_e64 v97, v107, v109, s[2:3]
	v_cndmask_b32_e64 v96, v106, v108, s[2:3]
	v_lshl_add_u64 v[104:105], v[104:105], 0, v[112:113]
	v_cvt_pk_bf16_f32 v87, v82, v83
	v_mov_b32_dpp v90, v80 row_ror:8 row_mask:0xf bank_mask:0xf
	v_cndmask_b32_e64 v80, v93, v85, s[2:3]
	v_mov_b32_e32 v91, 0
	v_cndmask_b32_e64 v81, v88, v86, s[2:3]
	v_mov_b32_e32 v94, 0
	global_store_dwordx4 v[114:115], v[118:121], off
	global_store_dwordx4 v[104:105], v[96:99], off
	v_mov_b32_dpp v91, v80 row_ror:8 row_mask:0xf bank_mask:0xf
	v_cndmask_b32_e64 v80, v89, v87, s[2:3]
	v_add_u32_e32 v98, 24, v146
	v_mov_b32_dpp v94, v81 row_ror:8 row_mask:0xf bank_mask:0xf
	v_mov_b32_e32 v95, 0
	v_cndmask_b32_e64 v96, v164, v98, s[2:3]
	v_cndmask_b32_e64 v82, v94, v88, s[2:3]
	v_mov_b32_dpp v95, v80 row_ror:8 row_mask:0xf bank_mask:0xf
	v_cndmask_b32_e64 v88, v98, v158, s[2:3]
	v_ashrrev_i32_e32 v97, 31, v96
	v_cndmask_b32_e64 v83, v95, v89, s[2:3]
	v_ashrrev_i32_e32 v89, 31, v88
	v_pk_mul_f32 v[68:69], v[68:69], v[170:171] op_sel_hi:[1,0]
	v_pk_mul_f32 v[76:77], v[76:77], v[170:171] op_sel_hi:[1,0]
	v_lshlrev_b64 v[96:97], 10, v[96:97]
	v_lshlrev_b64 v[88:89], 10, v[88:89]
	v_pk_mul_f32 v[64:65], v[64:65], v[170:171] op_sel_hi:[1,0]
	v_pk_mul_f32 v[70:71], v[70:71], v[170:171] op_sel_hi:[1,0]
	v_pk_mul_f32 v[78:79], v[78:79], v[170:171] op_sel_hi:[1,0]
	v_cvt_pk_bf16_f32 v76, v76, v77
	v_pk_mul_f32 v[74:75], v[74:75], v[170:171] op_sel_hi:[1,0]
	v_pk_mul_f32 v[72:73], v[72:73], v[170:171] op_sel_hi:[1,0]
	v_cvt_pk_bf16_f32 v68, v68, v69
	v_lshl_add_u64 v[96:97], s[38:39], 0, v[96:97]
	v_lshl_add_u64 v[88:89], s[38:39], 0, v[88:89]
	v_pk_mul_f32 v[66:67], v[66:67], v[170:171] op_sel_hi:[1,0]
	v_cvt_pk_bf16_f32 v77, v78, v79
	v_cvt_pk_bf16_f32 v72, v72, v73
	v_cvt_pk_bf16_f32 v73, v74, v75
	v_cvt_pk_bf16_f32 v69, v70, v71
	v_cvt_pk_bf16_f32 v70, v64, v65
	v_cndmask_b32_e64 v64, v76, v68, s[2:3]
	v_mov_b32_e32 v74, 0
	v_cndmask_b32_e64 v103, v103, v111, s[2:3]
	v_cndmask_b32_e64 v102, v102, v110, s[2:3]
	v_cndmask_b32_e64 v101, v101, v107, s[2:3]
	v_cndmask_b32_e64 v100, v100, v106, s[2:3]
	v_lshl_add_u64 v[96:97], v[96:97], 0, v[112:113]
	v_cndmask_b32_e64 v81, v91, v93, s[2:3]
	v_cndmask_b32_e64 v80, v90, v92, s[2:3]
	v_lshl_add_u64 v[88:89], v[88:89], 0, v[112:113]
	v_cvt_pk_bf16_f32 v71, v66, v67
	v_mov_b32_dpp v74, v64 row_ror:8 row_mask:0xf bank_mask:0xf
	v_cndmask_b32_e64 v64, v77, v69, s[2:3]
	v_mov_b32_e32 v75, 0
	v_cndmask_b32_e64 v65, v72, v70, s[2:3]
	v_mov_b32_e32 v78, 0
	global_store_dwordx4 v[96:97], v[100:103], off
	global_store_dwordx4 v[88:89], v[80:83], off
	v_mov_b32_dpp v75, v64 row_ror:8 row_mask:0xf bank_mask:0xf
	v_cndmask_b32_e64 v64, v73, v71, s[2:3]
	v_add_u32_e32 v82, 40, v146
	v_mov_b32_dpp v78, v65 row_ror:8 row_mask:0xf bank_mask:0xf
	v_mov_b32_e32 v79, 0
	v_cndmask_b32_e64 v80, v158, v82, s[2:3]
	v_cndmask_b32_e64 v66, v78, v72, s[2:3]
	v_mov_b32_dpp v79, v64 row_ror:8 row_mask:0xf bank_mask:0xf
	v_cndmask_b32_e64 v72, v82, v156, s[2:3]
	v_ashrrev_i32_e32 v81, 31, v80
	v_cndmask_b32_e64 v67, v79, v73, s[2:3]
	v_ashrrev_i32_e32 v73, 31, v72
	v_pk_mul_f32 v[48:49], v[48:49], v[168:169] op_sel_hi:[1,0]
	v_pk_mul_f32 v[54:55], v[54:55], v[168:169] op_sel_hi:[1,0]
	v_pk_mul_f32 v[52:53], v[52:53], v[168:169] op_sel_hi:[1,0]
	v_pk_mul_f32 v[60:61], v[60:61], v[168:169] op_sel_hi:[1,0]
	v_pk_mul_f32 v[56:57], v[56:57], v[168:169] op_sel_hi:[1,0]
	v_lshlrev_b64 v[80:81], 10, v[80:81]
	v_lshlrev_b64 v[72:73], 10, v[72:73]
	v_pk_mul_f32 v[62:63], v[62:63], v[168:169] op_sel_hi:[1,0]
	v_cvt_pk_bf16_f32 v60, v60, v61
	v_pk_mul_f32 v[58:59], v[58:59], v[168:169] op_sel_hi:[1,0]
	v_cvt_pk_bf16_f32 v56, v56, v57
	v_cvt_pk_bf16_f32 v52, v52, v53
	v_cvt_pk_bf16_f32 v53, v54, v55
	v_cvt_pk_bf16_f32 v54, v48, v49
	v_lshl_add_u64 v[80:81], s[38:39], 0, v[80:81]
	v_lshl_add_u64 v[72:73], s[38:39], 0, v[72:73]
	v_pk_mul_f32 v[50:51], v[50:51], v[168:169] op_sel_hi:[1,0]
	v_cvt_pk_bf16_f32 v61, v62, v63
	v_cvt_pk_bf16_f32 v57, v58, v59
	v_cndmask_b32_e64 v48, v60, v52, s[2:3]
	v_mov_b32_e32 v58, 0
	v_cndmask_b32_e64 v49, v56, v54, s[2:3]
	v_mov_b32_e32 v62, 0
	v_cndmask_b32_e64 v87, v87, v95, s[2:3]
	v_cndmask_b32_e64 v86, v86, v94, s[2:3]
	v_cndmask_b32_e64 v85, v85, v91, s[2:3]
	v_cndmask_b32_e64 v84, v84, v90, s[2:3]
	v_lshl_add_u64 v[80:81], v[80:81], 0, v[112:113]
	v_cndmask_b32_e64 v65, v75, v77, s[2:3]
	v_cndmask_b32_e64 v64, v74, v76, s[2:3]
	v_lshl_add_u64 v[72:73], v[72:73], 0, v[112:113]
	v_cvt_pk_bf16_f32 v55, v50, v51
	v_mov_b32_dpp v58, v48 row_ror:8 row_mask:0xf bank_mask:0xf
	v_cndmask_b32_e64 v48, v61, v53, s[2:3]
	v_mov_b32_e32 v59, 0
	v_mov_b32_dpp v62, v49 row_ror:8 row_mask:0xf bank_mask:0xf
	global_store_dwordx4 v[80:81], v[84:87], off
	global_store_dwordx4 v[72:73], v[64:67], off
	v_mov_b32_dpp v59, v48 row_ror:8 row_mask:0xf bank_mask:0xf
	v_cndmask_b32_e64 v48, v57, v55, s[2:3]
	v_add_u32_e32 v64, 56, v146
	v_mov_b32_e32 v63, 0
	v_cndmask_b32_e64 v50, v62, v56, s[2:3]
	v_add_u32_e32 v56, 0x78, v146
	v_cndmask_b32_e64 v64, v156, v64, s[2:3]
	v_mov_b32_dpp v63, v48 row_ror:8 row_mask:0xf bank_mask:0xf
	v_cndmask_b32_e64 v56, v56, v154, s[2:3]
	v_ashrrev_i32_e32 v65, 31, v64
	v_cndmask_b32_e64 v51, v63, v57, s[2:3]
	v_ashrrev_i32_e32 v57, 31, v56
	v_pk_mul_f32 v[36:37], v[36:37], v[166:167] op_sel_hi:[1,0]
	v_pk_mul_f32 v[44:45], v[44:45], v[166:167] op_sel_hi:[1,0]
	v_lshlrev_b64 v[64:65], 10, v[64:65]
	v_lshlrev_b64 v[56:57], 10, v[56:57]
	v_pk_mul_f32 v[32:33], v[32:33], v[166:167] op_sel_hi:[1,0]
	v_pk_mul_f32 v[38:39], v[38:39], v[166:167] op_sel_hi:[1,0]
	v_pk_mul_f32 v[46:47], v[46:47], v[166:167] op_sel_hi:[1,0]
	v_cvt_pk_bf16_f32 v44, v44, v45
	v_pk_mul_f32 v[42:43], v[42:43], v[166:167] op_sel_hi:[1,0]
	v_pk_mul_f32 v[40:41], v[40:41], v[166:167] op_sel_hi:[1,0]
	v_cvt_pk_bf16_f32 v36, v36, v37
	v_lshl_add_u64 v[64:65], s[38:39], 0, v[64:65]
	v_lshl_add_u64 v[56:57], s[38:39], 0, v[56:57]
	v_pk_mul_f32 v[34:35], v[34:35], v[166:167] op_sel_hi:[1,0]
	v_cvt_pk_bf16_f32 v45, v46, v47
	v_cvt_pk_bf16_f32 v40, v40, v41
	v_cvt_pk_bf16_f32 v41, v42, v43
	v_cvt_pk_bf16_f32 v37, v38, v39
	v_cvt_pk_bf16_f32 v38, v32, v33
	v_cndmask_b32_e64 v32, v44, v36, s[2:3]
	v_mov_b32_e32 v42, 0
	v_cndmask_b32_e64 v71, v71, v79, s[2:3]
	v_cndmask_b32_e64 v70, v70, v78, s[2:3]
	v_cndmask_b32_e64 v69, v69, v75, s[2:3]
	v_cndmask_b32_e64 v68, v68, v74, s[2:3]
	v_lshl_add_u64 v[64:65], v[64:65], 0, v[112:113]
	v_cndmask_b32_e64 v49, v59, v61, s[2:3]
	v_cndmask_b32_e64 v48, v58, v60, s[2:3]
	v_lshl_add_u64 v[56:57], v[56:57], 0, v[112:113]
	v_cvt_pk_bf16_f32 v39, v34, v35
	v_mov_b32_dpp v42, v32 row_ror:8 row_mask:0xf bank_mask:0xf
	v_cndmask_b32_e64 v32, v45, v37, s[2:3]
	v_mov_b32_e32 v43, 0
	v_cndmask_b32_e64 v33, v40, v38, s[2:3]
	v_mov_b32_e32 v46, 0
	global_store_dwordx4 v[64:65], v[68:71], off
	global_store_dwordx4 v[56:57], v[48:51], off
	v_mov_b32_dpp v43, v32 row_ror:8 row_mask:0xf bank_mask:0xf
	v_cndmask_b32_e64 v32, v41, v39, s[2:3]
	v_add_u32_e32 v50, 0x88, v146
	v_mov_b32_dpp v46, v33 row_ror:8 row_mask:0xf bank_mask:0xf
	v_mov_b32_e32 v47, 0
	v_cndmask_b32_e64 v34, v46, v40, s[2:3]
	v_cndmask_b32_e64 v40, v50, v152, s[2:3]
	v_mov_b32_dpp v47, v32 row_ror:8 row_mask:0xf bank_mask:0xf
	v_cndmask_b32_e64 v35, v47, v41, s[2:3]
	v_ashrrev_i32_e32 v41, 31, v40
	v_pk_mul_f32 v[20:21], v[20:21], v[162:163] op_sel_hi:[1,0]
	v_pk_mul_f32 v[28:29], v[28:29], v[162:163] op_sel_hi:[1,0]
	v_lshlrev_b64 v[40:41], 10, v[40:41]
	v_pk_mul_f32 v[16:17], v[16:17], v[162:163] op_sel_hi:[1,0]
	v_pk_mul_f32 v[22:23], v[22:23], v[162:163] op_sel_hi:[1,0]
	v_pk_mul_f32 v[30:31], v[30:31], v[162:163] op_sel_hi:[1,0]
	v_cvt_pk_bf16_f32 v28, v28, v29
	v_pk_mul_f32 v[26:27], v[26:27], v[162:163] op_sel_hi:[1,0]
	v_pk_mul_f32 v[24:25], v[24:25], v[162:163] op_sel_hi:[1,0]
	v_cvt_pk_bf16_f32 v20, v20, v21
	v_lshl_add_u64 v[40:41], s[38:39], 0, v[40:41]
	v_pk_mul_f32 v[18:19], v[18:19], v[162:163] op_sel_hi:[1,0]
	v_cvt_pk_bf16_f32 v29, v30, v31
	v_cvt_pk_bf16_f32 v24, v24, v25
	v_cvt_pk_bf16_f32 v25, v26, v27
	v_cvt_pk_bf16_f32 v21, v22, v23
	v_cvt_pk_bf16_f32 v22, v16, v17
	v_cndmask_b32_e64 v16, v28, v20, s[2:3]
	v_mov_b32_e32 v26, 0
	v_cndmask_b32_e64 v33, v43, v45, s[2:3]
	v_cndmask_b32_e64 v32, v42, v44, s[2:3]
	v_lshl_add_u64 v[40:41], v[40:41], 0, v[112:113]
	v_cvt_pk_bf16_f32 v23, v18, v19
	v_mov_b32_dpp v26, v16 row_ror:8 row_mask:0xf bank_mask:0xf
	v_cndmask_b32_e64 v16, v29, v21, s[2:3]
	v_mov_b32_e32 v27, 0
	v_cndmask_b32_e64 v17, v24, v22, s[2:3]
	v_mov_b32_e32 v30, 0
	global_store_dwordx4 v[40:41], v[32:35], off
	v_mov_b32_dpp v27, v16 row_ror:8 row_mask:0xf bank_mask:0xf
	v_cndmask_b32_e64 v16, v25, v23, s[2:3]
	v_add_u32_e32 v34, 0x98, v146
	v_mov_b32_dpp v30, v17 row_ror:8 row_mask:0xf bank_mask:0xf
	v_mov_b32_e32 v31, 0
	v_cndmask_b32_e64 v18, v30, v24, s[2:3]
	v_cndmask_b32_e64 v24, v34, v148, s[2:3]
	v_mov_b32_dpp v31, v16 row_ror:8 row_mask:0xf bank_mask:0xf
	v_cndmask_b32_e64 v19, v31, v25, s[2:3]
	v_ashrrev_i32_e32 v25, 31, v24
	v_lshlrev_b64 v[24:25], 10, v[24:25]
	v_lshl_add_u64 v[24:25], s[38:39], 0, v[24:25]
	v_cndmask_b32_e64 v17, v27, v29, s[2:3]
	v_cndmask_b32_e64 v16, v26, v28, s[2:3]
	v_lshl_add_u64 v[24:25], v[24:25], 0, v[112:113]
	global_store_dwordx4 v[24:25], v[16:19], off
	v_pk_mul_f32 v[4:5], v[4:5], v[160:161] op_sel_hi:[1,0]
	v_pk_mul_f32 v[12:13], v[12:13], v[160:161] op_sel_hi:[1,0]
	v_add_u32_e32 v18, 0xa8, v146
	v_cndmask_b32_e64 v16, v148, v18, s[2:3]
	v_ashrrev_i32_e32 v17, 31, v16
	v_pk_mul_f32 v[10:11], v[10:11], v[160:161] op_sel_hi:[1,0]
	v_pk_mul_f32 v[8:9], v[8:9], v[160:161] op_sel_hi:[1,0]
	v_lshlrev_b64 v[16:17], 10, v[16:17]
	v_pk_mul_f32 v[0:1], v[0:1], v[160:161] op_sel_hi:[1,0]
	v_pk_mul_f32 v[6:7], v[6:7], v[160:161] op_sel_hi:[1,0]
	v_pk_mul_f32 v[14:15], v[14:15], v[160:161] op_sel_hi:[1,0]
	v_cvt_pk_bf16_f32 v12, v12, v13
	v_cvt_pk_bf16_f32 v8, v8, v9
	v_cvt_pk_bf16_f32 v9, v10, v11
	v_cvt_pk_bf16_f32 v10, v4, v5
	v_lshl_add_u64 v[16:17], s[38:39], 0, v[16:17]
	v_pk_mul_f32 v[2:3], v[2:3], v[160:161] op_sel_hi:[1,0]
	v_cvt_pk_bf16_f32 v13, v14, v15
	v_cvt_pk_bf16_f32 v6, v6, v7
	v_cvt_pk_bf16_f32 v7, v0, v1
	v_cndmask_b32_e64 v0, v12, v10, s[2:3]
	v_mov_b32_e32 v14, 0
	v_cndmask_b32_e64 v4, v18, v150, s[2:3]
	v_cndmask_b32_e64 v23, v23, v31, s[2:3]
	v_cndmask_b32_e64 v22, v22, v30, s[2:3]
	v_cndmask_b32_e64 v21, v21, v27, s[2:3]
	v_cndmask_b32_e64 v20, v20, v26, s[2:3]
	v_lshl_add_u64 v[16:17], v[16:17], 0, v[112:113]
	v_cvt_pk_bf16_f32 v11, v2, v3
	v_mov_b32_dpp v14, v0 row_ror:8 row_mask:0xf bank_mask:0xf
	v_cndmask_b32_e64 v0, v13, v6, s[2:3]
	v_mov_b32_e32 v15, 0
	v_ashrrev_i32_e32 v5, 31, v4
	global_store_dwordx4 v[16:17], v[20:23], off
	v_mov_b32_dpp v15, v0 row_ror:8 row_mask:0xf bank_mask:0xf
	v_cndmask_b32_e64 v0, v9, v11, s[2:3]
	v_cndmask_b32_e64 v1, v8, v7, s[2:3]
	v_mov_b32_e32 v16, 0
	v_mov_b32_e32 v17, 0
	v_lshlrev_b64 v[4:5], 10, v[4:5]
	v_mov_b32_dpp v16, v1 row_ror:8 row_mask:0xf bank_mask:0xf
	v_mov_b32_dpp v17, v0 row_ror:8 row_mask:0xf bank_mask:0xf
	v_lshl_add_u64 v[4:5], s[38:39], 0, v[4:5]
	v_cndmask_b32_e64 v3, v17, v9, s[2:3]
	v_cndmask_b32_e64 v2, v16, v8, s[2:3]
	v_cndmask_b32_e64 v1, v15, v13, s[2:3]
	v_cndmask_b32_e64 v0, v14, v12, s[2:3]
	v_lshl_add_u64 v[4:5], v[4:5], 0, v[112:113]
	global_store_dwordx4 v[4:5], v[0:3], off
	v_cndmask_b32_e64 v48, v154, v50, s[2:3]
	v_cndmask_b32_e64 v32, v152, v34, s[2:3]
	v_add_u32_e32 v0, 0xb8, v146
	v_cndmask_b32_e64 v0, v150, v0, s[2:3]
	v_ashrrev_i32_e32 v49, 31, v48
	v_ashrrev_i32_e32 v33, 31, v32
	v_ashrrev_i32_e32 v1, 31, v0
	v_lshlrev_b64 v[48:49], 10, v[48:49]
	v_lshlrev_b64 v[32:33], 10, v[32:33]
	v_lshlrev_b64 v[0:1], 10, v[0:1]
	v_lshl_add_u64 v[48:49], s[38:39], 0, v[48:49]
	v_lshl_add_u64 v[32:33], s[38:39], 0, v[32:33]
	v_lshl_add_u64 v[0:1], s[38:39], 0, v[0:1]
	v_cndmask_b32_e64 v55, v55, v63, s[2:3]
	v_cndmask_b32_e64 v54, v54, v62, s[2:3]
	v_cndmask_b32_e64 v53, v53, v59, s[2:3]
	v_cndmask_b32_e64 v52, v52, v58, s[2:3]
	v_lshl_add_u64 v[48:49], v[48:49], 0, v[112:113]
	v_cndmask_b32_e64 v39, v39, v47, s[2:3]
	v_cndmask_b32_e64 v38, v38, v46, s[2:3]
	v_cndmask_b32_e64 v37, v37, v43, s[2:3]
	v_cndmask_b32_e64 v36, v36, v42, s[2:3]
	v_lshl_add_u64 v[32:33], v[32:33], 0, v[112:113]
	v_lshl_add_u64 v[4:5], v[0:1], 0, v[112:113]
	v_cndmask_b32_e64 v3, v11, v17, s[2:3]
	v_cndmask_b32_e64 v2, v7, v16, s[2:3]
	v_cndmask_b32_e64 v1, v6, v15, s[2:3]
	v_cndmask_b32_e64 v0, v10, v14, s[2:3]
	s_and_b64 vcc, exec, s[4:5]
	s_mov_b32 s66, s36
	s_mov_b32 s6, s44
	s_mov_b64 s[50:51], s[48:49]
	s_mov_b64 s[52:53], s[46:47]
	global_store_dwordx4 v[48:49], v[52:55], off
	global_store_dwordx4 v[32:33], v[36:39], off
	global_store_dwordx4 v[4:5], v[0:3], off
	s_cbranch_vccz .LBB0_897
	s_waitcnt vmcnt(0)
	s_cmpk_gt_u32 s11, 0xff
	s_cbranch_scc1 .LBB0_908
	s_barrier

.LBB0_997:
	ds_read_b128 v[128:131], v164
	ds_read_b128 v[132:135], v164 offset:1024
	ds_read_b128 v[152:155], v164 offset:2048
	ds_read_b128 v[156:159], v164 offset:3072
	s_add_u32 s28, s48, 0xfffe0080
	s_addc_u32 s29, s49, -1
	s_cmp_eq_u32 s79, 4
	s_cselect_b32 s53, s9, s29
	s_cselect_b32 s52, s41, s28
	s_cselect_b32 s51, s39, s78
	s_cselect_b32 s50, s76, s77
	v_lshl_add_u64 v[204:205], s[48:49], 0, v[144:145]
	s_add_i32 m0, s55, 0xc000
	ds_read_b128 v[168:171], v165
	ds_read_b128 v[172:175], v165 offset:1024
	ds_read_b128 v[176:179], v165 offset:2048
	ds_read_b128 v[180:183], v165 offset:3072
	ds_read_b128 v[184:187], v165 offset:4096
	ds_read_b128 v[188:191], v165 offset:5120
	ds_read_b128 v[196:199], v165 offset:6144
	ds_read_b128 v[200:203], v165 offset:7168
	global_load_lds_dwordx4 v[204:205], off
	v_lshl_add_u64 v[204:205], s[48:49], 0, v[146:147]
	s_add_i32 m0, s55, 0xe000
	s_nop 0
	global_load_lds_dwordx4 v[204:205], off
	s_waitcnt lgkmcnt(8)
	s_barrier
	s_waitcnt lgkmcnt(0)
	s_waitcnt lgkmcnt(0)
	v_mfma_f32_16x16x32_bf16 v[124:127], v[128:131], v[168:171], v[124:127]
	v_mfma_f32_16x16x32_bf16 v[120:123], v[152:155], v[168:171], v[120:123]
	v_mfma_f32_16x16x32_bf16 v[108:111], v[128:131], v[176:179], v[108:111]
	v_mfma_f32_16x16x32_bf16 v[104:107], v[152:155], v[176:179], v[104:107]
	v_mfma_f32_16x16x32_bf16 v[92:95], v[128:131], v[184:187], v[92:95]
	v_mfma_f32_16x16x32_bf16 v[88:91], v[152:155], v[184:187], v[88:91]
	v_mfma_f32_16x16x32_bf16 v[76:79], v[128:131], v[196:199], v[76:79]
	v_mfma_f32_16x16x32_bf16 v[72:75], v[152:155], v[196:199], v[72:75]
	v_mfma_f32_16x16x32_bf16 v[124:127], v[132:135], v[172:175], v[124:127]
	v_mfma_f32_16x16x32_bf16 v[120:123], v[156:159], v[172:175], v[120:123]
	v_mfma_f32_16x16x32_bf16 v[108:111], v[132:135], v[180:183], v[108:111]
	v_mfma_f32_16x16x32_bf16 v[104:107], v[156:159], v[180:183], v[104:107]
	v_mfma_f32_16x16x32_bf16 v[92:95], v[132:135], v[188:191], v[92:95]
	v_mfma_f32_16x16x32_bf16 v[88:91], v[156:159], v[188:191], v[88:91]
	v_mfma_f32_16x16x32_bf16 v[76:79], v[132:135], v[200:203], v[76:79]
	v_mfma_f32_16x16x32_bf16 v[72:75], v[156:159], v[200:203], v[72:75]
	s_barrier
	s_add_i32 s28, s65, s54
	v_lshl_add_u64 v[220:221], s[50:51], 0, v[138:139]
	s_mov_b32 m0, s28
	ds_read_b128 v[204:207], v166
	ds_read_b128 v[208:211], v166 offset:1024
	ds_read_b128 v[212:215], v166 offset:2048
	ds_read_b128 v[216:219], v166 offset:3072
	global_load_lds_dwordx4 v[220:221], off
	v_lshl_add_u64 v[222:223], s[50:51], 0, v[142:143]
	s_add_i32 m0, s28, 0x2000
	s_nop 0
	global_load_lds_dwordx4 v[222:223], off
	s_barrier
	s_waitcnt lgkmcnt(0)
	s_waitcnt lgkmcnt(0)
	v_mfma_f32_16x16x32_bf16 v[116:119], v[204:207], v[168:171], v[116:119]
	v_mfma_f32_16x16x32_bf16 v[112:115], v[212:215], v[168:171], v[112:115]
	v_mfma_f32_16x16x32_bf16 v[100:103], v[204:207], v[176:179], v[100:103]
	v_mfma_f32_16x16x32_bf16 v[96:99], v[212:215], v[176:179], v[96:99]
	v_mfma_f32_16x16x32_bf16 v[84:87], v[204:207], v[184:187], v[84:87]
	v_mfma_f32_16x16x32_bf16 v[80:83], v[212:215], v[184:187], v[80:83]
	v_mfma_f32_16x16x32_bf16 v[68:71], v[204:207], v[196:199], v[68:71]
	v_mfma_f32_16x16x32_bf16 v[64:67], v[212:215], v[196:199], v[64:67]
	v_mfma_f32_16x16x32_bf16 v[116:119], v[208:211], v[172:175], v[116:119]
	v_mfma_f32_16x16x32_bf16 v[112:115], v[216:219], v[172:175], v[112:115]
	v_mfma_f32_16x16x32_bf16 v[100:103], v[208:211], v[180:183], v[100:103]
	v_mfma_f32_16x16x32_bf16 v[96:99], v[216:219], v[180:183], v[96:99]
	v_mfma_f32_16x16x32_bf16 v[84:87], v[208:211], v[188:191], v[84:87]
	v_mfma_f32_16x16x32_bf16 v[80:83], v[216:219], v[188:191], v[80:83]
	v_mfma_f32_16x16x32_bf16 v[68:71], v[208:211], v[200:203], v[68:71]
	v_mfma_f32_16x16x32_bf16 v[64:67], v[216:219], v[200:203], v[64:67]
	s_mov_b32 m0, s55
	v_lshl_add_u64 v[224:225], s[52:53], 0, v[136:137]
	s_barrier
	ds_read_b128 v[168:171], v165 offset:16384
	ds_read_b128 v[172:175], v165 offset:17408
	ds_read_b128 v[176:179], v165 offset:18432
	ds_read_b128 v[180:183], v165 offset:19456
	ds_read_b128 v[184:187], v165 offset:20480
	ds_read_b128 v[188:191], v165 offset:21504
	ds_read_b128 v[196:199], v165 offset:22528
	ds_read_b128 v[200:203], v165 offset:23552
	global_load_lds_dwordx4 v[224:225], off
	v_lshl_add_u64 v[226:227], s[52:53], 0, v[140:141]
	s_mov_b32 m0, s56
	s_nop 0
	global_load_lds_dwordx4 v[226:227], off
	s_barrier
	s_waitcnt lgkmcnt(0)
	s_waitcnt lgkmcnt(0)
	v_mfma_f32_16x16x32_bf16 v[60:63], v[128:131], v[168:171], v[60:63]
	v_mfma_f32_16x16x32_bf16 v[56:59], v[152:155], v[168:171], v[56:59]
	v_mfma_f32_16x16x32_bf16 v[44:47], v[128:131], v[176:179], v[44:47]
	v_mfma_f32_16x16x32_bf16 v[40:43], v[152:155], v[176:179], v[40:43]
	v_mfma_f32_16x16x32_bf16 v[28:31], v[128:131], v[184:187], v[28:31]
	v_mfma_f32_16x16x32_bf16 v[24:27], v[152:155], v[184:187], v[24:27]
	v_mfma_f32_16x16x32_bf16 v[12:15], v[128:131], v[196:199], v[12:15]
	v_mfma_f32_16x16x32_bf16 v[8:11], v[152:155], v[196:199], v[8:11]
	v_mfma_f32_16x16x32_bf16 v[60:63], v[132:135], v[172:175], v[60:63]
	v_mfma_f32_16x16x32_bf16 v[56:59], v[156:159], v[172:175], v[56:59]
	v_mfma_f32_16x16x32_bf16 v[44:47], v[132:135], v[180:183], v[44:47]
	v_mfma_f32_16x16x32_bf16 v[40:43], v[156:159], v[180:183], v[40:43]
	v_mfma_f32_16x16x32_bf16 v[28:31], v[132:135], v[188:191], v[28:31]
	v_mfma_f32_16x16x32_bf16 v[24:27], v[156:159], v[188:191], v[24:27]
	v_mfma_f32_16x16x32_bf16 v[12:15], v[132:135], v[200:203], v[12:15]
	v_mfma_f32_16x16x32_bf16 v[8:11], v[156:159], v[200:203], v[8:11]
	s_barrier
	s_add_u32 s80, s50, 0x8000
	s_addc_u32 s81, s51, 0
	s_add_i32 s28, s66, s54
	v_lshl_add_u64 v[128:129], s[80:81], 0, v[138:139]
	s_mov_b32 m0, s28
	s_nop 0
	global_load_lds_dwordx4 v[128:129], off
	v_lshl_add_u64 v[128:129], s[80:81], 0, v[142:143]
	s_add_i32 m0, s28, 0x2000
	s_nop 0
	global_load_lds_dwordx4 v[128:129], off
	s_waitcnt vmcnt(6)
	s_barrier
	v_mfma_f32_16x16x32_bf16 v[52:55], v[204:207], v[168:171], v[52:55]
	v_mfma_f32_16x16x32_bf16 v[48:51], v[212:215], v[168:171], v[48:51]
	v_mfma_f32_16x16x32_bf16 v[36:39], v[204:207], v[176:179], v[36:39]
	v_mfma_f32_16x16x32_bf16 v[32:35], v[212:215], v[176:179], v[32:35]
	v_mfma_f32_16x16x32_bf16 v[20:23], v[204:207], v[184:187], v[20:23]
	v_mfma_f32_16x16x32_bf16 v[16:19], v[212:215], v[184:187], v[16:19]
	v_mfma_f32_16x16x32_bf16 v[4:7], v[204:207], v[196:199], v[4:7]
	v_mfma_f32_16x16x32_bf16 v[0:3], v[212:215], v[196:199], v[0:3]
	v_mfma_f32_16x16x32_bf16 v[52:55], v[208:211], v[172:175], v[52:55]
	v_mfma_f32_16x16x32_bf16 v[48:51], v[216:219], v[172:175], v[48:51]
	v_mfma_f32_16x16x32_bf16 v[36:39], v[208:211], v[180:183], v[36:39]
	v_mfma_f32_16x16x32_bf16 v[32:35], v[216:219], v[180:183], v[32:35]
	v_mfma_f32_16x16x32_bf16 v[20:23], v[208:211], v[188:191], v[20:23]
	v_mfma_f32_16x16x32_bf16 v[16:19], v[216:219], v[188:191], v[16:19]
	v_mfma_f32_16x16x32_bf16 v[4:7], v[208:211], v[200:203], v[4:7]
	v_mfma_f32_16x16x32_bf16 v[0:3], v[216:219], v[200:203], v[0:3]
	s_add_i32 s28, 0, 0x18000
	v_add_u32_e32 v156, s28, v161
	s_barrier
	ds_read_b128 v[128:131], v156
	ds_read_b128 v[132:135], v156 offset:1024
	ds_read_b128 v[152:155], v156 offset:2048
	ds_read_b128 v[156:159], v156 offset:3072
	s_add_u32 s52, s52, 0x20000
	s_addc_u32 s53, s53, 0
	s_mov_b32 m0, s57
	v_lshl_add_u64 v[204:205], s[52:53], 0, v[136:137]
	ds_read_b128 v[168:171], v165 offset:32768
	ds_read_b128 v[172:175], v165 offset:33792
	ds_read_b128 v[176:179], v165 offset:34816
	ds_read_b128 v[180:183], v165 offset:35840
	ds_read_b128 v[184:187], v165 offset:36864
	ds_read_b128 v[188:191], v165 offset:37888
	ds_read_b128 v[196:199], v165 offset:38912
	ds_read_b128 v[200:203], v165 offset:39936
	global_load_lds_dwordx4 v[204:205], off
	v_lshl_add_u64 v[204:205], s[52:53], 0, v[140:141]
	s_mov_b32 m0, s58
	s_nop 0
	global_load_lds_dwordx4 v[204:205], off
	s_waitcnt lgkmcnt(8)
	s_barrier
	s_waitcnt lgkmcnt(0)
	s_waitcnt lgkmcnt(0)
	v_mfma_f32_16x16x32_bf16 v[124:127], v[128:131], v[168:171], v[124:127]
	v_mfma_f32_16x16x32_bf16 v[120:123], v[152:155], v[168:171], v[120:123]
	v_mfma_f32_16x16x32_bf16 v[108:111], v[128:131], v[176:179], v[108:111]
	v_mfma_f32_16x16x32_bf16 v[104:107], v[152:155], v[176:179], v[104:107]
	v_mfma_f32_16x16x32_bf16 v[92:95], v[128:131], v[184:187], v[92:95]
	v_mfma_f32_16x16x32_bf16 v[88:91], v[152:155], v[184:187], v[88:91]
	v_mfma_f32_16x16x32_bf16 v[76:79], v[128:131], v[196:199], v[76:79]
	v_mfma_f32_16x16x32_bf16 v[72:75], v[152:155], v[196:199], v[72:75]
	v_mfma_f32_16x16x32_bf16 v[124:127], v[132:135], v[172:175], v[124:127]
	v_mfma_f32_16x16x32_bf16 v[120:123], v[156:159], v[172:175], v[120:123]
	v_mfma_f32_16x16x32_bf16 v[108:111], v[132:135], v[180:183], v[108:111]
	v_mfma_f32_16x16x32_bf16 v[104:107], v[156:159], v[180:183], v[104:107]
	v_mfma_f32_16x16x32_bf16 v[92:95], v[132:135], v[188:191], v[92:95]
	v_mfma_f32_16x16x32_bf16 v[88:91], v[156:159], v[188:191], v[88:91]
	v_mfma_f32_16x16x32_bf16 v[76:79], v[132:135], v[200:203], v[76:79]
	v_mfma_f32_16x16x32_bf16 v[72:75], v[156:159], v[200:203], v[72:75]
	s_barrier
	s_add_i32 s29, 0, 0x1c000
	s_add_i32 s28, s28, s54
	v_add_u32_e32 v195, s29, v161
	v_lshl_add_u64 v[220:221], v[220:221], 0, s[36:37]
	s_mov_b32 m0, s28
	ds_read_b128 v[204:207], v195
	ds_read_b128 v[208:211], v195 offset:1024
	ds_read_b128 v[212:215], v195 offset:2048
	ds_read_b128 v[216:219], v195 offset:3072
	global_load_lds_dwordx4 v[220:221], off
	v_lshl_add_u64 v[220:221], v[222:223], 0, s[36:37]
	s_add_i32 m0, s28, 0x2000
	s_nop 0
	global_load_lds_dwordx4 v[220:221], off
	s_barrier
	s_waitcnt lgkmcnt(0)
	s_waitcnt lgkmcnt(0)
	v_mfma_f32_16x16x32_bf16 v[116:119], v[204:207], v[168:171], v[116:119]
	v_mfma_f32_16x16x32_bf16 v[112:115], v[212:215], v[168:171], v[112:115]
	v_mfma_f32_16x16x32_bf16 v[100:103], v[204:207], v[176:179], v[100:103]
	v_mfma_f32_16x16x32_bf16 v[96:99], v[212:215], v[176:179], v[96:99]
	v_mfma_f32_16x16x32_bf16 v[84:87], v[204:207], v[184:187], v[84:87]
	v_mfma_f32_16x16x32_bf16 v[80:83], v[212:215], v[184:187], v[80:83]
	v_mfma_f32_16x16x32_bf16 v[68:71], v[204:207], v[196:199], v[68:71]
	v_mfma_f32_16x16x32_bf16 v[64:67], v[212:215], v[196:199], v[64:67]
	v_mfma_f32_16x16x32_bf16 v[116:119], v[208:211], v[172:175], v[116:119]
	v_mfma_f32_16x16x32_bf16 v[112:115], v[216:219], v[172:175], v[112:115]
	v_mfma_f32_16x16x32_bf16 v[100:103], v[208:211], v[180:183], v[100:103]
	v_mfma_f32_16x16x32_bf16 v[96:99], v[216:219], v[180:183], v[96:99]
	v_mfma_f32_16x16x32_bf16 v[84:87], v[208:211], v[188:191], v[84:87]
	v_mfma_f32_16x16x32_bf16 v[80:83], v[216:219], v[188:191], v[80:83]
	v_mfma_f32_16x16x32_bf16 v[68:71], v[208:211], v[200:203], v[68:71]
	v_mfma_f32_16x16x32_bf16 v[64:67], v[216:219], v[200:203], v[64:67]
	s_mov_b32 m0, s62
	v_lshl_add_u64 v[220:221], v[224:225], 0, s[36:37]
	s_barrier
	ds_read_b128 v[168:171], v165 offset:49152
	ds_read_b128 v[172:175], v165 offset:50176
	ds_read_b128 v[176:179], v165 offset:51200
	ds_read_b128 v[180:183], v165 offset:52224
	ds_read_b128 v[184:187], v165 offset:53248
	ds_read_b128 v[188:191], v165 offset:54272
	ds_read_b128 v[196:199], v165 offset:55296
	ds_read_b128 v[200:203], v165 offset:56320
	global_load_lds_dwordx4 v[220:221], off
	v_lshl_add_u64 v[220:221], v[226:227], 0, s[36:37]
	s_mov_b32 m0, s63
	s_nop 0
	global_load_lds_dwordx4 v[220:221], off
	s_barrier
	s_waitcnt lgkmcnt(0)
	s_waitcnt lgkmcnt(0)
	v_mfma_f32_16x16x32_bf16 v[60:63], v[128:131], v[168:171], v[60:63]
	v_mfma_f32_16x16x32_bf16 v[56:59], v[152:155], v[168:171], v[56:59]
	v_mfma_f32_16x16x32_bf16 v[44:47], v[128:131], v[176:179], v[44:47]
	v_mfma_f32_16x16x32_bf16 v[40:43], v[152:155], v[176:179], v[40:43]
	v_mfma_f32_16x16x32_bf16 v[28:31], v[128:131], v[184:187], v[28:31]
	v_mfma_f32_16x16x32_bf16 v[24:27], v[152:155], v[184:187], v[24:27]
	v_mfma_f32_16x16x32_bf16 v[12:15], v[128:131], v[196:199], v[12:15]
	v_mfma_f32_16x16x32_bf16 v[8:11], v[152:155], v[196:199], v[8:11]
	v_mfma_f32_16x16x32_bf16 v[60:63], v[132:135], v[172:175], v[60:63]
	v_mfma_f32_16x16x32_bf16 v[56:59], v[156:159], v[172:175], v[56:59]
	v_mfma_f32_16x16x32_bf16 v[44:47], v[132:135], v[180:183], v[44:47]
	v_mfma_f32_16x16x32_bf16 v[40:43], v[156:159], v[180:183], v[40:43]
	v_mfma_f32_16x16x32_bf16 v[28:31], v[132:135], v[188:191], v[28:31]
	v_mfma_f32_16x16x32_bf16 v[24:27], v[156:159], v[188:191], v[24:27]
	v_mfma_f32_16x16x32_bf16 v[12:15], v[132:135], v[200:203], v[12:15]
	v_mfma_f32_16x16x32_bf16 v[8:11], v[156:159], v[200:203], v[8:11]
	s_barrier
	s_add_u32 s50, s50, 0x8080
	s_addc_u32 s51, s51, 0
	s_add_i32 s28, s29, s54
	v_lshl_add_u64 v[128:129], s[50:51], 0, v[138:139]
	s_mov_b32 m0, s28
	s_nop 0
	global_load_lds_dwordx4 v[128:129], off
	v_lshl_add_u64 v[128:129], s[50:51], 0, v[142:143]
	s_add_i32 m0, s28, 0x2000
	s_nop 0
	global_load_lds_dwordx4 v[128:129], off
	s_waitcnt vmcnt(6)
	s_barrier
	v_mfma_f32_16x16x32_bf16 v[52:55], v[204:207], v[168:171], v[52:55]
	v_mfma_f32_16x16x32_bf16 v[48:51], v[212:215], v[168:171], v[48:51]
	v_mfma_f32_16x16x32_bf16 v[36:39], v[204:207], v[176:179], v[36:39]
	v_mfma_f32_16x16x32_bf16 v[32:35], v[212:215], v[176:179], v[32:35]
	v_mfma_f32_16x16x32_bf16 v[20:23], v[204:207], v[184:187], v[20:23]
	v_mfma_f32_16x16x32_bf16 v[16:19], v[212:215], v[184:187], v[16:19]
	v_mfma_f32_16x16x32_bf16 v[4:7], v[204:207], v[196:199], v[4:7]
	v_mfma_f32_16x16x32_bf16 v[0:3], v[212:215], v[196:199], v[0:3]
	v_mfma_f32_16x16x32_bf16 v[52:55], v[208:211], v[172:175], v[52:55]
	v_mfma_f32_16x16x32_bf16 v[48:51], v[216:219], v[172:175], v[48:51]
	v_mfma_f32_16x16x32_bf16 v[36:39], v[208:211], v[180:183], v[36:39]
	v_mfma_f32_16x16x32_bf16 v[32:35], v[216:219], v[180:183], v[32:35]
	v_mfma_f32_16x16x32_bf16 v[20:23], v[208:211], v[188:191], v[20:23]
	v_mfma_f32_16x16x32_bf16 v[16:19], v[216:219], v[188:191], v[16:19]
	v_mfma_f32_16x16x32_bf16 v[4:7], v[208:211], v[200:203], v[4:7]
	v_mfma_f32_16x16x32_bf16 v[0:3], v[216:219], v[200:203], v[0:3]
	s_add_i32 s79, s79, 2
	s_add_u32 s48, s48, 0x100
	s_addc_u32 s49, s49, 0
	s_add_u32 s77, s77, 0x100
	s_addc_u32 s78, s78, 0
	s_cmp_gt_u32 s79, 5
	s_barrier
	s_cbranch_scc0 .LBB0_997
	v_lshl_add_u32 v152, s8, 8, v160
	v_lshl_or_b32 v156, s10, 8, v162
	v_ashrrev_i32_e32 v153, 31, v152
	v_lshlrev_b64 v[128:129], 11, v[152:153]
	v_ashrrev_i32_e32 v157, 31, v156
	v_lshl_add_u64 v[128:129], s[42:43], 0, v[128:129]
	v_lshlrev_b64 v[130:131], 1, v[156:157]
	v_or_b32_e32 v158, 16, v152
	v_lshl_add_u64 v[128:129], v[128:129], 0, v[130:131]
	v_ashrrev_i32_e32 v159, 31, v158
	global_load_dwordx4 v[168:171], v[128:129], off
	global_load_dwordx4 v[172:175], v[128:129], off offset:64
	v_lshlrev_b64 v[128:129], 11, v[158:159]
	v_lshl_add_u64 v[128:129], s[42:43], 0, v[128:129]
	v_lshl_add_u64 v[128:129], v[128:129], 0, v[130:131]
	global_load_dwordx4 v[132:135], v[128:129], off
	s_nop 0
	global_load_dwordx4 v[128:131], v[128:129], off offset:64
	v_cndmask_b32_e64 v155, 0, 1, s[12:13]
	v_or_b32_e32 v154, v156, v163
	v_cmp_ne_u32_e64 s[8:9], 1, v155
	v_ashrrev_i32_e32 v155, 31, v154
	s_andn2_b64 vcc, exec, s[12:13]
	v_lshlrev_b64 v[154:155], 1, v[154:155]
	s_waitcnt vmcnt(0)
	v_lshlrev_b32_e32 v176, 16, v168
	v_and_b32_e32 v177, 0xffff0000, v168
	v_lshlrev_b32_e32 v168, 16, v169
	v_and_b32_e32 v169, 0xffff0000, v169
	v_lshlrev_b32_e32 v178, 16, v170
	v_and_b32_e32 v179, 0xffff0000, v170
	v_lshlrev_b32_e32 v170, 16, v171
	v_and_b32_e32 v171, 0xffff0000, v171
	v_lshlrev_b32_e32 v180, 16, v172
	v_and_b32_e32 v181, 0xffff0000, v172
	v_lshlrev_b32_e32 v172, 16, v173
	v_and_b32_e32 v173, 0xffff0000, v173
	v_lshlrev_b32_e32 v182, 16, v174
	v_and_b32_e32 v183, 0xffff0000, v174
	v_lshlrev_b32_e32 v174, 16, v175
	v_and_b32_e32 v175, 0xffff0000, v175
	v_pk_add_f32 v[126:127], v[126:127], v[168:169]
	v_pk_add_f32 v[124:125], v[124:125], v[176:177]
	v_pk_add_f32 v[122:123], v[122:123], v[170:171]
	v_pk_add_f32 v[120:121], v[120:121], v[178:179]
	v_pk_add_f32 v[118:119], v[118:119], v[172:173]
	v_pk_add_f32 v[116:117], v[116:117], v[180:181]
	v_pk_add_f32 v[114:115], v[114:115], v[174:175]
	v_pk_add_f32 v[112:113], v[112:113], v[182:183]
	v_add_u32_e32 v169, 8, v152
	s_cbranch_vccnz .LBB0_1000
	v_cvt_pk_bf16_f32 v168, v124, v125
	v_cvt_pk_bf16_f32 v174, v116, v117
	v_cvt_pk_bf16_f32 v170, v126, v127
	v_cvt_pk_bf16_f32 v171, v120, v121
	v_cvt_pk_bf16_f32 v175, v118, v119
	v_cvt_pk_bf16_f32 v176, v112, v113
	v_cndmask_b32_e64 v173, v168, v174, s[4:5]
	v_mov_b32_e32 v178, 0
	v_cvt_pk_bf16_f32 v172, v122, v123
	v_cvt_pk_bf16_f32 v177, v114, v115
	v_mov_b32_dpp v178, v173 row_ror:8 row_mask:0xf bank_mask:0xf
	v_cndmask_b32_e64 v173, v170, v175, s[4:5]
	v_mov_b32_e32 v179, 0
	v_cndmask_b32_e64 v180, v171, v176, s[4:5]
	v_mov_b32_e32 v181, 0
	v_mov_b32_dpp v179, v173 row_ror:8 row_mask:0xf bank_mask:0xf
	v_cndmask_b32_e64 v173, v172, v177, s[4:5]
	v_mov_b32_dpp v181, v180 row_ror:8 row_mask:0xf bank_mask:0xf
	v_mov_b32_e32 v180, 0
	v_cndmask_b32_e64 v174, v174, v178, s[4:5]
	v_cndmask_b32_e64 v175, v175, v179, s[4:5]
	v_mov_b32_dpp v180, v173 row_ror:8 row_mask:0xf bank_mask:0xf
	v_cndmask_b32_e64 v173, v180, v172, s[4:5]
	v_cndmask_b32_e64 v172, v181, v171, s[4:5]
	v_cndmask_b32_e64 v171, v179, v170, s[4:5]
	v_cndmask_b32_e64 v170, v178, v168, s[4:5]
	v_add_u32_e32 v168, -8, v152
	v_cndmask_b32_e64 v178, v168, v152, s[4:5]
	v_ashrrev_i32_e32 v179, 31, v178
	v_lshlrev_b64 v[178:179], 11, v[178:179]
	v_lshl_add_u64 v[178:179], s[68:69], 0, v[178:179]
	v_lshl_add_u64 v[178:179], v[178:179], 0, v[154:155]
	global_store_dwordx4 v[178:179], v[170:173], off
	v_cndmask_b32_e64 v177, v177, v180, s[4:5]
	v_cndmask_b32_e64 v176, v176, v181, s[4:5]
	v_cndmask_b32_e64 v170, v152, v169, s[4:5]
	v_ashrrev_i32_e32 v171, 31, v170
	v_lshlrev_b64 v[170:171], 11, v[170:171]
	v_lshl_add_u64 v[170:171], s[68:69], 0, v[170:171]
	v_lshl_add_u64 v[170:171], v[170:171], 0, v[154:155]
	global_store_dwordx4 v[170:171], v[174:177], off

.LBB0_1169:
	ds_read_b128 v[128:131], v167
	ds_read_b128 v[132:135], v167 offset:1024
	ds_read_b128 v[136:139], v167 offset:2048
	ds_read_b128 v[156:159], v167 offset:3072
	s_add_u32 s6, s40, 0x100
	s_addc_u32 s7, s41, 0
	s_cmp_eq_u32 s65, 40
	s_cselect_b32 s45, s1, s7
	s_cselect_b32 s44, s0, s6
	s_cselect_b32 s43, s39, s64
	s_cselect_b32 s42, s38, s63
	v_lshl_add_u64 v[202:203], s[40:41], 0, v[148:149]
	s_add_i32 m0, s47, 0xc000
	ds_read_b128 v[160:163], v168
	ds_read_b128 v[172:175], v168 offset:1024
	ds_read_b128 v[176:179], v168 offset:2048
	ds_read_b128 v[180:183], v168 offset:3072
	ds_read_b128 v[184:187], v168 offset:4096
	ds_read_b128 v[188:191], v168 offset:5120
	ds_read_b128 v[194:197], v168 offset:6144
	ds_read_b128 v[198:201], v168 offset:7168
	global_load_lds_dwordx4 v[202:203], off
	v_lshl_add_u64 v[202:203], s[40:41], 0, v[150:151]
	s_add_i32 m0, s47, 0xe000
	s_nop 0
	global_load_lds_dwordx4 v[202:203], off
	s_waitcnt lgkmcnt(8)
	s_barrier
	s_waitcnt lgkmcnt(0)
	s_waitcnt lgkmcnt(0)
	v_mfma_f32_16x16x32_bf16 v[124:127], v[128:131], v[160:163], v[124:127]
	v_mfma_f32_16x16x32_bf16 v[120:123], v[136:139], v[160:163], v[120:123]
	v_mfma_f32_16x16x32_bf16 v[108:111], v[128:131], v[176:179], v[108:111]
	v_mfma_f32_16x16x32_bf16 v[104:107], v[136:139], v[176:179], v[104:107]
	v_mfma_f32_16x16x32_bf16 v[92:95], v[128:131], v[184:187], v[92:95]
	v_mfma_f32_16x16x32_bf16 v[88:91], v[136:139], v[184:187], v[88:91]
	v_mfma_f32_16x16x32_bf16 v[76:79], v[128:131], v[194:197], v[76:79]
	v_mfma_f32_16x16x32_bf16 v[72:75], v[136:139], v[194:197], v[72:75]
	v_mfma_f32_16x16x32_bf16 v[124:127], v[132:135], v[172:175], v[124:127]
	v_mfma_f32_16x16x32_bf16 v[120:123], v[156:159], v[172:175], v[120:123]
	v_mfma_f32_16x16x32_bf16 v[108:111], v[132:135], v[180:183], v[108:111]
	v_mfma_f32_16x16x32_bf16 v[104:107], v[156:159], v[180:183], v[104:107]
	v_mfma_f32_16x16x32_bf16 v[92:95], v[132:135], v[188:191], v[92:95]
	v_mfma_f32_16x16x32_bf16 v[88:91], v[156:159], v[188:191], v[88:91]
	v_mfma_f32_16x16x32_bf16 v[76:79], v[132:135], v[198:201], v[76:79]
	v_mfma_f32_16x16x32_bf16 v[72:75], v[156:159], v[198:201], v[72:75]
	s_barrier
	s_add_i32 s28, s57, s46
	v_lshl_add_u64 v[218:219], s[42:43], 0, v[142:143]
	s_mov_b32 m0, s28
	ds_read_b128 v[202:205], v169
	ds_read_b128 v[206:209], v169 offset:1024
	ds_read_b128 v[210:213], v169 offset:2048
	ds_read_b128 v[214:217], v169 offset:3072
	global_load_lds_dwordx4 v[218:219], off
	v_lshl_add_u64 v[220:221], s[42:43], 0, v[146:147]
	s_add_i32 m0, s28, 0x2000
	s_nop 0
	global_load_lds_dwordx4 v[220:221], off
	s_barrier
	s_waitcnt lgkmcnt(0)
	s_waitcnt lgkmcnt(0)
	v_mfma_f32_16x16x32_bf16 v[116:119], v[202:205], v[160:163], v[116:119]
	v_mfma_f32_16x16x32_bf16 v[112:115], v[210:213], v[160:163], v[112:115]
	v_mfma_f32_16x16x32_bf16 v[100:103], v[202:205], v[176:179], v[100:103]
	v_mfma_f32_16x16x32_bf16 v[96:99], v[210:213], v[176:179], v[96:99]
	v_mfma_f32_16x16x32_bf16 v[84:87], v[202:205], v[184:187], v[84:87]
	v_mfma_f32_16x16x32_bf16 v[80:83], v[210:213], v[184:187], v[80:83]
	v_mfma_f32_16x16x32_bf16 v[68:71], v[202:205], v[194:197], v[68:71]
	v_mfma_f32_16x16x32_bf16 v[64:67], v[210:213], v[194:197], v[64:67]
	v_mfma_f32_16x16x32_bf16 v[116:119], v[206:209], v[172:175], v[116:119]
	v_mfma_f32_16x16x32_bf16 v[112:115], v[214:217], v[172:175], v[112:115]
	v_mfma_f32_16x16x32_bf16 v[100:103], v[206:209], v[180:183], v[100:103]
	v_mfma_f32_16x16x32_bf16 v[96:99], v[214:217], v[180:183], v[96:99]
	v_mfma_f32_16x16x32_bf16 v[84:87], v[206:209], v[188:191], v[84:87]
	v_mfma_f32_16x16x32_bf16 v[80:83], v[214:217], v[188:191], v[80:83]
	v_mfma_f32_16x16x32_bf16 v[68:71], v[206:209], v[198:201], v[68:71]
	v_mfma_f32_16x16x32_bf16 v[64:67], v[214:217], v[198:201], v[64:67]
	s_mov_b32 m0, s47
	v_lshl_add_u64 v[222:223], s[44:45], 0, v[140:141]
	s_barrier
	ds_read_b128 v[160:163], v168 offset:16384
	ds_read_b128 v[172:175], v168 offset:17408
	ds_read_b128 v[176:179], v168 offset:18432
	ds_read_b128 v[180:183], v168 offset:19456
	ds_read_b128 v[184:187], v168 offset:20480
	ds_read_b128 v[188:191], v168 offset:21504
	ds_read_b128 v[194:197], v168 offset:22528
	ds_read_b128 v[198:201], v168 offset:23552
	global_load_lds_dwordx4 v[222:223], off
	v_lshl_add_u64 v[224:225], s[44:45], 0, v[144:145]
	s_mov_b32 m0, s48
	s_nop 0
	global_load_lds_dwordx4 v[224:225], off
	s_barrier
	s_waitcnt lgkmcnt(0)
	s_waitcnt lgkmcnt(0)
	v_mfma_f32_16x16x32_bf16 v[60:63], v[128:131], v[160:163], v[60:63]
	v_mfma_f32_16x16x32_bf16 v[56:59], v[136:139], v[160:163], v[56:59]
	v_mfma_f32_16x16x32_bf16 v[44:47], v[128:131], v[176:179], v[44:47]
	v_mfma_f32_16x16x32_bf16 v[40:43], v[136:139], v[176:179], v[40:43]
	v_mfma_f32_16x16x32_bf16 v[28:31], v[128:131], v[184:187], v[28:31]
	v_mfma_f32_16x16x32_bf16 v[24:27], v[136:139], v[184:187], v[24:27]
	v_mfma_f32_16x16x32_bf16 v[12:15], v[128:131], v[194:197], v[12:15]
	v_mfma_f32_16x16x32_bf16 v[8:11], v[136:139], v[194:197], v[8:11]
	v_mfma_f32_16x16x32_bf16 v[60:63], v[132:135], v[172:175], v[60:63]
	v_mfma_f32_16x16x32_bf16 v[56:59], v[156:159], v[172:175], v[56:59]
	v_mfma_f32_16x16x32_bf16 v[44:47], v[132:135], v[180:183], v[44:47]
	v_mfma_f32_16x16x32_bf16 v[40:43], v[156:159], v[180:183], v[40:43]
	v_mfma_f32_16x16x32_bf16 v[28:31], v[132:135], v[188:191], v[28:31]
	v_mfma_f32_16x16x32_bf16 v[24:27], v[156:159], v[188:191], v[24:27]
	v_mfma_f32_16x16x32_bf16 v[12:15], v[132:135], v[198:201], v[12:15]
	v_mfma_f32_16x16x32_bf16 v[8:11], v[156:159], v[198:201], v[8:11]
	s_barrier
	s_add_u32 s40, s42, 0x2c000
	s_addc_u32 s41, s43, 0
	s_add_i32 s28, s58, s46
	v_lshl_add_u64 v[128:129], s[40:41], 0, v[142:143]
	s_mov_b32 m0, s28
	s_nop 0
	global_load_lds_dwordx4 v[128:129], off
	v_lshl_add_u64 v[128:129], s[40:41], 0, v[146:147]
	s_add_i32 m0, s28, 0x2000
	s_nop 0
	global_load_lds_dwordx4 v[128:129], off
	s_waitcnt vmcnt(6)
	s_barrier
	v_mfma_f32_16x16x32_bf16 v[52:55], v[202:205], v[160:163], v[52:55]
	v_mfma_f32_16x16x32_bf16 v[48:51], v[210:213], v[160:163], v[48:51]
	v_mfma_f32_16x16x32_bf16 v[36:39], v[202:205], v[176:179], v[36:39]
	v_mfma_f32_16x16x32_bf16 v[32:35], v[210:213], v[176:179], v[32:35]
	v_mfma_f32_16x16x32_bf16 v[20:23], v[202:205], v[184:187], v[20:23]
	v_mfma_f32_16x16x32_bf16 v[16:19], v[210:213], v[184:187], v[16:19]
	v_mfma_f32_16x16x32_bf16 v[4:7], v[202:205], v[194:197], v[4:7]
	v_mfma_f32_16x16x32_bf16 v[0:3], v[210:213], v[194:197], v[0:3]
	v_mfma_f32_16x16x32_bf16 v[52:55], v[206:209], v[172:175], v[52:55]
	v_mfma_f32_16x16x32_bf16 v[48:51], v[214:217], v[172:175], v[48:51]
	v_mfma_f32_16x16x32_bf16 v[36:39], v[206:209], v[180:183], v[36:39]
	v_mfma_f32_16x16x32_bf16 v[32:35], v[214:217], v[180:183], v[32:35]
	v_mfma_f32_16x16x32_bf16 v[20:23], v[206:209], v[188:191], v[20:23]
	v_mfma_f32_16x16x32_bf16 v[16:19], v[214:217], v[188:191], v[16:19]
	v_mfma_f32_16x16x32_bf16 v[4:7], v[206:209], v[198:201], v[4:7]
	v_mfma_f32_16x16x32_bf16 v[0:3], v[214:217], v[198:201], v[0:3]
	s_add_i32 s28, 0, 0x18000
	v_add_u32_e32 v156, s28, v165
	s_barrier
	ds_read_b128 v[128:131], v156
	ds_read_b128 v[132:135], v156 offset:1024
	ds_read_b128 v[136:139], v156 offset:2048
	ds_read_b128 v[156:159], v156 offset:3072
	s_add_u32 s40, s44, 0xb0000
	s_addc_u32 s41, s45, 0
	s_mov_b32 m0, s49
	v_lshl_add_u64 v[202:203], s[40:41], 0, v[140:141]
	ds_read_b128 v[160:163], v168 offset:32768
	ds_read_b128 v[172:175], v168 offset:33792
	ds_read_b128 v[176:179], v168 offset:34816
	ds_read_b128 v[180:183], v168 offset:35840
	ds_read_b128 v[184:187], v168 offset:36864
	ds_read_b128 v[188:191], v168 offset:37888
	ds_read_b128 v[194:197], v168 offset:38912
	ds_read_b128 v[198:201], v168 offset:39936
	global_load_lds_dwordx4 v[202:203], off
	v_lshl_add_u64 v[202:203], s[40:41], 0, v[144:145]
	s_mov_b32 m0, s50
	s_nop 0
	global_load_lds_dwordx4 v[202:203], off
	s_waitcnt lgkmcnt(8)
	s_barrier
	s_waitcnt lgkmcnt(0)
	s_waitcnt lgkmcnt(0)
	v_mfma_f32_16x16x32_bf16 v[124:127], v[128:131], v[160:163], v[124:127]
	v_mfma_f32_16x16x32_bf16 v[120:123], v[136:139], v[160:163], v[120:123]
	v_mfma_f32_16x16x32_bf16 v[108:111], v[128:131], v[176:179], v[108:111]
	v_mfma_f32_16x16x32_bf16 v[104:107], v[136:139], v[176:179], v[104:107]
	v_mfma_f32_16x16x32_bf16 v[92:95], v[128:131], v[184:187], v[92:95]
	v_mfma_f32_16x16x32_bf16 v[88:91], v[136:139], v[184:187], v[88:91]
	v_mfma_f32_16x16x32_bf16 v[76:79], v[128:131], v[194:197], v[76:79]
	v_mfma_f32_16x16x32_bf16 v[72:75], v[136:139], v[194:197], v[72:75]
	v_mfma_f32_16x16x32_bf16 v[124:127], v[132:135], v[172:175], v[124:127]
	v_mfma_f32_16x16x32_bf16 v[120:123], v[156:159], v[172:175], v[120:123]
	v_mfma_f32_16x16x32_bf16 v[108:111], v[132:135], v[180:183], v[108:111]
	v_mfma_f32_16x16x32_bf16 v[104:107], v[156:159], v[180:183], v[104:107]
	v_mfma_f32_16x16x32_bf16 v[92:95], v[132:135], v[188:191], v[92:95]
	v_mfma_f32_16x16x32_bf16 v[88:91], v[156:159], v[188:191], v[88:91]
	v_mfma_f32_16x16x32_bf16 v[76:79], v[132:135], v[198:201], v[76:79]
	v_mfma_f32_16x16x32_bf16 v[72:75], v[156:159], v[198:201], v[72:75]
	s_barrier
	s_add_i32 s29, 0, 0x1c000
	s_add_i32 s28, s28, s46
	v_add_u32_e32 v171, s29, v165
	v_lshl_add_u64 v[218:219], v[218:219], 0, s[36:37]
	s_mov_b32 m0, s28
	ds_read_b128 v[202:205], v171
	ds_read_b128 v[206:209], v171 offset:1024
	ds_read_b128 v[210:213], v171 offset:2048
	ds_read_b128 v[214:217], v171 offset:3072
	global_load_lds_dwordx4 v[218:219], off
	v_lshl_add_u64 v[218:219], v[220:221], 0, s[36:37]
	s_add_i32 m0, s28, 0x2000
	s_nop 0
	global_load_lds_dwordx4 v[218:219], off
	s_barrier
	s_waitcnt lgkmcnt(0)
	s_waitcnt lgkmcnt(0)
	v_mfma_f32_16x16x32_bf16 v[116:119], v[202:205], v[160:163], v[116:119]
	v_mfma_f32_16x16x32_bf16 v[112:115], v[210:213], v[160:163], v[112:115]
	v_mfma_f32_16x16x32_bf16 v[100:103], v[202:205], v[176:179], v[100:103]
	v_mfma_f32_16x16x32_bf16 v[96:99], v[210:213], v[176:179], v[96:99]
	v_mfma_f32_16x16x32_bf16 v[84:87], v[202:205], v[184:187], v[84:87]
	v_mfma_f32_16x16x32_bf16 v[80:83], v[210:213], v[184:187], v[80:83]
	v_mfma_f32_16x16x32_bf16 v[68:71], v[202:205], v[194:197], v[68:71]
	v_mfma_f32_16x16x32_bf16 v[64:67], v[210:213], v[194:197], v[64:67]
	v_mfma_f32_16x16x32_bf16 v[116:119], v[206:209], v[172:175], v[116:119]
	v_mfma_f32_16x16x32_bf16 v[112:115], v[214:217], v[172:175], v[112:115]
	v_mfma_f32_16x16x32_bf16 v[100:103], v[206:209], v[180:183], v[100:103]
	v_mfma_f32_16x16x32_bf16 v[96:99], v[214:217], v[180:183], v[96:99]
	v_mfma_f32_16x16x32_bf16 v[84:87], v[206:209], v[188:191], v[84:87]
	v_mfma_f32_16x16x32_bf16 v[80:83], v[214:217], v[188:191], v[80:83]
	v_mfma_f32_16x16x32_bf16 v[68:71], v[206:209], v[198:201], v[68:71]
	v_mfma_f32_16x16x32_bf16 v[64:67], v[214:217], v[198:201], v[64:67]
	s_mov_b32 m0, s54
	v_lshl_add_u64 v[218:219], v[222:223], 0, s[36:37]
	s_barrier
	ds_read_b128 v[160:163], v168 offset:49152
	ds_read_b128 v[172:175], v168 offset:50176
	ds_read_b128 v[176:179], v168 offset:51200
	ds_read_b128 v[180:183], v168 offset:52224
	ds_read_b128 v[184:187], v168 offset:53248
	ds_read_b128 v[188:191], v168 offset:54272
	ds_read_b128 v[194:197], v168 offset:55296
	ds_read_b128 v[198:201], v168 offset:56320
	global_load_lds_dwordx4 v[218:219], off
	v_lshl_add_u64 v[218:219], v[224:225], 0, s[36:37]
	s_mov_b32 m0, s55
	s_nop 0
	global_load_lds_dwordx4 v[218:219], off
	s_barrier
	s_waitcnt lgkmcnt(0)
	s_waitcnt lgkmcnt(0)
	v_mfma_f32_16x16x32_bf16 v[60:63], v[128:131], v[160:163], v[60:63]
	v_mfma_f32_16x16x32_bf16 v[56:59], v[136:139], v[160:163], v[56:59]
	v_mfma_f32_16x16x32_bf16 v[44:47], v[128:131], v[176:179], v[44:47]
	v_mfma_f32_16x16x32_bf16 v[40:43], v[136:139], v[176:179], v[40:43]
	v_mfma_f32_16x16x32_bf16 v[28:31], v[128:131], v[184:187], v[28:31]
	v_mfma_f32_16x16x32_bf16 v[24:27], v[136:139], v[184:187], v[24:27]
	v_mfma_f32_16x16x32_bf16 v[12:15], v[128:131], v[194:197], v[12:15]
	v_mfma_f32_16x16x32_bf16 v[8:11], v[136:139], v[194:197], v[8:11]
	v_mfma_f32_16x16x32_bf16 v[60:63], v[132:135], v[172:175], v[60:63]
	v_mfma_f32_16x16x32_bf16 v[56:59], v[156:159], v[172:175], v[56:59]
	v_mfma_f32_16x16x32_bf16 v[44:47], v[132:135], v[180:183], v[44:47]
	v_mfma_f32_16x16x32_bf16 v[40:43], v[156:159], v[180:183], v[40:43]
	v_mfma_f32_16x16x32_bf16 v[28:31], v[132:135], v[188:191], v[28:31]
	v_mfma_f32_16x16x32_bf16 v[24:27], v[156:159], v[188:191], v[24:27]
	v_mfma_f32_16x16x32_bf16 v[12:15], v[132:135], v[198:201], v[12:15]
	v_mfma_f32_16x16x32_bf16 v[8:11], v[156:159], v[198:201], v[8:11]
	s_barrier
	s_add_u32 s40, s42, 0x2c080
	s_addc_u32 s41, s43, 0
	s_add_i32 s28, s29, s46
	v_lshl_add_u64 v[128:129], s[40:41], 0, v[142:143]
	s_mov_b32 m0, s28
	s_nop 0
	global_load_lds_dwordx4 v[128:129], off
	v_lshl_add_u64 v[128:129], s[40:41], 0, v[146:147]
	s_add_i32 m0, s28, 0x2000
	s_nop 0
	global_load_lds_dwordx4 v[128:129], off
	s_waitcnt vmcnt(6)
	s_barrier
	v_mfma_f32_16x16x32_bf16 v[52:55], v[202:205], v[160:163], v[52:55]
	v_mfma_f32_16x16x32_bf16 v[48:51], v[210:213], v[160:163], v[48:51]
	v_mfma_f32_16x16x32_bf16 v[36:39], v[202:205], v[176:179], v[36:39]
	v_mfma_f32_16x16x32_bf16 v[32:35], v[210:213], v[176:179], v[32:35]
	v_mfma_f32_16x16x32_bf16 v[20:23], v[202:205], v[184:187], v[20:23]
	v_mfma_f32_16x16x32_bf16 v[16:19], v[210:213], v[184:187], v[16:19]
	v_mfma_f32_16x16x32_bf16 v[4:7], v[202:205], v[194:197], v[4:7]
	v_mfma_f32_16x16x32_bf16 v[0:3], v[210:213], v[194:197], v[0:3]
	v_mfma_f32_16x16x32_bf16 v[52:55], v[206:209], v[172:175], v[52:55]
	v_mfma_f32_16x16x32_bf16 v[48:51], v[214:217], v[172:175], v[48:51]
	v_mfma_f32_16x16x32_bf16 v[36:39], v[206:209], v[180:183], v[36:39]
	v_mfma_f32_16x16x32_bf16 v[32:35], v[214:217], v[180:183], v[32:35]
	v_mfma_f32_16x16x32_bf16 v[20:23], v[206:209], v[188:191], v[20:23]
	v_mfma_f32_16x16x32_bf16 v[16:19], v[214:217], v[188:191], v[16:19]
	v_mfma_f32_16x16x32_bf16 v[4:7], v[206:209], v[198:201], v[4:7]
	v_mfma_f32_16x16x32_bf16 v[0:3], v[214:217], v[198:201], v[0:3]
	s_add_i32 s65, s65, 2
	s_add_u32 s63, s63, 0x100
	s_addc_u32 s64, s64, 0
	s_cmp_gt_u32 s65, 41
	s_mov_b64 s[40:41], s[6:7]
	s_barrier
	s_cbranch_scc0 .LBB0_1169
	v_lshl_add_u32 v171, s62, 8, v164
	v_lshl_or_b32 v188, s10, 8, v166
	s_mov_b32 s63, 0xffff0000
	v_lshlrev_b32_e32 v128, 11, v171
	v_lshl_add_u32 v128, v188, 1, v128
	v_lshlrev_b32_e32 v129, 12, v171
	v_lshl_add_u32 v129, v188, 2, v129
	v_lshlrev_b32_e32 v132, 2, v188
	s_mov_b64 s[70:71], s[68:69]
	global_load_dwordx4 v[194:197], v128, s[70:71]
	global_load_dwordx4 v[198:201], v128, s[70:71] offset:64
	s_add_u32 s70, s70, 0x8000
	s_addc_u32 s71, s71, 0
	global_load_dwordx4 v[202:205], v128, s[70:71]
	global_load_dwordx4 v[206:209], v128, s[70:71] offset:64
	s_add_u32 s70, s70, 0x8000
	s_addc_u32 s71, s71, 0
	global_load_dwordx4 v[210:213], v128, s[70:71]
	global_load_dwordx4 v[214:217], v128, s[70:71] offset:64
	s_add_u32 s70, s70, 0x8000
	s_addc_u32 s71, s71, 0
	global_load_dwordx4 v[218:221], v128, s[70:71]
	global_load_dwordx4 v[222:225], v128, s[70:71] offset:64
	s_add_u32 s70, s70, 0x28000
	s_addc_u32 s71, s71, 0
	global_load_dwordx4 v[226:229], v128, s[70:71]
	global_load_dwordx4 v[230:233], v128, s[70:71] offset:64
	s_add_u32 s70, s70, 0x8000
	s_addc_u32 s71, s71, 0
	global_load_dwordx4 v[234:237], v128, s[70:71]
	global_load_dwordx4 v[238:241], v128, s[70:71] offset:64
	s_add_u32 s70, s70, 0x8000
	s_addc_u32 s71, s71, 0
	global_load_dwordx4 v[172:175], v128, s[70:71]
	global_load_dwordx4 v[176:179], v128, s[70:71] offset:64
	s_add_u32 s70, s70, 0x8000
	s_addc_u32 s71, s71, 0
	global_load_dwordx4 v[180:183], v128, s[70:71]
	global_load_dwordx4 v[184:187], v128, s[70:71] offset:64
	s_bfe_u32 s42, s17, 0x20006
	s_lshl_b32 s43, s10, 4
	s_lshl_b32 s42, s42, 2
	s_add_i32 s43, s43, s42
	v_lshl_add_u32 v130, v171, 6, s43
	v_and_b32_e32 v131, 48, v170
	v_lshl_add_u32 v131, v171, 6, v131
	v_xor_b32_e32 v134, 16, v170
	v_xor_b32_e32 v135, 32, v170
	v_lshlrev_b32_e32 v134, 2, v134
	v_lshlrev_b32_e32 v135, 2, v135
	v_cmp_gt_u32_e64 s[64:65], 16, v170
	s_add_u32 s74, s8, 0x2000
	s_addc_u32 s75, s9, 0
	s_lshl_b32 s42, s62, 7
	s_add_u32 s78, s26, 0x3c08000
	s_addc_u32 s79, s27, 0
	s_add_u32 s78, s78, s42
	s_addc_u32 s79, s79, 0
	s_waitcnt vmcnt(14)
	v_lshlrev_b32_e32 v136, 16, v194
	v_and_b32_e32 v137, s63, v194
	v_pk_add_f32 v[124:125], v[124:125], v[136:137]
	v_lshlrev_b32_e32 v138, 16, v195
	v_and_b32_e32 v139, s63, v195
	v_pk_add_f32 v[126:127], v[126:127], v[138:139]
	v_lshlrev_b32_e32 v190, 16, v196
	v_and_b32_e32 v191, s63, v196
	v_pk_add_f32 v[120:121], v[120:121], v[190:191]
	v_lshlrev_b32_e32 v136, 16, v197
	v_and_b32_e32 v137, s63, v197
	v_pk_add_f32 v[122:123], v[122:123], v[136:137]
	v_lshlrev_b32_e32 v138, 16, v198
	v_and_b32_e32 v139, s63, v198
	v_pk_add_f32 v[116:117], v[116:117], v[138:139]
	v_lshlrev_b32_e32 v190, 16, v199
	v_and_b32_e32 v191, s63, v199
	v_pk_add_f32 v[118:119], v[118:119], v[190:191]
	v_lshlrev_b32_e32 v136, 16, v200
	v_and_b32_e32 v137, s63, v200
	v_pk_add_f32 v[112:113], v[112:113], v[136:137]
	v_lshlrev_b32_e32 v138, 16, v201
	v_and_b32_e32 v139, s63, v201
	v_pk_add_f32 v[114:115], v[114:115], v[138:139]
	v_mul_f32_e32 v156, v120, v120
	v_mul_f32_e32 v189, v112, v112
	v_fmac_f32_e32 v156, v121, v121
	v_fmac_f32_e32 v189, v113, v113
	v_fmac_f32_e32 v156, v122, v122
	v_fmac_f32_e32 v189, v114, v114
	v_fmac_f32_e32 v156, v123, v123
	v_fmac_f32_e32 v189, v115, v115
	v_fmac_f32_e32 v156, v124, v124
	v_fmac_f32_e32 v189, v116, v116
	v_fmac_f32_e32 v156, v125, v125
	v_fmac_f32_e32 v189, v117, v117
	v_fmac_f32_e32 v156, v126, v126
	v_fmac_f32_e32 v189, v118, v118
	v_fmac_f32_e32 v156, v127, v127
	v_fmac_f32_e32 v189, v119, v119
	v_add_f32_e32 v156, v156, v189
	s_waitcnt vmcnt(12)
	v_lshlrev_b32_e32 v190, 16, v202
	v_and_b32_e32 v191, s63, v202
	v_pk_add_f32 v[108:109], v[108:109], v[190:191]
	v_lshlrev_b32_e32 v136, 16, v203
	v_and_b32_e32 v137, s63, v203
	v_pk_add_f32 v[110:111], v[110:111], v[136:137]
	v_lshlrev_b32_e32 v138, 16, v204
	v_and_b32_e32 v139, s63, v204
	v_pk_add_f32 v[104:105], v[104:105], v[138:139]
	v_lshlrev_b32_e32 v190, 16, v205
	v_and_b32_e32 v191, s63, v205
	v_pk_add_f32 v[106:107], v[106:107], v[190:191]
	v_lshlrev_b32_e32 v136, 16, v206
	v_and_b32_e32 v137, s63, v206
	v_pk_add_f32 v[100:101], v[100:101], v[136:137]
	v_lshlrev_b32_e32 v138, 16, v207
	v_and_b32_e32 v139, s63, v207
	v_pk_add_f32 v[102:103], v[102:103], v[138:139]
	v_lshlrev_b32_e32 v190, 16, v208
	v_and_b32_e32 v191, s63, v208
	v_pk_add_f32 v[96:97], v[96:97], v[190:191]
	v_lshlrev_b32_e32 v136, 16, v209
	v_and_b32_e32 v137, s63, v209
	v_pk_add_f32 v[98:99], v[98:99], v[136:137]
	v_mul_f32_e32 v157, v104, v104
	v_mul_f32_e32 v189, v96, v96
	v_fmac_f32_e32 v157, v105, v105
	v_fmac_f32_e32 v189, v97, v97
	v_fmac_f32_e32 v157, v106, v106
	v_fmac_f32_e32 v189, v98, v98
	v_fmac_f32_e32 v157, v107, v107
	v_fmac_f32_e32 v189, v99, v99
	v_fmac_f32_e32 v157, v108, v108
	v_fmac_f32_e32 v189, v100, v100
	v_fmac_f32_e32 v157, v109, v109
	v_fmac_f32_e32 v189, v101, v101
	v_fmac_f32_e32 v157, v110, v110
	v_fmac_f32_e32 v189, v102, v102
	v_fmac_f32_e32 v157, v111, v111
	v_fmac_f32_e32 v189, v103, v103
	v_add_f32_e32 v157, v157, v189
	s_waitcnt vmcnt(10)
	v_lshlrev_b32_e32 v138, 16, v210
	v_and_b32_e32 v139, s63, v210
	v_pk_add_f32 v[92:93], v[92:93], v[138:139]
	v_lshlrev_b32_e32 v190, 16, v211
	v_and_b32_e32 v191, s63, v211
	v_pk_add_f32 v[94:95], v[94:95], v[190:191]
	v_lshlrev_b32_e32 v136, 16, v212
	v_and_b32_e32 v137, s63, v212
	v_pk_add_f32 v[88:89], v[88:89], v[136:137]
	v_lshlrev_b32_e32 v138, 16, v213
	v_and_b32_e32 v139, s63, v213
	v_pk_add_f32 v[90:91], v[90:91], v[138:139]
	v_lshlrev_b32_e32 v190, 16, v214
	v_and_b32_e32 v191, s63, v214
	v_pk_add_f32 v[84:85], v[84:85], v[190:191]
	v_lshlrev_b32_e32 v136, 16, v215
	v_and_b32_e32 v137, s63, v215
	v_pk_add_f32 v[86:87], v[86:87], v[136:137]
	v_lshlrev_b32_e32 v138, 16, v216
	v_and_b32_e32 v139, s63, v216
	v_pk_add_f32 v[80:81], v[80:81], v[138:139]
	v_lshlrev_b32_e32 v190, 16, v217
	v_and_b32_e32 v191, s63, v217
	v_pk_add_f32 v[82:83], v[82:83], v[190:191]
	v_mul_f32_e32 v158, v88, v88
	v_mul_f32_e32 v189, v80, v80
	v_fmac_f32_e32 v158, v89, v89
	v_fmac_f32_e32 v189, v81, v81
	v_fmac_f32_e32 v158, v90, v90
	v_fmac_f32_e32 v189, v82, v82
	v_fmac_f32_e32 v158, v91, v91
	v_fmac_f32_e32 v189, v83, v83
	v_fmac_f32_e32 v158, v92, v92
	v_fmac_f32_e32 v189, v84, v84
	v_fmac_f32_e32 v158, v93, v93
	v_fmac_f32_e32 v189, v85, v85
	v_fmac_f32_e32 v158, v94, v94
	v_fmac_f32_e32 v189, v86, v86
	v_fmac_f32_e32 v158, v95, v95
	v_fmac_f32_e32 v189, v87, v87
	v_add_f32_e32 v158, v158, v189
	s_waitcnt vmcnt(8)
	v_lshlrev_b32_e32 v136, 16, v218
	v_and_b32_e32 v137, s63, v218
	v_pk_add_f32 v[76:77], v[76:77], v[136:137]
	v_lshlrev_b32_e32 v138, 16, v219
	v_and_b32_e32 v139, s63, v219
	v_pk_add_f32 v[78:79], v[78:79], v[138:139]
	v_lshlrev_b32_e32 v190, 16, v220
	v_and_b32_e32 v191, s63, v220
	v_pk_add_f32 v[72:73], v[72:73], v[190:191]
	v_lshlrev_b32_e32 v136, 16, v221
	v_and_b32_e32 v137, s63, v221
	v_pk_add_f32 v[74:75], v[74:75], v[136:137]
	v_lshlrev_b32_e32 v138, 16, v222
	v_and_b32_e32 v139, s63, v222
	v_pk_add_f32 v[68:69], v[68:69], v[138:139]
	v_lshlrev_b32_e32 v190, 16, v223
	v_and_b32_e32 v191, s63, v223
	v_pk_add_f32 v[70:71], v[70:71], v[190:191]
	v_lshlrev_b32_e32 v136, 16, v224
	v_and_b32_e32 v137, s63, v224
	v_pk_add_f32 v[64:65], v[64:65], v[136:137]
	v_lshlrev_b32_e32 v138, 16, v225
	v_and_b32_e32 v139, s63, v225
	v_pk_add_f32 v[66:67], v[66:67], v[138:139]
	v_mul_f32_e32 v159, v72, v72
	v_mul_f32_e32 v189, v64, v64
	v_fmac_f32_e32 v159, v73, v73
	v_fmac_f32_e32 v189, v65, v65
	v_fmac_f32_e32 v159, v74, v74
	v_fmac_f32_e32 v189, v66, v66
	v_fmac_f32_e32 v159, v75, v75
	v_fmac_f32_e32 v189, v67, v67
	v_fmac_f32_e32 v159, v76, v76
	v_fmac_f32_e32 v189, v68, v68
	v_fmac_f32_e32 v159, v77, v77
	v_fmac_f32_e32 v189, v69, v69
	v_fmac_f32_e32 v159, v78, v78
	v_fmac_f32_e32 v189, v70, v70
	v_fmac_f32_e32 v159, v79, v79
	v_fmac_f32_e32 v189, v71, v71
	v_add_f32_e32 v159, v159, v189
	s_waitcnt vmcnt(6)
	v_lshlrev_b32_e32 v190, 16, v226
	v_and_b32_e32 v191, s63, v226
	v_pk_add_f32 v[60:61], v[60:61], v[190:191]
	v_lshlrev_b32_e32 v136, 16, v227
	v_and_b32_e32 v137, s63, v227
	v_pk_add_f32 v[62:63], v[62:63], v[136:137]
	v_lshlrev_b32_e32 v138, 16, v228
	v_and_b32_e32 v139, s63, v228
	v_pk_add_f32 v[56:57], v[56:57], v[138:139]
	v_lshlrev_b32_e32 v190, 16, v229
	v_and_b32_e32 v191, s63, v229
	v_pk_add_f32 v[58:59], v[58:59], v[190:191]
	v_lshlrev_b32_e32 v136, 16, v230
	v_and_b32_e32 v137, s63, v230
	v_pk_add_f32 v[52:53], v[52:53], v[136:137]
	v_lshlrev_b32_e32 v138, 16, v231
	v_and_b32_e32 v139, s63, v231
	v_pk_add_f32 v[54:55], v[54:55], v[138:139]
	v_lshlrev_b32_e32 v190, 16, v232
	v_and_b32_e32 v191, s63, v232
	v_pk_add_f32 v[48:49], v[48:49], v[190:191]
	v_lshlrev_b32_e32 v136, 16, v233
	v_and_b32_e32 v137, s63, v233
	v_pk_add_f32 v[50:51], v[50:51], v[136:137]
	v_mul_f32_e32 v160, v56, v56
	v_mul_f32_e32 v189, v48, v48
	v_fmac_f32_e32 v160, v57, v57
	v_fmac_f32_e32 v189, v49, v49
	v_fmac_f32_e32 v160, v58, v58
	v_fmac_f32_e32 v189, v50, v50
	v_fmac_f32_e32 v160, v59, v59
	v_fmac_f32_e32 v189, v51, v51
	v_fmac_f32_e32 v160, v60, v60
	v_fmac_f32_e32 v189, v52, v52
	v_fmac_f32_e32 v160, v61, v61
	v_fmac_f32_e32 v189, v53, v53
	v_fmac_f32_e32 v160, v62, v62
	v_fmac_f32_e32 v189, v54, v54
	v_fmac_f32_e32 v160, v63, v63
	v_fmac_f32_e32 v189, v55, v55
	v_add_f32_e32 v160, v160, v189
	s_waitcnt vmcnt(4)
	v_lshlrev_b32_e32 v138, 16, v234
	v_and_b32_e32 v139, s63, v234
	v_pk_add_f32 v[44:45], v[44:45], v[138:139]
	v_lshlrev_b32_e32 v190, 16, v235
	v_and_b32_e32 v191, s63, v235
	v_pk_add_f32 v[46:47], v[46:47], v[190:191]
	v_lshlrev_b32_e32 v136, 16, v236
	v_and_b32_e32 v137, s63, v236
	v_pk_add_f32 v[40:41], v[40:41], v[136:137]
	v_lshlrev_b32_e32 v138, 16, v237
	v_and_b32_e32 v139, s63, v237
	v_pk_add_f32 v[42:43], v[42:43], v[138:139]
	v_lshlrev_b32_e32 v190, 16, v238
	v_and_b32_e32 v191, s63, v238
	v_pk_add_f32 v[36:37], v[36:37], v[190:191]
	v_lshlrev_b32_e32 v136, 16, v239
	v_and_b32_e32 v137, s63, v239
	v_pk_add_f32 v[38:39], v[38:39], v[136:137]
	v_lshlrev_b32_e32 v138, 16, v240
	v_and_b32_e32 v139, s63, v240
	v_pk_add_f32 v[32:33], v[32:33], v[138:139]
	v_lshlrev_b32_e32 v190, 16, v241
	v_and_b32_e32 v191, s63, v241
	v_pk_add_f32 v[34:35], v[34:35], v[190:191]
	v_mul_f32_e32 v161, v40, v40
	v_mul_f32_e32 v189, v32, v32
	v_fmac_f32_e32 v161, v41, v41
	v_fmac_f32_e32 v189, v33, v33
	v_fmac_f32_e32 v161, v42, v42
	v_fmac_f32_e32 v189, v34, v34
	v_fmac_f32_e32 v161, v43, v43
	v_fmac_f32_e32 v189, v35, v35
	v_fmac_f32_e32 v161, v44, v44
	v_fmac_f32_e32 v189, v36, v36
	v_fmac_f32_e32 v161, v45, v45
	v_fmac_f32_e32 v189, v37, v37
	v_fmac_f32_e32 v161, v46, v46
	v_fmac_f32_e32 v189, v38, v38
	v_fmac_f32_e32 v161, v47, v47
	v_fmac_f32_e32 v189, v39, v39
	v_add_f32_e32 v161, v161, v189
	s_waitcnt vmcnt(2)
	v_lshlrev_b32_e32 v136, 16, v172
	v_and_b32_e32 v137, s63, v172
	v_pk_add_f32 v[28:29], v[28:29], v[136:137]
	v_lshlrev_b32_e32 v138, 16, v173
	v_and_b32_e32 v139, s63, v173
	v_pk_add_f32 v[30:31], v[30:31], v[138:139]
	v_lshlrev_b32_e32 v190, 16, v174
	v_and_b32_e32 v191, s63, v174
	v_pk_add_f32 v[24:25], v[24:25], v[190:191]
	v_lshlrev_b32_e32 v136, 16, v175
	v_and_b32_e32 v137, s63, v175
	v_pk_add_f32 v[26:27], v[26:27], v[136:137]
	v_lshlrev_b32_e32 v138, 16, v176
	v_and_b32_e32 v139, s63, v176
	v_pk_add_f32 v[20:21], v[20:21], v[138:139]
	v_lshlrev_b32_e32 v190, 16, v177
	v_and_b32_e32 v191, s63, v177
	v_pk_add_f32 v[22:23], v[22:23], v[190:191]
	v_lshlrev_b32_e32 v136, 16, v178
	v_and_b32_e32 v137, s63, v178
	v_pk_add_f32 v[16:17], v[16:17], v[136:137]
	v_lshlrev_b32_e32 v138, 16, v179
	v_and_b32_e32 v139, s63, v179
	v_pk_add_f32 v[18:19], v[18:19], v[138:139]
	v_mul_f32_e32 v162, v24, v24
	v_mul_f32_e32 v189, v16, v16
	v_fmac_f32_e32 v162, v25, v25
	v_fmac_f32_e32 v189, v17, v17
	v_fmac_f32_e32 v162, v26, v26
	v_fmac_f32_e32 v189, v18, v18
	v_fmac_f32_e32 v162, v27, v27
	v_fmac_f32_e32 v189, v19, v19
	v_fmac_f32_e32 v162, v28, v28
	v_fmac_f32_e32 v189, v20, v20
	v_fmac_f32_e32 v162, v29, v29
	v_fmac_f32_e32 v189, v21, v21
	v_fmac_f32_e32 v162, v30, v30
	v_fmac_f32_e32 v189, v22, v22
	v_fmac_f32_e32 v162, v31, v31
	v_fmac_f32_e32 v189, v23, v23
	v_add_f32_e32 v162, v162, v189
	s_waitcnt vmcnt(0)
	v_lshlrev_b32_e32 v190, 16, v180
	v_and_b32_e32 v191, s63, v180
	v_pk_add_f32 v[12:13], v[12:13], v[190:191]
	v_lshlrev_b32_e32 v136, 16, v181
	v_and_b32_e32 v137, s63, v181
	v_pk_add_f32 v[14:15], v[14:15], v[136:137]
	v_lshlrev_b32_e32 v138, 16, v182
	v_and_b32_e32 v139, s63, v182
	v_pk_add_f32 v[8:9], v[8:9], v[138:139]
	v_lshlrev_b32_e32 v190, 16, v183
	v_and_b32_e32 v191, s63, v183
	v_pk_add_f32 v[10:11], v[10:11], v[190:191]
	v_lshlrev_b32_e32 v136, 16, v184
	v_and_b32_e32 v137, s63, v184
	v_pk_add_f32 v[4:5], v[4:5], v[136:137]
	v_lshlrev_b32_e32 v138, 16, v185
	v_and_b32_e32 v139, s63, v185
	v_pk_add_f32 v[6:7], v[6:7], v[138:139]
	v_lshlrev_b32_e32 v190, 16, v186
	v_and_b32_e32 v191, s63, v186
	v_pk_add_f32 v[0:1], v[0:1], v[190:191]
	v_lshlrev_b32_e32 v136, 16, v187
	v_and_b32_e32 v137, s63, v187
	v_pk_add_f32 v[2:3], v[2:3], v[136:137]
	v_mul_f32_e32 v163, v8, v8
	v_mul_f32_e32 v189, v0, v0
	v_fmac_f32_e32 v163, v9, v9
	v_fmac_f32_e32 v189, v1, v1
	v_fmac_f32_e32 v163, v10, v10
	v_fmac_f32_e32 v189, v2, v2
	v_fmac_f32_e32 v163, v11, v11
	v_fmac_f32_e32 v189, v3, v3
	v_fmac_f32_e32 v163, v12, v12
	v_fmac_f32_e32 v189, v4, v4
	v_fmac_f32_e32 v163, v13, v13
	v_fmac_f32_e32 v189, v5, v5
	v_fmac_f32_e32 v163, v14, v14
	v_fmac_f32_e32 v189, v6, v6
	v_fmac_f32_e32 v163, v15, v15
	v_fmac_f32_e32 v189, v7, v7
	v_add_f32_e32 v163, v163, v189
	ds_bpermute_b32 v136, v134, v156
	ds_bpermute_b32 v137, v134, v157
	ds_bpermute_b32 v138, v134, v158
	ds_bpermute_b32 v139, v134, v159
	ds_bpermute_b32 v188, v134, v160
	ds_bpermute_b32 v189, v134, v161
	ds_bpermute_b32 v190, v134, v162
	ds_bpermute_b32 v191, v134, v163
	s_waitcnt lgkmcnt(0)
	v_add_f32_e32 v156, v156, v136
	v_add_f32_e32 v157, v157, v137
	v_add_f32_e32 v158, v158, v138
	v_add_f32_e32 v159, v159, v139
	v_add_f32_e32 v160, v160, v188
	v_add_f32_e32 v161, v161, v189
	v_add_f32_e32 v162, v162, v190
	v_add_f32_e32 v163, v163, v191
	ds_bpermute_b32 v136, v135, v156
	ds_bpermute_b32 v137, v135, v157
	ds_bpermute_b32 v138, v135, v158
	ds_bpermute_b32 v139, v135, v159
	ds_bpermute_b32 v188, v135, v160
	ds_bpermute_b32 v189, v135, v161
	ds_bpermute_b32 v190, v135, v162
	ds_bpermute_b32 v191, v135, v163
	s_waitcnt lgkmcnt(0)
	v_add_f32_e32 v156, v156, v136
	v_add_f32_e32 v157, v157, v137
	v_add_f32_e32 v158, v158, v138
	v_add_f32_e32 v159, v159, v139
	v_add_f32_e32 v160, v160, v188
	v_add_f32_e32 v161, v161, v189
	v_add_f32_e32 v162, v162, v190
	v_add_f32_e32 v163, v163, v191
	s_and_saveexec_b64 s[66:67], s[64:65]
	global_store_dword v130, v156, s[8:9] sc1
	global_store_dword v130, v157, s[8:9] offset:1024 sc1
	global_store_dword v130, v158, s[8:9] offset:2048 sc1
	global_store_dword v130, v159, s[8:9] offset:3072 sc1
	global_store_dword v130, v160, s[74:75] sc1
	global_store_dword v130, v161, s[74:75] offset:1024 sc1
	global_store_dword v130, v162, s[74:75] offset:2048 sc1
	global_store_dword v130, v163, s[74:75] offset:3072 sc1
	s_or_b64 exec, exec, s[66:67]
	global_load_dwordx4 v[210:213], v132, s[22:23]
	global_load_dwordx4 v[214:217], v132, s[22:23] offset:16
	global_load_dwordx4 v[218:221], v132, s[22:23] offset:128
	global_load_dwordx4 v[222:225], v132, s[22:23] offset:144
	s_waitcnt vmcnt(0)
	s_barrier
	s_barrier
	s_cmpk_gt_u32 s17, 0xff
	s_cbranch_scc1 .Lf11_w1_a
	s_and_saveexec_b64 s[40:41], s[14:15]
	s_cbranch_execz .Lf11_t0_done
	v_mov_b32_e32 v133, 0
	v_mov_b32_e32 v189, 1
	global_atomic_add v133, v189, s[78:79]
	s_mov_b32 s80, 0
